# per-segment s_setprio flips removed from all six GEMM K-loops
# speedup vs baseline: 1.0092x; 1.0092x over previous
; #define PG8_STAGE(bufoff, gbase, voff) do { _Pragma("unroll") for (int _i = 0; _i < 2; ++_i) \
;         __builtin_amdgcn_global_load_lds((const unsigned*)((const char*)(gbase) + (voff)[_i]), (PG8_LAS unsigned*)(lds + (bufoff) + ldsw + _i * 8192), 16, 0, 0); } while (0)
; #define PG8_LDA(dst, b, h) do { _Pragma("unroll") for (int m = 0; m < 4; ++m) _Pragma("unroll") for (int k = 0; k < 2; ++k) dst[m][k] = *(const PG8_LAS bf16x8*)(lds + PG8_SA(b, h) + aoff + m * 2048 + k * 1024); } while (0)
; #define PG8_LDB(dst, b, h) do { _Pragma("unroll") for (int n = 0; n < 2; ++n) _Pragma("unroll") for (int k = 0; k < 2; ++k) dst[n][k] = *(const PG8_LAS bf16x8*)(lds + PG8_SB(b, h) + boff + n * 2048 + k * 1024); } while (0)
; #define PG8_MMA(ai, bj, At, Bt) do { __builtin_amdgcn_s_setprio(1); _Pragma("unroll") for (int m = 0; m < 4; ++m) _Pragma("unroll") for (int n = 0; n < 2; ++n) _Pragma("unroll") for (int k = 0; k < 2; ++k) \
;         acc[ai][bj][m][n] = __builtin_amdgcn_mfma_f32_16x16x32_bf16(Bt[n][k], At[m][k], acc[ai][bj][m][n], 0, 0, 0); __builtin_amdgcn_s_setprio(0); } while (0)
; #define PG8_WAIT_V(n) asm volatile("s_waitcnt vmcnt(" #n ")" ::: "memory")
; #define PG8_WAIT_L(n) asm volatile("s_waitcnt lgkmcnt(" #n ")" ::: "memory")
; #define PG8_BAR __builtin_amdgcn_s_barrier()
; #define PG8_SCHED __builtin_amdgcn_sched_barrier(0)
; template <class Epi, class Sched, bool ALIGN_EPI = false, bool SP2 = false, bool ATILED = false>
; __device__ __forceinline__ void gemm_phase(PG8_LAS unsigned char* lds, const Gemm g, const Sched& S, const Epi& E) {
;     ...
;             PG8_LDB(B0, 0, 0); PG8_LDB(B1, 0, 1); PG8_SCHED; PG8_LDA(At, 0, 0); PG8_STAGE(PG8_SA(1, 1), a1 + hstepA, voffA);
;             PG8_WAIT_V(8); PG8_WAIT_L(0); PG8_BAR; PG8_MMA(0, 0, At, B0); PG8_MMA(0, 1, At, B1); PG8_BAR; PG8_SCHED;
;             PG8_LDA(At, 0, 1); PG8_STAGE(PG8_SB(0, 0), b2, voffB); PG8_STAGE(PG8_SB(0, 1), b2 + hstep, voffB); PG8_STAGE(PG8_SA(0, 0), a2, voffA);
.LBB0_133:
	ds_read_b128 v[150:153], v156
	ds_read_b128 v[162:165], v156 offset:1024
	ds_read_b128 v[166:169], v156 offset:2048
	ds_read_b128 v[170:173], v156 offset:3072
	ds_read_b128 v[174:177], v157
	ds_read_b128 v[178:181], v157 offset:1024
	ds_read_b128 v[182:185], v157 offset:2048
	ds_read_b128 v[186:189], v157 offset:3072
	s_add_u32 s62, s60, 0xfffc0080
	s_addc_u32 s63, s61, -1
	s_cmp_eq_u32 s87, 12
	s_cselect_b32 s65, s43, s63
	s_cselect_b32 s64, s83, s62
	s_cselect_b32 s63, s41, s86
	s_cselect_b32 s62, s84, s85
	v_lshl_add_u64 v[224:225], s[60:61], 0, v[140:141]
	s_add_i32 m0, s49, 0xc000
	ds_read_b128 v[190:193], v158
	ds_read_b128 v[194:197], v158 offset:1024
	ds_read_b128 v[200:203], v158 offset:2048
	ds_read_b128 v[204:207], v158 offset:3072
	ds_read_b128 v[208:211], v158 offset:4096
	ds_read_b128 v[212:215], v158 offset:5120
	ds_read_b128 v[216:219], v158 offset:6144
	ds_read_b128 v[220:223], v158 offset:7168
	global_load_lds_dwordx4 v[224:225], off
	v_lshl_add_u64 v[224:225], s[60:61], 0, v[142:143]
	s_add_i32 m0, s49, 0xe000
	s_nop 0
	global_load_lds_dwordx4 v[224:225], off
	s_waitcnt vmcnt(8)
	s_waitcnt lgkmcnt(0)
	s_barrier
	s_waitcnt lgkmcnt(0)
	v_mfma_f32_16x16x32_bf16 v[124:127], v[150:153], v[190:193], v[124:127]
	v_mfma_f32_16x16x32_bf16 v[120:123], v[166:169], v[190:193], v[120:123]
	v_mfma_f32_16x16x32_bf16 v[108:111], v[150:153], v[200:203], v[108:111]
	v_mfma_f32_16x16x32_bf16 v[104:107], v[166:169], v[200:203], v[104:107]
	v_mfma_f32_16x16x32_bf16 v[92:95], v[150:153], v[208:211], v[92:95]
	v_mfma_f32_16x16x32_bf16 v[88:91], v[166:169], v[208:211], v[88:91]
	v_mfma_f32_16x16x32_bf16 v[76:79], v[150:153], v[216:219], v[76:79]
	v_mfma_f32_16x16x32_bf16 v[72:75], v[166:169], v[216:219], v[72:75]
	v_mfma_f32_16x16x32_bf16 v[124:127], v[162:165], v[194:197], v[124:127]
	v_mfma_f32_16x16x32_bf16 v[120:123], v[170:173], v[194:197], v[120:123]
	v_mfma_f32_16x16x32_bf16 v[108:111], v[162:165], v[204:207], v[108:111]
	v_mfma_f32_16x16x32_bf16 v[104:107], v[170:173], v[204:207], v[104:107]
	v_mfma_f32_16x16x32_bf16 v[92:95], v[162:165], v[212:215], v[92:95]
	v_mfma_f32_16x16x32_bf16 v[88:91], v[170:173], v[212:215], v[88:91]
	v_mfma_f32_16x16x32_bf16 v[76:79], v[162:165], v[220:223], v[76:79]
	v_mfma_f32_16x16x32_bf16 v[72:75], v[170:173], v[220:223], v[72:75]
	v_mfma_f32_16x16x32_bf16 v[116:119], v[174:177], v[190:193], v[116:119]
	v_mfma_f32_16x16x32_bf16 v[112:115], v[182:185], v[190:193], v[112:115]
	v_mfma_f32_16x16x32_bf16 v[100:103], v[174:177], v[200:203], v[100:103]
	v_mfma_f32_16x16x32_bf16 v[96:99], v[182:185], v[200:203], v[96:99]
	v_mfma_f32_16x16x32_bf16 v[84:87], v[174:177], v[208:211], v[84:87]
	v_mfma_f32_16x16x32_bf16 v[80:83], v[182:185], v[208:211], v[80:83]
	v_mfma_f32_16x16x32_bf16 v[68:71], v[174:177], v[216:219], v[68:71]
	v_mfma_f32_16x16x32_bf16 v[64:67], v[182:185], v[216:219], v[64:67]
	v_mfma_f32_16x16x32_bf16 v[116:119], v[178:181], v[194:197], v[116:119]
	v_mfma_f32_16x16x32_bf16 v[112:115], v[186:189], v[194:197], v[112:115]
	v_mfma_f32_16x16x32_bf16 v[100:103], v[178:181], v[204:207], v[100:103]
	v_mfma_f32_16x16x32_bf16 v[96:99], v[186:189], v[204:207], v[96:99]
	v_mfma_f32_16x16x32_bf16 v[84:87], v[178:181], v[212:215], v[84:87]
	v_mfma_f32_16x16x32_bf16 v[80:83], v[186:189], v[212:215], v[80:83]
	v_mfma_f32_16x16x32_bf16 v[68:71], v[178:181], v[220:223], v[68:71]
	v_mfma_f32_16x16x32_bf16 v[64:67], v[186:189], v[220:223], v[64:67]
	s_barrier
	s_add_i32 s88, s78, s66
	v_lshl_add_u64 v[224:225], s[62:63], 0, v[130:131]
	s_mov_b32 m0, s88
	ds_read_b128 v[190:193], v158 offset:16384
	ds_read_b128 v[194:197], v158 offset:17408
	ds_read_b128 v[200:203], v158 offset:18432
	ds_read_b128 v[204:207], v158 offset:19456
	ds_read_b128 v[208:211], v158 offset:20480
	ds_read_b128 v[212:215], v158 offset:21504
	ds_read_b128 v[216:219], v158 offset:22528
	ds_read_b128 v[220:223], v158 offset:23552
	global_load_lds_dwordx4 v[224:225], off
	s_add_i32 m0, s88, 0x2000
	s_add_u32 s88, s62, 0x40000
	v_lshl_add_u64 v[226:227], s[62:63], 0, v[134:135]
	s_addc_u32 s89, s63, 0
	s_add_i32 s90, s79, s66
	global_load_lds_dwordx4 v[226:227], off
	v_lshl_add_u64 v[228:229], s[88:89], 0, v[130:131]
	s_mov_b32 m0, s90
	v_lshl_add_u64 v[230:231], s[64:65], 0, v[132:133]
	global_load_lds_dwordx4 v[228:229], off
	v_lshl_add_u64 v[228:229], s[88:89], 0, v[134:135]
	s_add_i32 m0, s90, 0x2000
	s_nop 0
	global_load_lds_dwordx4 v[228:229], off
	v_lshl_add_u64 v[228:229], s[64:65], 0, v[128:129]
	s_mov_b32 m0, s49
	s_nop 0
	global_load_lds_dwordx4 v[228:229], off
	s_mov_b32 m0, s68
	s_nop 0
	global_load_lds_dwordx4 v[230:231], off
	s_waitcnt vmcnt(8)
	s_waitcnt lgkmcnt(0)
	s_barrier
; #define PG8_STAGE(bufoff, gbase, voff) do { _Pragma("unroll") for (int _i = 0; _i < 2; ++_i) \
;         __builtin_amdgcn_global_load_lds((const unsigned*)((const char*)(gbase) + (voff)[_i]), (PG8_LAS unsigned*)(lds + (bufoff) + ldsw + _i * 8192), 16, 0, 0); } while (0)
; #define PG8_LDA(dst, b, h) do { _Pragma("unroll") for (int m = 0; m < 4; ++m) _Pragma("unroll") for (int k = 0; k < 2; ++k) dst[m][k] = *(const PG8_LAS bf16x8*)(lds + PG8_SA(b, h) + aoff + m * 2048 + k * 1024); } while (0)
; #define PG8_LDB(dst, b, h) do { _Pragma("unroll") for (int n = 0; n < 2; ++n) _Pragma("unroll") for (int k = 0; k < 2; ++k) dst[n][k] = *(const PG8_LAS bf16x8*)(lds + PG8_SB(b, h) + boff + n * 2048 + k * 1024); } while (0)
; #define PG8_MMA(ai, bj, At, Bt) do { __builtin_amdgcn_s_setprio(1); _Pragma("unroll") for (int m = 0; m < 4; ++m) _Pragma("unroll") for (int n = 0; n < 2; ++n) _Pragma("unroll") for (int k = 0; k < 2; ++k) \
;         acc[ai][bj][m][n] = __builtin_amdgcn_mfma_f32_16x16x32_bf16(Bt[n][k], At[m][k], acc[ai][bj][m][n], 0, 0, 0); __builtin_amdgcn_s_setprio(0); } while (0)
; #define PG8_WAIT_V(n) asm volatile("s_waitcnt vmcnt(" #n ")" ::: "memory")
; #define PG8_WAIT_L(n) asm volatile("s_waitcnt lgkmcnt(" #n ")" ::: "memory")
; #define PG8_BAR __builtin_amdgcn_s_barrier()
; #define PG8_SCHED __builtin_amdgcn_sched_barrier(0)
; template <class Epi, class Sched, bool ALIGN_EPI = false, bool SP2 = false, bool ATILED = false>
; __device__ __forceinline__ void gemm_phase(PG8_LAS unsigned char* lds, const Gemm g, const Sched& S, const Epi& E) {
;     ...
;             PG8_WAIT_V(8); PG8_WAIT_L(0); PG8_BAR; PG8_MMA(1, 0, At, B0); PG8_MMA(1, 1, At, B1); PG8_BAR; PG8_SCHED;
;             PG8_LDB(B0, 1, 0); PG8_LDB(B1, 1, 1); PG8_SCHED; PG8_LDA(At, 1, 0); PG8_STAGE(PG8_SA(0, 1), a2 + hstepA, voffA);
;             PG8_WAIT_V(8); PG8_WAIT_L(0); PG8_BAR; PG8_MMA(0, 0, At, B0); PG8_MMA(0, 1, At, B1); PG8_BAR; PG8_SCHED;
	s_waitcnt lgkmcnt(0)
	v_mfma_f32_16x16x32_bf16 v[60:63], v[150:153], v[190:193], v[60:63]
	v_mfma_f32_16x16x32_bf16 v[56:59], v[166:169], v[190:193], v[56:59]
	v_mfma_f32_16x16x32_bf16 v[44:47], v[150:153], v[200:203], v[44:47]
	v_mfma_f32_16x16x32_bf16 v[40:43], v[166:169], v[200:203], v[40:43]
	v_mfma_f32_16x16x32_bf16 v[28:31], v[150:153], v[208:211], v[28:31]
	v_mfma_f32_16x16x32_bf16 v[24:27], v[166:169], v[208:211], v[24:27]
	v_mfma_f32_16x16x32_bf16 v[12:15], v[150:153], v[216:219], v[12:15]
	v_mfma_f32_16x16x32_bf16 v[8:11], v[166:169], v[216:219], v[8:11]
	v_mfma_f32_16x16x32_bf16 v[60:63], v[162:165], v[194:197], v[60:63]
	v_mfma_f32_16x16x32_bf16 v[56:59], v[170:173], v[194:197], v[56:59]
	v_mfma_f32_16x16x32_bf16 v[44:47], v[162:165], v[204:207], v[44:47]
	v_mfma_f32_16x16x32_bf16 v[40:43], v[170:173], v[204:207], v[40:43]
	v_mfma_f32_16x16x32_bf16 v[28:31], v[162:165], v[212:215], v[28:31]
	v_mfma_f32_16x16x32_bf16 v[24:27], v[170:173], v[212:215], v[24:27]
	v_mfma_f32_16x16x32_bf16 v[12:15], v[162:165], v[220:223], v[12:15]
	v_mfma_f32_16x16x32_bf16 v[8:11], v[170:173], v[220:223], v[8:11]
	v_mfma_f32_16x16x32_bf16 v[52:55], v[174:177], v[190:193], v[52:55]
	v_mfma_f32_16x16x32_bf16 v[48:51], v[182:185], v[190:193], v[48:51]
	v_mfma_f32_16x16x32_bf16 v[36:39], v[174:177], v[200:203], v[36:39]
	v_mfma_f32_16x16x32_bf16 v[32:35], v[182:185], v[200:203], v[32:35]
	v_mfma_f32_16x16x32_bf16 v[20:23], v[174:177], v[208:211], v[20:23]
	v_mfma_f32_16x16x32_bf16 v[16:19], v[182:185], v[208:211], v[16:19]
	v_mfma_f32_16x16x32_bf16 v[4:7], v[174:177], v[216:219], v[4:7]
	v_mfma_f32_16x16x32_bf16 v[0:3], v[182:185], v[216:219], v[0:3]
	v_mfma_f32_16x16x32_bf16 v[52:55], v[178:181], v[194:197], v[52:55]
	v_mfma_f32_16x16x32_bf16 v[48:51], v[186:189], v[194:197], v[48:51]
	v_mfma_f32_16x16x32_bf16 v[36:39], v[178:181], v[204:207], v[36:39]
	v_mfma_f32_16x16x32_bf16 v[32:35], v[186:189], v[204:207], v[32:35]
	v_mfma_f32_16x16x32_bf16 v[20:23], v[178:181], v[212:215], v[20:23]
	v_mfma_f32_16x16x32_bf16 v[16:19], v[186:189], v[212:215], v[16:19]
	v_mfma_f32_16x16x32_bf16 v[4:7], v[178:181], v[220:223], v[4:7]
	v_mfma_f32_16x16x32_bf16 v[0:3], v[186:189], v[220:223], v[0:3]
	s_barrier
	s_add_i32 s88, 0, 0x18000
	v_add_u32_e32 v136, s88, v155
	s_add_i32 s89, 0, 0x1c000
	ds_read_b128 v[150:153], v136
	ds_read_b128 v[162:165], v136 offset:1024
	ds_read_b128 v[166:169], v136 offset:2048
	ds_read_b128 v[170:173], v136 offset:3072
	v_add_u32_e32 v136, s89, v155
	ds_read_b128 v[174:177], v136
	ds_read_b128 v[178:181], v136 offset:1024
	ds_read_b128 v[182:185], v136 offset:2048
	ds_read_b128 v[186:189], v136 offset:3072
	s_add_u32 s64, s64, 0x40000
	s_addc_u32 s65, s65, 0
	s_mov_b32 m0, s69
	v_lshl_add_u64 v[232:233], s[64:65], 0, v[128:129]
	ds_read_b128 v[190:193], v158 offset:32768
	ds_read_b128 v[194:197], v158 offset:33792
	ds_read_b128 v[200:203], v158 offset:34816
	ds_read_b128 v[204:207], v158 offset:35840
	ds_read_b128 v[208:211], v158 offset:36864
	ds_read_b128 v[212:215], v158 offset:37888
	ds_read_b128 v[216:219], v158 offset:38912
	ds_read_b128 v[220:223], v158 offset:39936
	global_load_lds_dwordx4 v[232:233], off
	v_lshl_add_u64 v[232:233], s[64:65], 0, v[132:133]
	s_mov_b32 m0, s70
	s_nop 0
	global_load_lds_dwordx4 v[232:233], off
	s_waitcnt vmcnt(8)
	s_waitcnt lgkmcnt(0)
	s_barrier
	s_waitcnt lgkmcnt(0)
	v_mfma_f32_16x16x32_bf16 v[124:127], v[150:153], v[190:193], v[124:127]
	v_mfma_f32_16x16x32_bf16 v[120:123], v[166:169], v[190:193], v[120:123]
	v_mfma_f32_16x16x32_bf16 v[108:111], v[150:153], v[200:203], v[108:111]
	v_mfma_f32_16x16x32_bf16 v[104:107], v[166:169], v[200:203], v[104:107]
	v_mfma_f32_16x16x32_bf16 v[92:95], v[150:153], v[208:211], v[92:95]
	v_mfma_f32_16x16x32_bf16 v[88:91], v[166:169], v[208:211], v[88:91]
	v_mfma_f32_16x16x32_bf16 v[76:79], v[150:153], v[216:219], v[76:79]
	v_mfma_f32_16x16x32_bf16 v[72:75], v[166:169], v[216:219], v[72:75]
	v_mfma_f32_16x16x32_bf16 v[124:127], v[162:165], v[194:197], v[124:127]
	v_mfma_f32_16x16x32_bf16 v[120:123], v[170:173], v[194:197], v[120:123]
	v_mfma_f32_16x16x32_bf16 v[108:111], v[162:165], v[204:207], v[108:111]
	v_mfma_f32_16x16x32_bf16 v[104:107], v[170:173], v[204:207], v[104:107]
	v_mfma_f32_16x16x32_bf16 v[92:95], v[162:165], v[212:215], v[92:95]
	v_mfma_f32_16x16x32_bf16 v[88:91], v[170:173], v[212:215], v[88:91]
	v_mfma_f32_16x16x32_bf16 v[76:79], v[162:165], v[220:223], v[76:79]
	v_mfma_f32_16x16x32_bf16 v[72:75], v[170:173], v[220:223], v[72:75]
	v_mfma_f32_16x16x32_bf16 v[116:119], v[174:177], v[190:193], v[116:119]
	v_mfma_f32_16x16x32_bf16 v[112:115], v[182:185], v[190:193], v[112:115]
	v_mfma_f32_16x16x32_bf16 v[100:103], v[174:177], v[200:203], v[100:103]
	v_mfma_f32_16x16x32_bf16 v[96:99], v[182:185], v[200:203], v[96:99]
	v_mfma_f32_16x16x32_bf16 v[84:87], v[174:177], v[208:211], v[84:87]
	v_mfma_f32_16x16x32_bf16 v[80:83], v[182:185], v[208:211], v[80:83]
	v_mfma_f32_16x16x32_bf16 v[68:71], v[174:177], v[216:219], v[68:71]
	v_mfma_f32_16x16x32_bf16 v[64:67], v[182:185], v[216:219], v[64:67]
	v_mfma_f32_16x16x32_bf16 v[116:119], v[178:181], v[194:197], v[116:119]
	v_mfma_f32_16x16x32_bf16 v[112:115], v[186:189], v[194:197], v[112:115]
	v_mfma_f32_16x16x32_bf16 v[100:103], v[178:181], v[204:207], v[100:103]
	v_mfma_f32_16x16x32_bf16 v[96:99], v[186:189], v[204:207], v[96:99]
	v_mfma_f32_16x16x32_bf16 v[84:87], v[178:181], v[212:215], v[84:87]
	v_mfma_f32_16x16x32_bf16 v[80:83], v[186:189], v[212:215], v[80:83]
	v_mfma_f32_16x16x32_bf16 v[68:71], v[178:181], v[220:223], v[68:71]
	v_mfma_f32_16x16x32_bf16 v[64:67], v[186:189], v[220:223], v[64:67]
	s_barrier
; #define PG8_STAGE(bufoff, gbase, voff) do { _Pragma("unroll") for (int _i = 0; _i < 2; ++_i) \
;         __builtin_amdgcn_global_load_lds((const unsigned*)((const char*)(gbase) + (voff)[_i]), (PG8_LAS unsigned*)(lds + (bufoff) + ldsw + _i * 8192), 16, 0, 0); } while (0)
; #define PG8_LDA(dst, b, h) do { _Pragma("unroll") for (int m = 0; m < 4; ++m) _Pragma("unroll") for (int k = 0; k < 2; ++k) dst[m][k] = *(const PG8_LAS bf16x8*)(lds + PG8_SA(b, h) + aoff + m * 2048 + k * 1024); } while (0)
; #define PG8_MMA(ai, bj, At, Bt) do { __builtin_amdgcn_s_setprio(1); _Pragma("unroll") for (int m = 0; m < 4; ++m) _Pragma("unroll") for (int n = 0; n < 2; ++n) _Pragma("unroll") for (int k = 0; k < 2; ++k) \
;         acc[ai][bj][m][n] = __builtin_amdgcn_mfma_f32_16x16x32_bf16(Bt[n][k], At[m][k], acc[ai][bj][m][n], 0, 0, 0); __builtin_amdgcn_s_setprio(0); } while (0)
; #define PG8_WAIT_V(n) asm volatile("s_waitcnt vmcnt(" #n ")" ::: "memory")
; #define PG8_WAIT_L(n) asm volatile("s_waitcnt lgkmcnt(" #n ")" ::: "memory")
; #define PG8_BAR __builtin_amdgcn_s_barrier()
; #define PG8_SCHED __builtin_amdgcn_sched_barrier(0)
; template <class Epi, class Sched, bool ALIGN_EPI = false, bool SP2 = false, bool ATILED = false>
; __device__ __forceinline__ void gemm_phase(PG8_LAS unsigned char* lds, const Gemm g, const Sched& S, const Epi& E) {
;     ...
;         for (int t = 0; t < nt; t += 2) {
;             const bool last = (t == nt - 2);
;             const char* a1 = cA + (size_t)(t + 1) * kstepA;
;             const char* a2 = last ? nA : cA + (size_t)(t + 2) * kstepA; const char* b2 = last ? nB : cB + (size_t)(t + 2) * kstep;
;             const char* a3 = a2 + kstepA; const char* b3 = b2 + kstep;
;             if (last && has_next) S.a_ready(nxt);
;     ...
;             PG8_LDA(At, 1, 1); PG8_STAGE(PG8_SB(1, 0), b3, voffB); PG8_STAGE(PG8_SB(1, 1), b3 + hstep, voffB); PG8_STAGE(PG8_SA(1, 0), a3, voffA);
;             PG8_WAIT_V(8); PG8_WAIT_L(0); PG8_BAR; PG8_MMA(1, 0, At, B0); PG8_MMA(1, 1, At, B1); PG8_BAR; PG8_SCHED;
	s_add_i32 s64, s88, s66
	v_lshl_add_u64 v[224:225], v[224:225], 0, s[8:9]
	s_mov_b32 m0, s64
	ds_read_b128 v[190:193], v158 offset:49152
	ds_read_b128 v[194:197], v158 offset:50176
	ds_read_b128 v[200:203], v158 offset:51200
	ds_read_b128 v[204:207], v158 offset:52224
	ds_read_b128 v[208:211], v158 offset:53248
	ds_read_b128 v[212:215], v158 offset:54272
	ds_read_b128 v[216:219], v158 offset:55296
	ds_read_b128 v[220:223], v158 offset:56320
	global_load_lds_dwordx4 v[224:225], off
	s_add_i32 m0, s64, 0x2000
	s_add_u32 s62, s62, 0x40080
	v_lshl_add_u64 v[224:225], v[226:227], 0, s[8:9]
	s_addc_u32 s63, s63, 0
	s_add_i32 s64, s89, s66
	global_load_lds_dwordx4 v[224:225], off
	v_lshl_add_u64 v[224:225], s[62:63], 0, v[130:131]
	s_mov_b32 m0, s64
	s_nop 0
	global_load_lds_dwordx4 v[224:225], off
	v_lshl_add_u64 v[224:225], s[62:63], 0, v[134:135]
	s_add_i32 m0, s64, 0x2000
	s_nop 0
	global_load_lds_dwordx4 v[224:225], off
	v_lshl_add_u64 v[224:225], v[228:229], 0, s[8:9]
	s_mov_b32 m0, s76
	s_nop 0
	global_load_lds_dwordx4 v[224:225], off
	v_lshl_add_u64 v[224:225], v[230:231], 0, s[8:9]
	s_mov_b32 m0, s77
	s_nop 0
	global_load_lds_dwordx4 v[224:225], off
	s_waitcnt vmcnt(8)
	s_waitcnt lgkmcnt(0)
	s_barrier
	s_waitcnt lgkmcnt(0)
	v_mfma_f32_16x16x32_bf16 v[60:63], v[150:153], v[190:193], v[60:63]
	v_mfma_f32_16x16x32_bf16 v[56:59], v[166:169], v[190:193], v[56:59]
	v_mfma_f32_16x16x32_bf16 v[44:47], v[150:153], v[200:203], v[44:47]
	v_mfma_f32_16x16x32_bf16 v[40:43], v[166:169], v[200:203], v[40:43]
	v_mfma_f32_16x16x32_bf16 v[28:31], v[150:153], v[208:211], v[28:31]
	v_mfma_f32_16x16x32_bf16 v[24:27], v[166:169], v[208:211], v[24:27]
	v_mfma_f32_16x16x32_bf16 v[12:15], v[150:153], v[216:219], v[12:15]
	v_mfma_f32_16x16x32_bf16 v[8:11], v[166:169], v[216:219], v[8:11]
	v_mfma_f32_16x16x32_bf16 v[60:63], v[162:165], v[194:197], v[60:63]
	v_mfma_f32_16x16x32_bf16 v[56:59], v[170:173], v[194:197], v[56:59]
	v_mfma_f32_16x16x32_bf16 v[44:47], v[162:165], v[204:207], v[44:47]
	v_mfma_f32_16x16x32_bf16 v[40:43], v[170:173], v[204:207], v[40:43]
	v_mfma_f32_16x16x32_bf16 v[28:31], v[162:165], v[212:215], v[28:31]
	v_mfma_f32_16x16x32_bf16 v[24:27], v[170:173], v[212:215], v[24:27]
	v_mfma_f32_16x16x32_bf16 v[12:15], v[162:165], v[220:223], v[12:15]
	v_mfma_f32_16x16x32_bf16 v[8:11], v[170:173], v[220:223], v[8:11]
	v_mfma_f32_16x16x32_bf16 v[52:55], v[174:177], v[190:193], v[52:55]
	v_mfma_f32_16x16x32_bf16 v[48:51], v[182:185], v[190:193], v[48:51]
	v_mfma_f32_16x16x32_bf16 v[36:39], v[174:177], v[200:203], v[36:39]
	v_mfma_f32_16x16x32_bf16 v[32:35], v[182:185], v[200:203], v[32:35]
	v_mfma_f32_16x16x32_bf16 v[20:23], v[174:177], v[208:211], v[20:23]
	v_mfma_f32_16x16x32_bf16 v[16:19], v[182:185], v[208:211], v[16:19]
	v_mfma_f32_16x16x32_bf16 v[4:7], v[174:177], v[216:219], v[4:7]
	v_mfma_f32_16x16x32_bf16 v[0:3], v[182:185], v[216:219], v[0:3]
	v_mfma_f32_16x16x32_bf16 v[52:55], v[178:181], v[194:197], v[52:55]
	v_mfma_f32_16x16x32_bf16 v[48:51], v[186:189], v[194:197], v[48:51]
	v_mfma_f32_16x16x32_bf16 v[36:39], v[178:181], v[204:207], v[36:39]
	v_mfma_f32_16x16x32_bf16 v[32:35], v[186:189], v[204:207], v[32:35]
	v_mfma_f32_16x16x32_bf16 v[20:23], v[178:181], v[212:215], v[20:23]
	v_mfma_f32_16x16x32_bf16 v[16:19], v[186:189], v[212:215], v[16:19]
	v_mfma_f32_16x16x32_bf16 v[4:7], v[178:181], v[220:223], v[4:7]
	v_mfma_f32_16x16x32_bf16 v[0:3], v[186:189], v[220:223], v[0:3]
	s_barrier
	s_add_i32 s87, s87, 2
	s_add_u32 s60, s60, 0x100
	s_addc_u32 s61, s61, 0
	s_add_u32 s85, s85, 0x100
	s_addc_u32 s86, s86, 0
	s_cmp_gt_u32 s87, 13
	s_cbranch_scc0 .LBB0_133
	s_and_b64 vcc, exec, s[38:39]
	s_cbranch_vccz .LBB0_136
	s_barrier

; #define PG8_STAGE(bufoff, gbase, voff) do { _Pragma("unroll") for (int _i = 0; _i < 2; ++_i) \
;         __builtin_amdgcn_global_load_lds((const unsigned*)((const char*)(gbase) + (voff)[_i]), (PG8_LAS unsigned*)(lds + (bufoff) + ldsw + _i * 8192), 16, 0, 0); } while (0)
; #define PG8_LDA(dst, b, h) do { _Pragma("unroll") for (int m = 0; m < 4; ++m) _Pragma("unroll") for (int k = 0; k < 2; ++k) dst[m][k] = *(const PG8_LAS bf16x8*)(lds + PG8_SA(b, h) + aoff + m * 2048 + k * 1024); } while (0)
; #define PG8_LDB(dst, b, h) do { _Pragma("unroll") for (int n = 0; n < 2; ++n) _Pragma("unroll") for (int k = 0; k < 2; ++k) dst[n][k] = *(const PG8_LAS bf16x8*)(lds + PG8_SB(b, h) + boff + n * 2048 + k * 1024); } while (0)
; #define PG8_MMA(ai, bj, At, Bt) do { __builtin_amdgcn_s_setprio(1); _Pragma("unroll") for (int m = 0; m < 4; ++m) _Pragma("unroll") for (int n = 0; n < 2; ++n) _Pragma("unroll") for (int k = 0; k < 2; ++k) \
;         acc[ai][bj][m][n] = __builtin_amdgcn_mfma_f32_16x16x32_bf16(Bt[n][k], At[m][k], acc[ai][bj][m][n], 0, 0, 0); __builtin_amdgcn_s_setprio(0); } while (0)
; #define PG8_WAIT_V(n) asm volatile("s_waitcnt vmcnt(" #n ")" ::: "memory")
; #define PG8_WAIT_L(n) asm volatile("s_waitcnt lgkmcnt(" #n ")" ::: "memory")
; #define PG8_BAR __builtin_amdgcn_s_barrier()
; #define PG8_SCHED __builtin_amdgcn_sched_barrier(0)
; template <class Epi, class Sched, bool ALIGN_EPI = false, bool SP2 = false, bool ATILED = false>
; __device__ __forceinline__ void gemm_phase(PG8_LAS unsigned char* lds, const Gemm g, const Sched& S, const Epi& E) {
;     ...
;             PG8_LDB(B0, 0, 0); PG8_LDB(B1, 0, 1); PG8_SCHED; PG8_LDA(At, 0, 0); PG8_STAGE(PG8_SA(1, 1), a1 + hstepA, voffA);
;             PG8_WAIT_V(8); PG8_WAIT_L(0); PG8_BAR; PG8_MMA(0, 0, At, B0); PG8_MMA(0, 1, At, B1); PG8_BAR; PG8_SCHED;
;             PG8_LDA(At, 0, 1); PG8_STAGE(PG8_SB(0, 0), b2, voffB); PG8_STAGE(PG8_SB(0, 1), b2 + hstep, voffB); PG8_STAGE(PG8_SA(0, 0), a2, voffA);
.LBB0_211:
	ds_read_b128 v[128:131], v189
	ds_read_b128 v[132:135], v189 offset:1024
	ds_read_b128 v[136:139], v189 offset:2048
	ds_read_b128 v[140:143], v189 offset:3072
	ds_read_b128 v[144:147], v190
	ds_read_b128 v[148:151], v190 offset:1024
	ds_read_b128 v[168:171], v190 offset:2048
	ds_read_b128 v[172:175], v190 offset:3072
	s_add_u32 s48, s46, 0x4000
	s_addc_u32 s49, s47, 0
	s_cmp_eq_u32 s81, 40
	s_cselect_b32 s62, s4, s48
	s_cselect_b32 s63, s5, s49
	s_cselect_b32 s60, s44, s79
	s_cselect_b32 s61, s45, s80
	s_add_u32 s48, s62, 0x8000
	s_addc_u32 s49, s63, 0
	v_lshl_add_u64 v[184:185], s[46:47], 0, v[160:161]
	s_add_i32 m0, s65, 0xc000
	ds_read_b128 v[176:179], v191
	ds_read_b128 v[180:183], v191 offset:1024
	ds_read_b128 v[194:197], v191 offset:2048
	ds_read_b128 v[200:203], v191 offset:3072
	ds_read_b128 v[204:207], v191 offset:4096
	ds_read_b128 v[208:211], v191 offset:5120
	ds_read_b128 v[212:215], v191 offset:6144
	ds_read_b128 v[216:219], v191 offset:7168
	global_load_lds_dwordx4 v[184:185], off
	v_lshl_add_u64 v[184:185], s[46:47], 0, v[162:163]
	s_add_i32 m0, s65, 0xe000
	s_nop 0
	global_load_lds_dwordx4 v[184:185], off
	s_waitcnt vmcnt(8)
	s_waitcnt lgkmcnt(0)
	s_barrier
	s_waitcnt lgkmcnt(0)
	v_mfma_f32_16x16x32_bf16 v[124:127], v[128:131], v[176:179], v[124:127]
	v_mfma_f32_16x16x32_bf16 v[120:123], v[136:139], v[176:179], v[120:123]
	v_mfma_f32_16x16x32_bf16 v[108:111], v[128:131], v[194:197], v[108:111]
	v_mfma_f32_16x16x32_bf16 v[104:107], v[136:139], v[194:197], v[104:107]
	v_mfma_f32_16x16x32_bf16 v[92:95], v[128:131], v[204:207], v[92:95]
	v_mfma_f32_16x16x32_bf16 v[88:91], v[136:139], v[204:207], v[88:91]
	v_mfma_f32_16x16x32_bf16 v[76:79], v[128:131], v[212:215], v[76:79]
	v_mfma_f32_16x16x32_bf16 v[72:75], v[136:139], v[212:215], v[72:75]
	v_mfma_f32_16x16x32_bf16 v[124:127], v[132:135], v[180:183], v[124:127]
	v_mfma_f32_16x16x32_bf16 v[120:123], v[140:143], v[180:183], v[120:123]
	v_mfma_f32_16x16x32_bf16 v[108:111], v[132:135], v[200:203], v[108:111]
	v_mfma_f32_16x16x32_bf16 v[104:107], v[140:143], v[200:203], v[104:107]
	v_mfma_f32_16x16x32_bf16 v[92:95], v[132:135], v[208:211], v[92:95]
	v_mfma_f32_16x16x32_bf16 v[88:91], v[140:143], v[208:211], v[88:91]
	v_mfma_f32_16x16x32_bf16 v[76:79], v[132:135], v[216:219], v[76:79]
	v_mfma_f32_16x16x32_bf16 v[72:75], v[140:143], v[216:219], v[72:75]
	v_mfma_f32_16x16x32_bf16 v[116:119], v[144:147], v[176:179], v[116:119]
	v_mfma_f32_16x16x32_bf16 v[112:115], v[168:171], v[176:179], v[112:115]
	v_mfma_f32_16x16x32_bf16 v[100:103], v[144:147], v[194:197], v[100:103]
	v_mfma_f32_16x16x32_bf16 v[96:99], v[168:171], v[194:197], v[96:99]
	v_mfma_f32_16x16x32_bf16 v[84:87], v[144:147], v[204:207], v[84:87]
	v_mfma_f32_16x16x32_bf16 v[80:83], v[168:171], v[204:207], v[80:83]
	v_mfma_f32_16x16x32_bf16 v[68:71], v[144:147], v[212:215], v[68:71]
	v_mfma_f32_16x16x32_bf16 v[64:67], v[168:171], v[212:215], v[64:67]
	v_mfma_f32_16x16x32_bf16 v[116:119], v[148:151], v[180:183], v[116:119]
	v_mfma_f32_16x16x32_bf16 v[112:115], v[172:175], v[180:183], v[112:115]
	v_mfma_f32_16x16x32_bf16 v[100:103], v[148:151], v[200:203], v[100:103]
	v_mfma_f32_16x16x32_bf16 v[96:99], v[172:175], v[200:203], v[96:99]
	v_mfma_f32_16x16x32_bf16 v[84:87], v[148:151], v[208:211], v[84:87]
	v_mfma_f32_16x16x32_bf16 v[80:83], v[172:175], v[208:211], v[80:83]
	v_mfma_f32_16x16x32_bf16 v[68:71], v[148:151], v[216:219], v[68:71]
	v_mfma_f32_16x16x32_bf16 v[64:67], v[172:175], v[216:219], v[64:67]
	s_barrier
	s_add_i32 s83, s73, s64
	v_lshl_add_u64 v[184:185], s[60:61], 0, v[154:155]
	s_mov_b32 m0, s83
	ds_read_b128 v[176:179], v191 offset:16384
	ds_read_b128 v[180:183], v191 offset:17408
	ds_read_b128 v[194:197], v191 offset:18432
	ds_read_b128 v[200:203], v191 offset:19456
	ds_read_b128 v[204:207], v191 offset:20480
	ds_read_b128 v[208:211], v191 offset:21504
	ds_read_b128 v[212:215], v191 offset:22528
	ds_read_b128 v[216:219], v191 offset:23552
	global_load_lds_dwordx4 v[184:185], off
	s_add_i32 m0, s83, 0x2000
	s_add_u32 s84, s60, 0xb0000
	v_lshl_add_u64 v[220:221], s[60:61], 0, v[158:159]
	s_addc_u32 s85, s61, 0
	s_add_i32 s83, s74, s64
	global_load_lds_dwordx4 v[220:221], off
	v_lshl_add_u64 v[222:223], s[84:85], 0, v[154:155]
	s_mov_b32 m0, s83
	s_nop 0
	global_load_lds_dwordx4 v[222:223], off
	v_lshl_add_u64 v[222:223], s[84:85], 0, v[158:159]
	s_add_i32 m0, s83, 0x2000
	s_nop 0
	global_load_lds_dwordx4 v[222:223], off
	v_lshl_add_u64 v[222:223], s[62:63], 0, v[152:153]
	s_mov_b32 m0, s65
	s_nop 0
	global_load_lds_dwordx4 v[222:223], off
	v_lshl_add_u64 v[222:223], s[62:63], 0, v[156:157]
	s_mov_b32 m0, s66
	s_nop 0
	global_load_lds_dwordx4 v[222:223], off
	s_waitcnt vmcnt(8)
	s_waitcnt lgkmcnt(0)
	s_barrier
; #define PG8_STAGE(bufoff, gbase, voff) do { _Pragma("unroll") for (int _i = 0; _i < 2; ++_i) \
;         __builtin_amdgcn_global_load_lds((const unsigned*)((const char*)(gbase) + (voff)[_i]), (PG8_LAS unsigned*)(lds + (bufoff) + ldsw + _i * 8192), 16, 0, 0); } while (0)
; #define PG8_LDA(dst, b, h) do { _Pragma("unroll") for (int m = 0; m < 4; ++m) _Pragma("unroll") for (int k = 0; k < 2; ++k) dst[m][k] = *(const PG8_LAS bf16x8*)(lds + PG8_SA(b, h) + aoff + m * 2048 + k * 1024); } while (0)
; #define PG8_LDB(dst, b, h) do { _Pragma("unroll") for (int n = 0; n < 2; ++n) _Pragma("unroll") for (int k = 0; k < 2; ++k) dst[n][k] = *(const PG8_LAS bf16x8*)(lds + PG8_SB(b, h) + boff + n * 2048 + k * 1024); } while (0)
; #define PG8_MMA(ai, bj, At, Bt) do { __builtin_amdgcn_s_setprio(1); _Pragma("unroll") for (int m = 0; m < 4; ++m) _Pragma("unroll") for (int n = 0; n < 2; ++n) _Pragma("unroll") for (int k = 0; k < 2; ++k) \
;         acc[ai][bj][m][n] = __builtin_amdgcn_mfma_f32_16x16x32_bf16(Bt[n][k], At[m][k], acc[ai][bj][m][n], 0, 0, 0); __builtin_amdgcn_s_setprio(0); } while (0)
; #define PG8_WAIT_V(n) asm volatile("s_waitcnt vmcnt(" #n ")" ::: "memory")
; #define PG8_WAIT_L(n) asm volatile("s_waitcnt lgkmcnt(" #n ")" ::: "memory")
; #define PG8_BAR __builtin_amdgcn_s_barrier()
; #define PG8_SCHED __builtin_amdgcn_sched_barrier(0)
; template <class Epi, class Sched, bool ALIGN_EPI = false, bool SP2 = false, bool ATILED = false>
; __device__ __forceinline__ void gemm_phase(PG8_LAS unsigned char* lds, const Gemm g, const Sched& S, const Epi& E) {
;     ...
;             PG8_WAIT_V(8); PG8_WAIT_L(0); PG8_BAR; PG8_MMA(1, 0, At, B0); PG8_MMA(1, 1, At, B1); PG8_BAR; PG8_SCHED;
;             PG8_LDB(B0, 1, 0); PG8_LDB(B1, 1, 1); PG8_SCHED; PG8_LDA(At, 1, 0); PG8_STAGE(PG8_SA(0, 1), a2 + hstepA, voffA);
;             PG8_WAIT_V(8); PG8_WAIT_L(0); PG8_BAR; PG8_MMA(0, 0, At, B0); PG8_MMA(0, 1, At, B1); PG8_BAR; PG8_SCHED;
	s_waitcnt lgkmcnt(0)
	v_mfma_f32_16x16x32_bf16 v[60:63], v[128:131], v[176:179], v[60:63]
	v_mfma_f32_16x16x32_bf16 v[56:59], v[136:139], v[176:179], v[56:59]
	v_mfma_f32_16x16x32_bf16 v[44:47], v[128:131], v[194:197], v[44:47]
	v_mfma_f32_16x16x32_bf16 v[40:43], v[136:139], v[194:197], v[40:43]
	v_mfma_f32_16x16x32_bf16 v[28:31], v[128:131], v[204:207], v[28:31]
	v_mfma_f32_16x16x32_bf16 v[24:27], v[136:139], v[204:207], v[24:27]
	v_mfma_f32_16x16x32_bf16 v[12:15], v[128:131], v[212:215], v[12:15]
	v_mfma_f32_16x16x32_bf16 v[8:11], v[136:139], v[212:215], v[8:11]
	v_mfma_f32_16x16x32_bf16 v[60:63], v[132:135], v[180:183], v[60:63]
	v_mfma_f32_16x16x32_bf16 v[56:59], v[140:143], v[180:183], v[56:59]
	v_mfma_f32_16x16x32_bf16 v[44:47], v[132:135], v[200:203], v[44:47]
	v_mfma_f32_16x16x32_bf16 v[40:43], v[140:143], v[200:203], v[40:43]
	v_mfma_f32_16x16x32_bf16 v[28:31], v[132:135], v[208:211], v[28:31]
	v_mfma_f32_16x16x32_bf16 v[24:27], v[140:143], v[208:211], v[24:27]
	v_mfma_f32_16x16x32_bf16 v[12:15], v[132:135], v[216:219], v[12:15]
	v_mfma_f32_16x16x32_bf16 v[8:11], v[140:143], v[216:219], v[8:11]
	v_mfma_f32_16x16x32_bf16 v[52:55], v[144:147], v[176:179], v[52:55]
	v_mfma_f32_16x16x32_bf16 v[48:51], v[168:171], v[176:179], v[48:51]
	v_mfma_f32_16x16x32_bf16 v[36:39], v[144:147], v[194:197], v[36:39]
	v_mfma_f32_16x16x32_bf16 v[32:35], v[168:171], v[194:197], v[32:35]
	v_mfma_f32_16x16x32_bf16 v[20:23], v[144:147], v[204:207], v[20:23]
	v_mfma_f32_16x16x32_bf16 v[16:19], v[168:171], v[204:207], v[16:19]
	v_mfma_f32_16x16x32_bf16 v[4:7], v[144:147], v[212:215], v[4:7]
	v_mfma_f32_16x16x32_bf16 v[0:3], v[168:171], v[212:215], v[0:3]
	v_mfma_f32_16x16x32_bf16 v[52:55], v[148:151], v[180:183], v[52:55]
	v_mfma_f32_16x16x32_bf16 v[48:51], v[172:175], v[180:183], v[48:51]
	v_mfma_f32_16x16x32_bf16 v[36:39], v[148:151], v[200:203], v[36:39]
	v_mfma_f32_16x16x32_bf16 v[32:35], v[172:175], v[200:203], v[32:35]
	v_mfma_f32_16x16x32_bf16 v[20:23], v[148:151], v[208:211], v[20:23]
	v_mfma_f32_16x16x32_bf16 v[16:19], v[172:175], v[208:211], v[16:19]
	v_mfma_f32_16x16x32_bf16 v[4:7], v[148:151], v[216:219], v[4:7]
	v_mfma_f32_16x16x32_bf16 v[0:3], v[172:175], v[216:219], v[0:3]
	s_barrier
	s_add_i32 s83, 0, 0x18000
	s_add_i32 s84, 0, 0x1c000
	v_add_u32_e32 v140, s83, v187
	v_add_u32_e32 v172, s84, v187
	ds_read_b128 v[128:131], v140
	ds_read_b128 v[132:135], v140 offset:1024
	ds_read_b128 v[136:139], v140 offset:2048
	ds_read_b128 v[140:143], v140 offset:3072
	ds_read_b128 v[144:147], v172
	ds_read_b128 v[148:151], v172 offset:1024
	ds_read_b128 v[168:171], v172 offset:2048
	ds_read_b128 v[172:175], v172 offset:3072
	s_add_u32 s62, s62, 0x4000
	s_addc_u32 s63, s63, 0
	s_mov_b32 m0, s67
	v_lshl_add_u64 v[222:223], s[62:63], 0, v[152:153]
	ds_read_b128 v[176:179], v191 offset:32768
	ds_read_b128 v[180:183], v191 offset:33792
	ds_read_b128 v[194:197], v191 offset:34816
	ds_read_b128 v[200:203], v191 offset:35840
	ds_read_b128 v[204:207], v191 offset:36864
	ds_read_b128 v[208:211], v191 offset:37888
	ds_read_b128 v[212:215], v191 offset:38912
	ds_read_b128 v[216:219], v191 offset:39936
	global_load_lds_dwordx4 v[222:223], off
	v_lshl_add_u64 v[222:223], s[62:63], 0, v[156:157]
	s_mov_b32 m0, s68
	s_nop 0
	global_load_lds_dwordx4 v[222:223], off
	s_waitcnt vmcnt(8)
	s_waitcnt lgkmcnt(0)
	s_barrier
	s_waitcnt lgkmcnt(0)
	v_mfma_f32_16x16x32_bf16 v[124:127], v[128:131], v[176:179], v[124:127]
	v_mfma_f32_16x16x32_bf16 v[120:123], v[136:139], v[176:179], v[120:123]
	v_mfma_f32_16x16x32_bf16 v[108:111], v[128:131], v[194:197], v[108:111]
	v_mfma_f32_16x16x32_bf16 v[104:107], v[136:139], v[194:197], v[104:107]
	v_mfma_f32_16x16x32_bf16 v[92:95], v[128:131], v[204:207], v[92:95]
	v_mfma_f32_16x16x32_bf16 v[88:91], v[136:139], v[204:207], v[88:91]
	v_mfma_f32_16x16x32_bf16 v[76:79], v[128:131], v[212:215], v[76:79]
	v_mfma_f32_16x16x32_bf16 v[72:75], v[136:139], v[212:215], v[72:75]
	v_mfma_f32_16x16x32_bf16 v[124:127], v[132:135], v[180:183], v[124:127]
	v_mfma_f32_16x16x32_bf16 v[120:123], v[140:143], v[180:183], v[120:123]
	v_mfma_f32_16x16x32_bf16 v[108:111], v[132:135], v[200:203], v[108:111]
	v_mfma_f32_16x16x32_bf16 v[104:107], v[140:143], v[200:203], v[104:107]
	v_mfma_f32_16x16x32_bf16 v[92:95], v[132:135], v[208:211], v[92:95]
	v_mfma_f32_16x16x32_bf16 v[88:91], v[140:143], v[208:211], v[88:91]
	v_mfma_f32_16x16x32_bf16 v[76:79], v[132:135], v[216:219], v[76:79]
	v_mfma_f32_16x16x32_bf16 v[72:75], v[140:143], v[216:219], v[72:75]
	v_mfma_f32_16x16x32_bf16 v[116:119], v[144:147], v[176:179], v[116:119]
	v_mfma_f32_16x16x32_bf16 v[112:115], v[168:171], v[176:179], v[112:115]
	v_mfma_f32_16x16x32_bf16 v[100:103], v[144:147], v[194:197], v[100:103]
	v_mfma_f32_16x16x32_bf16 v[96:99], v[168:171], v[194:197], v[96:99]
	v_mfma_f32_16x16x32_bf16 v[84:87], v[144:147], v[204:207], v[84:87]
	v_mfma_f32_16x16x32_bf16 v[80:83], v[168:171], v[204:207], v[80:83]
	v_mfma_f32_16x16x32_bf16 v[68:71], v[144:147], v[212:215], v[68:71]
	v_mfma_f32_16x16x32_bf16 v[64:67], v[168:171], v[212:215], v[64:67]
	v_mfma_f32_16x16x32_bf16 v[116:119], v[148:151], v[180:183], v[116:119]
	v_mfma_f32_16x16x32_bf16 v[112:115], v[172:175], v[180:183], v[112:115]
	v_mfma_f32_16x16x32_bf16 v[100:103], v[148:151], v[200:203], v[100:103]
	v_mfma_f32_16x16x32_bf16 v[96:99], v[172:175], v[200:203], v[96:99]
	v_mfma_f32_16x16x32_bf16 v[84:87], v[148:151], v[208:211], v[84:87]
	v_mfma_f32_16x16x32_bf16 v[80:83], v[172:175], v[208:211], v[80:83]
	v_mfma_f32_16x16x32_bf16 v[68:71], v[148:151], v[216:219], v[68:71]
	v_mfma_f32_16x16x32_bf16 v[64:67], v[172:175], v[216:219], v[64:67]
	s_barrier
; #define PG8_STAGE(bufoff, gbase, voff) do { _Pragma("unroll") for (int _i = 0; _i < 2; ++_i) \
;         __builtin_amdgcn_global_load_lds((const unsigned*)((const char*)(gbase) + (voff)[_i]), (PG8_LAS unsigned*)(lds + (bufoff) + ldsw + _i * 8192), 16, 0, 0); } while (0)
; #define PG8_LDA(dst, b, h) do { _Pragma("unroll") for (int m = 0; m < 4; ++m) _Pragma("unroll") for (int k = 0; k < 2; ++k) dst[m][k] = *(const PG8_LAS bf16x8*)(lds + PG8_SA(b, h) + aoff + m * 2048 + k * 1024); } while (0)
; #define PG8_MMA(ai, bj, At, Bt) do { __builtin_amdgcn_s_setprio(1); _Pragma("unroll") for (int m = 0; m < 4; ++m) _Pragma("unroll") for (int n = 0; n < 2; ++n) _Pragma("unroll") for (int k = 0; k < 2; ++k) \
;         acc[ai][bj][m][n] = __builtin_amdgcn_mfma_f32_16x16x32_bf16(Bt[n][k], At[m][k], acc[ai][bj][m][n], 0, 0, 0); __builtin_amdgcn_s_setprio(0); } while (0)
; #define PG8_WAIT_V(n) asm volatile("s_waitcnt vmcnt(" #n ")" ::: "memory")
; #define PG8_WAIT_L(n) asm volatile("s_waitcnt lgkmcnt(" #n ")" ::: "memory")
; #define PG8_BAR __builtin_amdgcn_s_barrier()
; #define PG8_SCHED __builtin_amdgcn_sched_barrier(0)
; template <class Epi, class Sched, bool ALIGN_EPI = false, bool SP2 = false, bool ATILED = false>
; __device__ __forceinline__ void gemm_phase(PG8_LAS unsigned char* lds, const Gemm g, const Sched& S, const Epi& E) {
;     ...
;         for (int t = 0; t < nt; t += 2) {
;             const bool last = (t == nt - 2);
;             const char* a1 = cA + (size_t)(t + 1) * kstepA;
;             const char* a2 = last ? nA : cA + (size_t)(t + 2) * kstepA; const char* b2 = last ? nB : cB + (size_t)(t + 2) * kstep;
;             const char* a3 = a2 + kstepA; const char* b3 = b2 + kstep;
;             if (last && has_next) S.a_ready(nxt);
;     ...
;             PG8_LDA(At, 1, 1); PG8_STAGE(PG8_SB(1, 0), b3, voffB); PG8_STAGE(PG8_SB(1, 1), b3 + hstep, voffB); PG8_STAGE(PG8_SA(1, 0), a3, voffA);
;             PG8_WAIT_V(8); PG8_WAIT_L(0); PG8_BAR; PG8_MMA(1, 0, At, B0); PG8_MMA(1, 1, At, B1); PG8_BAR; PG8_SCHED;
	s_add_i32 s62, s83, s64
	v_lshl_add_u64 v[184:185], v[184:185], 0, s[40:41]
	s_mov_b32 m0, s62
	ds_read_b128 v[176:179], v191 offset:49152
	ds_read_b128 v[180:183], v191 offset:50176
	ds_read_b128 v[194:197], v191 offset:51200
	ds_read_b128 v[200:203], v191 offset:52224
	ds_read_b128 v[204:207], v191 offset:53248
	ds_read_b128 v[208:211], v191 offset:54272
	ds_read_b128 v[212:215], v191 offset:55296
	ds_read_b128 v[216:219], v191 offset:56320
	global_load_lds_dwordx4 v[184:185], off
	s_add_i32 m0, s62, 0x2000
	s_add_u32 s60, s60, 0xb0080
	v_lshl_add_u64 v[184:185], v[220:221], 0, s[40:41]
	s_addc_u32 s61, s61, 0
	s_add_i32 s62, s84, s64
	global_load_lds_dwordx4 v[184:185], off
	v_lshl_add_u64 v[184:185], s[60:61], 0, v[154:155]
	s_mov_b32 m0, s62
	s_nop 0
	global_load_lds_dwordx4 v[184:185], off
	v_lshl_add_u64 v[184:185], s[60:61], 0, v[158:159]
	s_add_i32 m0, s62, 0x2000
	s_nop 0
	global_load_lds_dwordx4 v[184:185], off
	v_lshl_add_u64 v[184:185], s[48:49], 0, v[152:153]
	s_mov_b32 m0, s71
	s_nop 0
	global_load_lds_dwordx4 v[184:185], off
	v_lshl_add_u64 v[184:185], s[48:49], 0, v[156:157]
	s_mov_b32 m0, s72
	s_nop 0
	global_load_lds_dwordx4 v[184:185], off
	s_waitcnt vmcnt(8)
	s_waitcnt lgkmcnt(0)
	s_barrier
	s_waitcnt lgkmcnt(0)
	v_mfma_f32_16x16x32_bf16 v[60:63], v[128:131], v[176:179], v[60:63]
	v_mfma_f32_16x16x32_bf16 v[56:59], v[136:139], v[176:179], v[56:59]
	v_mfma_f32_16x16x32_bf16 v[44:47], v[128:131], v[194:197], v[44:47]
	v_mfma_f32_16x16x32_bf16 v[40:43], v[136:139], v[194:197], v[40:43]
	v_mfma_f32_16x16x32_bf16 v[28:31], v[128:131], v[204:207], v[28:31]
	v_mfma_f32_16x16x32_bf16 v[24:27], v[136:139], v[204:207], v[24:27]
	v_mfma_f32_16x16x32_bf16 v[12:15], v[128:131], v[212:215], v[12:15]
	v_mfma_f32_16x16x32_bf16 v[8:11], v[136:139], v[212:215], v[8:11]
	v_mfma_f32_16x16x32_bf16 v[60:63], v[132:135], v[180:183], v[60:63]
	v_mfma_f32_16x16x32_bf16 v[56:59], v[140:143], v[180:183], v[56:59]
	v_mfma_f32_16x16x32_bf16 v[44:47], v[132:135], v[200:203], v[44:47]
	v_mfma_f32_16x16x32_bf16 v[40:43], v[140:143], v[200:203], v[40:43]
	v_mfma_f32_16x16x32_bf16 v[28:31], v[132:135], v[208:211], v[28:31]
	v_mfma_f32_16x16x32_bf16 v[24:27], v[140:143], v[208:211], v[24:27]
	v_mfma_f32_16x16x32_bf16 v[12:15], v[132:135], v[216:219], v[12:15]
	v_mfma_f32_16x16x32_bf16 v[8:11], v[140:143], v[216:219], v[8:11]
	v_mfma_f32_16x16x32_bf16 v[52:55], v[144:147], v[176:179], v[52:55]
	v_mfma_f32_16x16x32_bf16 v[48:51], v[168:171], v[176:179], v[48:51]
	v_mfma_f32_16x16x32_bf16 v[36:39], v[144:147], v[194:197], v[36:39]
	v_mfma_f32_16x16x32_bf16 v[32:35], v[168:171], v[194:197], v[32:35]
	v_mfma_f32_16x16x32_bf16 v[20:23], v[144:147], v[204:207], v[20:23]
	v_mfma_f32_16x16x32_bf16 v[16:19], v[168:171], v[204:207], v[16:19]
	v_mfma_f32_16x16x32_bf16 v[4:7], v[144:147], v[212:215], v[4:7]
	v_mfma_f32_16x16x32_bf16 v[0:3], v[168:171], v[212:215], v[0:3]
	v_mfma_f32_16x16x32_bf16 v[52:55], v[148:151], v[180:183], v[52:55]
	v_mfma_f32_16x16x32_bf16 v[48:51], v[172:175], v[180:183], v[48:51]
	v_mfma_f32_16x16x32_bf16 v[36:39], v[148:151], v[200:203], v[36:39]
	v_mfma_f32_16x16x32_bf16 v[32:35], v[172:175], v[200:203], v[32:35]
	v_mfma_f32_16x16x32_bf16 v[20:23], v[148:151], v[208:211], v[20:23]
	v_mfma_f32_16x16x32_bf16 v[16:19], v[172:175], v[208:211], v[16:19]
	v_mfma_f32_16x16x32_bf16 v[4:7], v[148:151], v[216:219], v[4:7]
	v_mfma_f32_16x16x32_bf16 v[0:3], v[172:175], v[216:219], v[0:3]
	s_barrier
	s_add_i32 s81, s81, 2
	s_add_u32 s79, s79, 0x100
	s_addc_u32 s80, s80, 0
	s_add_u32 s46, s46, 0x10000
	s_addc_u32 s47, s47, 0
	s_cmp_gt_u32 s81, 41
	s_cbranch_scc0 .LBB0_211
	s_and_b64 vcc, exec, s[42:43]
	s_cbranch_vccz .LBB0_214
	s_barrier

; #define PG8_STAGE(bufoff, gbase, voff) do { _Pragma("unroll") for (int _i = 0; _i < 2; ++_i) \
;         __builtin_amdgcn_global_load_lds((const unsigned*)((const char*)(gbase) + (voff)[_i]), (PG8_LAS unsigned*)(lds + (bufoff) + ldsw + _i * 8192), 16, 0, 0); } while (0)
; #define PG8_LDA(dst, b, h) do { _Pragma("unroll") for (int m = 0; m < 4; ++m) _Pragma("unroll") for (int k = 0; k < 2; ++k) dst[m][k] = *(const PG8_LAS bf16x8*)(lds + PG8_SA(b, h) + aoff + m * 2048 + k * 1024); } while (0)
; #define PG8_LDB(dst, b, h) do { _Pragma("unroll") for (int n = 0; n < 2; ++n) _Pragma("unroll") for (int k = 0; k < 2; ++k) dst[n][k] = *(const PG8_LAS bf16x8*)(lds + PG8_SB(b, h) + boff + n * 2048 + k * 1024); } while (0)
; #define PG8_MMA(ai, bj, At, Bt) do { __builtin_amdgcn_s_setprio(1); _Pragma("unroll") for (int m = 0; m < 4; ++m) _Pragma("unroll") for (int n = 0; n < 2; ++n) _Pragma("unroll") for (int k = 0; k < 2; ++k) \
;         acc[ai][bj][m][n] = __builtin_amdgcn_mfma_f32_16x16x32_bf16(Bt[n][k], At[m][k], acc[ai][bj][m][n], 0, 0, 0); __builtin_amdgcn_s_setprio(0); } while (0)
; #define PG8_WAIT_V(n) asm volatile("s_waitcnt vmcnt(" #n ")" ::: "memory")
; #define PG8_WAIT_L(n) asm volatile("s_waitcnt lgkmcnt(" #n ")" ::: "memory")
; #define PG8_BAR __builtin_amdgcn_s_barrier()
; #define PG8_SCHED __builtin_amdgcn_sched_barrier(0)
; template <class Epi, class Sched, bool ALIGN_EPI = false, bool SP2 = false, bool ATILED = false>
; __device__ __forceinline__ void gemm_phase(PG8_LAS unsigned char* lds, const Gemm g, const Sched& S, const Epi& E) {
;     ...
;             PG8_LDB(B0, 0, 0); PG8_LDB(B1, 0, 1); PG8_SCHED; PG8_LDA(At, 0, 0); PG8_STAGE(PG8_SA(1, 1), a1 + hstepA, voffA);
;             PG8_WAIT_V(8); PG8_WAIT_L(0); PG8_BAR; PG8_MMA(0, 0, At, B0); PG8_MMA(0, 1, At, B1); PG8_BAR; PG8_SCHED;
;             PG8_LDA(At, 0, 1); PG8_STAGE(PG8_SB(0, 0), b2, voffB); PG8_STAGE(PG8_SB(0, 1), b2 + hstep, voffB); PG8_STAGE(PG8_SA(0, 0), a2, voffA);
.LBB0_300:
	ds_read_b128 v[156:159], v201
	ds_read_b128 v[160:163], v201 offset:1024
	ds_read_b128 v[164:167], v201 offset:2048
	ds_read_b128 v[168:171], v201 offset:3072
	ds_read_b128 v[172:175], v202
	ds_read_b128 v[176:179], v202 offset:1024
	ds_read_b128 v[180:183], v202 offset:2048
	ds_read_b128 v[184:187], v202 offset:3072
	s_add_u32 s66, s64, 0xfffc0080
	s_addc_u32 s67, s65, -1
	s_cmp_eq_u32 s83, 12
	s_cselect_b32 s69, s5, s67
	s_cselect_b32 s68, s6, s66
	s_cselect_b32 s67, s45, s63
	s_cselect_b32 s66, s47, s49
	v_lshl_add_u64 v[196:197], s[64:65], 0, v[146:147]
	s_add_i32 m0, s71, 0xc000
	ds_read_b128 v[188:191], v203
	ds_read_b128 v[192:195], v203 offset:1024
	ds_read_b128 v[208:211], v203 offset:2048
	ds_read_b128 v[212:215], v203 offset:3072
	ds_read_b128 v[216:219], v203 offset:4096
	ds_read_b128 v[220:223], v203 offset:5120
	ds_read_b128 v[224:227], v203 offset:6144
	ds_read_b128 v[228:231], v203 offset:7168
	global_load_lds_dwordx4 v[196:197], off
	v_lshl_add_u64 v[196:197], s[64:65], 0, v[148:149]
	s_add_i32 m0, s71, 0xe000
	s_nop 0
	global_load_lds_dwordx4 v[196:197], off
	s_waitcnt vmcnt(8)
	s_waitcnt lgkmcnt(0)
	s_barrier
	s_waitcnt lgkmcnt(0)
	v_mfma_f32_16x16x32_bf16 v[124:127], v[156:159], v[188:191], v[124:127]
	v_mfma_f32_16x16x32_bf16 v[120:123], v[164:167], v[188:191], v[120:123]
	v_mfma_f32_16x16x32_bf16 v[116:119], v[156:159], v[208:211], v[116:119]
	v_mfma_f32_16x16x32_bf16 v[112:115], v[164:167], v[208:211], v[112:115]
	v_mfma_f32_16x16x32_bf16 v[96:99], v[156:159], v[216:219], v[96:99]
	v_mfma_f32_16x16x32_bf16 v[88:91], v[164:167], v[216:219], v[88:91]
	v_mfma_f32_16x16x32_bf16 v[80:83], v[156:159], v[224:227], v[80:83]
	v_mfma_f32_16x16x32_bf16 v[72:75], v[164:167], v[224:227], v[72:75]
	v_mfma_f32_16x16x32_bf16 v[124:127], v[160:163], v[192:195], v[124:127]
	v_mfma_f32_16x16x32_bf16 v[120:123], v[168:171], v[192:195], v[120:123]
	v_mfma_f32_16x16x32_bf16 v[116:119], v[160:163], v[212:215], v[116:119]
	v_mfma_f32_16x16x32_bf16 v[112:115], v[168:171], v[212:215], v[112:115]
	v_mfma_f32_16x16x32_bf16 v[96:99], v[160:163], v[220:223], v[96:99]
	v_mfma_f32_16x16x32_bf16 v[88:91], v[168:171], v[220:223], v[88:91]
	v_mfma_f32_16x16x32_bf16 v[80:83], v[160:163], v[228:231], v[80:83]
	v_mfma_f32_16x16x32_bf16 v[72:75], v[168:171], v[228:231], v[72:75]
	v_mfma_f32_16x16x32_bf16 v[108:111], v[172:175], v[188:191], v[108:111]
	v_mfma_f32_16x16x32_bf16 v[104:107], v[180:183], v[188:191], v[104:107]
	v_mfma_f32_16x16x32_bf16 v[100:103], v[172:175], v[208:211], v[100:103]
	v_mfma_f32_16x16x32_bf16 v[92:95], v[180:183], v[208:211], v[92:95]
	v_mfma_f32_16x16x32_bf16 v[84:87], v[172:175], v[216:219], v[84:87]
	v_mfma_f32_16x16x32_bf16 v[76:79], v[180:183], v[216:219], v[76:79]
	v_mfma_f32_16x16x32_bf16 v[68:71], v[172:175], v[224:227], v[68:71]
	v_mfma_f32_16x16x32_bf16 v[64:67], v[180:183], v[224:227], v[64:67]
	v_mfma_f32_16x16x32_bf16 v[108:111], v[176:179], v[192:195], v[108:111]
	v_mfma_f32_16x16x32_bf16 v[104:107], v[184:187], v[192:195], v[104:107]
	v_mfma_f32_16x16x32_bf16 v[100:103], v[176:179], v[212:215], v[100:103]
	v_mfma_f32_16x16x32_bf16 v[92:95], v[184:187], v[212:215], v[92:95]
	v_mfma_f32_16x16x32_bf16 v[84:87], v[176:179], v[220:223], v[84:87]
	v_mfma_f32_16x16x32_bf16 v[76:79], v[184:187], v[220:223], v[76:79]
	v_mfma_f32_16x16x32_bf16 v[68:71], v[176:179], v[228:231], v[68:71]
	v_mfma_f32_16x16x32_bf16 v[64:67], v[184:187], v[228:231], v[64:67]
	s_barrier
	s_add_i32 s84, s79, s70
	v_lshl_add_u64 v[196:197], s[66:67], 0, v[130:131]
	s_mov_b32 m0, s84
	ds_read_b128 v[188:191], v203 offset:16384
	ds_read_b128 v[192:195], v203 offset:17408
	ds_read_b128 v[208:211], v203 offset:18432
	ds_read_b128 v[212:215], v203 offset:19456
	ds_read_b128 v[216:219], v203 offset:20480
	ds_read_b128 v[220:223], v203 offset:21504
	ds_read_b128 v[224:227], v203 offset:22528
	ds_read_b128 v[228:231], v203 offset:23552
	global_load_lds_dwordx4 v[196:197], off
	s_add_i32 m0, s84, 0x2000
	s_add_u32 s84, s66, 0x40000
	v_lshl_add_u64 v[232:233], s[66:67], 0, v[134:135]
	s_addc_u32 s85, s67, 0
	s_add_i32 s86, s80, s70
	global_load_lds_dwordx4 v[232:233], off
	v_lshl_add_u64 v[234:235], s[84:85], 0, v[130:131]
	s_mov_b32 m0, s86
	v_lshl_add_u64 v[236:237], s[68:69], 0, v[132:133]
	global_load_lds_dwordx4 v[234:235], off
	v_lshl_add_u64 v[234:235], s[84:85], 0, v[134:135]
	s_add_i32 m0, s86, 0x2000
	s_nop 0
	global_load_lds_dwordx4 v[234:235], off
	v_lshl_add_u64 v[234:235], s[68:69], 0, v[128:129]
	s_mov_b32 m0, s71
	s_nop 0
	global_load_lds_dwordx4 v[234:235], off
	s_mov_b32 m0, s72
	s_nop 0
	global_load_lds_dwordx4 v[236:237], off
	s_waitcnt vmcnt(8)
	s_waitcnt lgkmcnt(0)
	s_barrier
; #define PG8_STAGE(bufoff, gbase, voff) do { _Pragma("unroll") for (int _i = 0; _i < 2; ++_i) \
;         __builtin_amdgcn_global_load_lds((const unsigned*)((const char*)(gbase) + (voff)[_i]), (PG8_LAS unsigned*)(lds + (bufoff) + ldsw + _i * 8192), 16, 0, 0); } while (0)
; #define PG8_LDA(dst, b, h) do { _Pragma("unroll") for (int m = 0; m < 4; ++m) _Pragma("unroll") for (int k = 0; k < 2; ++k) dst[m][k] = *(const PG8_LAS bf16x8*)(lds + PG8_SA(b, h) + aoff + m * 2048 + k * 1024); } while (0)
; #define PG8_LDB(dst, b, h) do { _Pragma("unroll") for (int n = 0; n < 2; ++n) _Pragma("unroll") for (int k = 0; k < 2; ++k) dst[n][k] = *(const PG8_LAS bf16x8*)(lds + PG8_SB(b, h) + boff + n * 2048 + k * 1024); } while (0)
; #define PG8_MMA(ai, bj, At, Bt) do { __builtin_amdgcn_s_setprio(1); _Pragma("unroll") for (int m = 0; m < 4; ++m) _Pragma("unroll") for (int n = 0; n < 2; ++n) _Pragma("unroll") for (int k = 0; k < 2; ++k) \
;         acc[ai][bj][m][n] = __builtin_amdgcn_mfma_f32_16x16x32_bf16(Bt[n][k], At[m][k], acc[ai][bj][m][n], 0, 0, 0); __builtin_amdgcn_s_setprio(0); } while (0)
; #define PG8_WAIT_V(n) asm volatile("s_waitcnt vmcnt(" #n ")" ::: "memory")
; #define PG8_WAIT_L(n) asm volatile("s_waitcnt lgkmcnt(" #n ")" ::: "memory")
; #define PG8_BAR __builtin_amdgcn_s_barrier()
; #define PG8_SCHED __builtin_amdgcn_sched_barrier(0)
; template <class Epi, class Sched, bool ALIGN_EPI = false, bool SP2 = false, bool ATILED = false>
; __device__ __forceinline__ void gemm_phase(PG8_LAS unsigned char* lds, const Gemm g, const Sched& S, const Epi& E) {
;     ...
;             PG8_WAIT_V(8); PG8_WAIT_L(0); PG8_BAR; PG8_MMA(1, 0, At, B0); PG8_MMA(1, 1, At, B1); PG8_BAR; PG8_SCHED;
;             PG8_LDB(B0, 1, 0); PG8_LDB(B1, 1, 1); PG8_SCHED; PG8_LDA(At, 1, 0); PG8_STAGE(PG8_SA(0, 1), a2 + hstepA, voffA);
;             PG8_WAIT_V(8); PG8_WAIT_L(0); PG8_BAR; PG8_MMA(0, 0, At, B0); PG8_MMA(0, 1, At, B1); PG8_BAR; PG8_SCHED;
	s_waitcnt lgkmcnt(0)
	v_mfma_f32_16x16x32_bf16 v[60:63], v[156:159], v[188:191], v[60:63]
	v_mfma_f32_16x16x32_bf16 v[56:59], v[164:167], v[188:191], v[56:59]
	v_mfma_f32_16x16x32_bf16 v[48:51], v[156:159], v[208:211], v[48:51]
	v_mfma_f32_16x16x32_bf16 v[40:43], v[164:167], v[208:211], v[40:43]
	v_mfma_f32_16x16x32_bf16 v[32:35], v[156:159], v[216:219], v[32:35]
	v_mfma_f32_16x16x32_bf16 v[24:27], v[164:167], v[216:219], v[24:27]
	v_mfma_f32_16x16x32_bf16 v[16:19], v[156:159], v[224:227], v[16:19]
	v_mfma_f32_16x16x32_bf16 v[8:11], v[164:167], v[224:227], v[8:11]
	v_mfma_f32_16x16x32_bf16 v[60:63], v[160:163], v[192:195], v[60:63]
	v_mfma_f32_16x16x32_bf16 v[56:59], v[168:171], v[192:195], v[56:59]
	v_mfma_f32_16x16x32_bf16 v[48:51], v[160:163], v[212:215], v[48:51]
	v_mfma_f32_16x16x32_bf16 v[40:43], v[168:171], v[212:215], v[40:43]
	v_mfma_f32_16x16x32_bf16 v[32:35], v[160:163], v[220:223], v[32:35]
	v_mfma_f32_16x16x32_bf16 v[24:27], v[168:171], v[220:223], v[24:27]
	v_mfma_f32_16x16x32_bf16 v[16:19], v[160:163], v[228:231], v[16:19]
	v_mfma_f32_16x16x32_bf16 v[8:11], v[168:171], v[228:231], v[8:11]
	v_mfma_f32_16x16x32_bf16 v[52:55], v[172:175], v[188:191], v[52:55]
	v_mfma_f32_16x16x32_bf16 v[44:47], v[180:183], v[188:191], v[44:47]
	v_mfma_f32_16x16x32_bf16 v[36:39], v[172:175], v[208:211], v[36:39]
	v_mfma_f32_16x16x32_bf16 v[28:31], v[180:183], v[208:211], v[28:31]
	v_mfma_f32_16x16x32_bf16 v[20:23], v[172:175], v[216:219], v[20:23]
	v_mfma_f32_16x16x32_bf16 v[12:15], v[180:183], v[216:219], v[12:15]
	v_mfma_f32_16x16x32_bf16 v[4:7], v[172:175], v[224:227], v[4:7]
	v_mfma_f32_16x16x32_bf16 v[0:3], v[180:183], v[224:227], v[0:3]
	v_mfma_f32_16x16x32_bf16 v[52:55], v[176:179], v[192:195], v[52:55]
	v_mfma_f32_16x16x32_bf16 v[44:47], v[184:187], v[192:195], v[44:47]
	v_mfma_f32_16x16x32_bf16 v[36:39], v[176:179], v[212:215], v[36:39]
	v_mfma_f32_16x16x32_bf16 v[28:31], v[184:187], v[212:215], v[28:31]
	v_mfma_f32_16x16x32_bf16 v[20:23], v[176:179], v[220:223], v[20:23]
	v_mfma_f32_16x16x32_bf16 v[12:15], v[184:187], v[220:223], v[12:15]
	v_mfma_f32_16x16x32_bf16 v[4:7], v[176:179], v[228:231], v[4:7]
	v_mfma_f32_16x16x32_bf16 v[0:3], v[184:187], v[228:231], v[0:3]
	s_barrier
	s_add_i32 s84, 0, 0x18000
	v_add_u32_e32 v136, s84, v200
	s_add_i32 s85, 0, 0x1c000
	ds_read_b128 v[156:159], v136
	ds_read_b128 v[160:163], v136 offset:1024
	ds_read_b128 v[164:167], v136 offset:2048
	ds_read_b128 v[168:171], v136 offset:3072
	v_add_u32_e32 v136, s85, v200
	ds_read_b128 v[172:175], v136
	ds_read_b128 v[176:179], v136 offset:1024
	ds_read_b128 v[180:183], v136 offset:2048
	ds_read_b128 v[184:187], v136 offset:3072
	s_add_u32 s68, s68, 0x40000
	s_addc_u32 s69, s69, 0
	s_mov_b32 m0, s73
	v_lshl_add_u64 v[238:239], s[68:69], 0, v[128:129]
	ds_read_b128 v[188:191], v203 offset:32768
	ds_read_b128 v[192:195], v203 offset:33792
	ds_read_b128 v[208:211], v203 offset:34816
	ds_read_b128 v[212:215], v203 offset:35840
	ds_read_b128 v[216:219], v203 offset:36864
	ds_read_b128 v[220:223], v203 offset:37888
	ds_read_b128 v[224:227], v203 offset:38912
	ds_read_b128 v[228:231], v203 offset:39936
	global_load_lds_dwordx4 v[238:239], off
	v_lshl_add_u64 v[238:239], s[68:69], 0, v[132:133]
	s_mov_b32 m0, s74
	s_nop 0
	global_load_lds_dwordx4 v[238:239], off
	s_waitcnt vmcnt(8)
	s_waitcnt lgkmcnt(0)
	s_barrier
	s_waitcnt lgkmcnt(0)
	v_mfma_f32_16x16x32_bf16 v[124:127], v[156:159], v[188:191], v[124:127]
	v_mfma_f32_16x16x32_bf16 v[120:123], v[164:167], v[188:191], v[120:123]
	v_mfma_f32_16x16x32_bf16 v[116:119], v[156:159], v[208:211], v[116:119]
	v_mfma_f32_16x16x32_bf16 v[112:115], v[164:167], v[208:211], v[112:115]
	v_mfma_f32_16x16x32_bf16 v[96:99], v[156:159], v[216:219], v[96:99]
	v_mfma_f32_16x16x32_bf16 v[88:91], v[164:167], v[216:219], v[88:91]
	v_mfma_f32_16x16x32_bf16 v[80:83], v[156:159], v[224:227], v[80:83]
	v_mfma_f32_16x16x32_bf16 v[72:75], v[164:167], v[224:227], v[72:75]
	v_mfma_f32_16x16x32_bf16 v[124:127], v[160:163], v[192:195], v[124:127]
	v_mfma_f32_16x16x32_bf16 v[120:123], v[168:171], v[192:195], v[120:123]
	v_mfma_f32_16x16x32_bf16 v[116:119], v[160:163], v[212:215], v[116:119]
	v_mfma_f32_16x16x32_bf16 v[112:115], v[168:171], v[212:215], v[112:115]
	v_mfma_f32_16x16x32_bf16 v[96:99], v[160:163], v[220:223], v[96:99]
	v_mfma_f32_16x16x32_bf16 v[88:91], v[168:171], v[220:223], v[88:91]
	v_mfma_f32_16x16x32_bf16 v[80:83], v[160:163], v[228:231], v[80:83]
	v_mfma_f32_16x16x32_bf16 v[72:75], v[168:171], v[228:231], v[72:75]
	v_mfma_f32_16x16x32_bf16 v[108:111], v[172:175], v[188:191], v[108:111]
	v_mfma_f32_16x16x32_bf16 v[104:107], v[180:183], v[188:191], v[104:107]
	v_mfma_f32_16x16x32_bf16 v[100:103], v[172:175], v[208:211], v[100:103]
	v_mfma_f32_16x16x32_bf16 v[92:95], v[180:183], v[208:211], v[92:95]
	v_mfma_f32_16x16x32_bf16 v[84:87], v[172:175], v[216:219], v[84:87]
	v_mfma_f32_16x16x32_bf16 v[76:79], v[180:183], v[216:219], v[76:79]
	v_mfma_f32_16x16x32_bf16 v[68:71], v[172:175], v[224:227], v[68:71]
	v_mfma_f32_16x16x32_bf16 v[64:67], v[180:183], v[224:227], v[64:67]
	v_mfma_f32_16x16x32_bf16 v[108:111], v[176:179], v[192:195], v[108:111]
	v_mfma_f32_16x16x32_bf16 v[104:107], v[184:187], v[192:195], v[104:107]
	v_mfma_f32_16x16x32_bf16 v[100:103], v[176:179], v[212:215], v[100:103]
	v_mfma_f32_16x16x32_bf16 v[92:95], v[184:187], v[212:215], v[92:95]
	v_mfma_f32_16x16x32_bf16 v[84:87], v[176:179], v[220:223], v[84:87]
	v_mfma_f32_16x16x32_bf16 v[76:79], v[184:187], v[220:223], v[76:79]
	v_mfma_f32_16x16x32_bf16 v[68:71], v[176:179], v[228:231], v[68:71]
	v_mfma_f32_16x16x32_bf16 v[64:67], v[184:187], v[228:231], v[64:67]
	s_barrier
; #define PG8_STAGE(bufoff, gbase, voff) do { _Pragma("unroll") for (int _i = 0; _i < 2; ++_i) \
;         __builtin_amdgcn_global_load_lds((const unsigned*)((const char*)(gbase) + (voff)[_i]), (PG8_LAS unsigned*)(lds + (bufoff) + ldsw + _i * 8192), 16, 0, 0); } while (0)
; #define PG8_LDA(dst, b, h) do { _Pragma("unroll") for (int m = 0; m < 4; ++m) _Pragma("unroll") for (int k = 0; k < 2; ++k) dst[m][k] = *(const PG8_LAS bf16x8*)(lds + PG8_SA(b, h) + aoff + m * 2048 + k * 1024); } while (0)
; #define PG8_MMA(ai, bj, At, Bt) do { __builtin_amdgcn_s_setprio(1); _Pragma("unroll") for (int m = 0; m < 4; ++m) _Pragma("unroll") for (int n = 0; n < 2; ++n) _Pragma("unroll") for (int k = 0; k < 2; ++k) \
;         acc[ai][bj][m][n] = __builtin_amdgcn_mfma_f32_16x16x32_bf16(Bt[n][k], At[m][k], acc[ai][bj][m][n], 0, 0, 0); __builtin_amdgcn_s_setprio(0); } while (0)
; #define PG8_WAIT_V(n) asm volatile("s_waitcnt vmcnt(" #n ")" ::: "memory")
; #define PG8_WAIT_L(n) asm volatile("s_waitcnt lgkmcnt(" #n ")" ::: "memory")
; #define PG8_BAR __builtin_amdgcn_s_barrier()
; #define PG8_SCHED __builtin_amdgcn_sched_barrier(0)
; template <class Epi, class Sched, bool ALIGN_EPI = false, bool SP2 = false, bool ATILED = false>
; __device__ __forceinline__ void gemm_phase(PG8_LAS unsigned char* lds, const Gemm g, const Sched& S, const Epi& E) {
;     ...
;         for (int t = 0; t < nt; t += 2) {
;             const bool last = (t == nt - 2);
;             const char* a1 = cA + (size_t)(t + 1) * kstepA;
;             const char* a2 = last ? nA : cA + (size_t)(t + 2) * kstepA; const char* b2 = last ? nB : cB + (size_t)(t + 2) * kstep;
;             const char* a3 = a2 + kstepA; const char* b3 = b2 + kstep;
;             if (last && has_next) S.a_ready(nxt);
;     ...
;             PG8_LDA(At, 1, 1); PG8_STAGE(PG8_SB(1, 0), b3, voffB); PG8_STAGE(PG8_SB(1, 1), b3 + hstep, voffB); PG8_STAGE(PG8_SA(1, 0), a3, voffA);
;             PG8_WAIT_V(8); PG8_WAIT_L(0); PG8_BAR; PG8_MMA(1, 0, At, B0); PG8_MMA(1, 1, At, B1); PG8_BAR; PG8_SCHED;
	s_add_i32 s68, s84, s70
	v_lshl_add_u64 v[196:197], v[196:197], 0, s[38:39]
	s_mov_b32 m0, s68
	ds_read_b128 v[188:191], v203 offset:49152
	ds_read_b128 v[192:195], v203 offset:50176
	ds_read_b128 v[208:211], v203 offset:51200
	ds_read_b128 v[212:215], v203 offset:52224
	ds_read_b128 v[216:219], v203 offset:53248
	ds_read_b128 v[220:223], v203 offset:54272
	ds_read_b128 v[224:227], v203 offset:55296
	ds_read_b128 v[228:231], v203 offset:56320
	global_load_lds_dwordx4 v[196:197], off
	s_add_i32 m0, s68, 0x2000
	s_add_u32 s66, s66, 0x40080
	v_lshl_add_u64 v[196:197], v[232:233], 0, s[38:39]
	s_addc_u32 s67, s67, 0
	s_add_i32 s68, s85, s70
	global_load_lds_dwordx4 v[196:197], off
	v_lshl_add_u64 v[196:197], s[66:67], 0, v[130:131]
	s_mov_b32 m0, s68
	s_nop 0
	global_load_lds_dwordx4 v[196:197], off
	v_lshl_add_u64 v[196:197], s[66:67], 0, v[134:135]
	s_add_i32 m0, s68, 0x2000
	s_nop 0
	global_load_lds_dwordx4 v[196:197], off
	v_lshl_add_u64 v[196:197], v[234:235], 0, s[38:39]
	s_mov_b32 m0, s77
	s_nop 0
	global_load_lds_dwordx4 v[196:197], off
	v_lshl_add_u64 v[196:197], v[236:237], 0, s[38:39]
	s_mov_b32 m0, s78
	s_nop 0
	global_load_lds_dwordx4 v[196:197], off
	s_waitcnt vmcnt(8)
	s_waitcnt lgkmcnt(0)
	s_barrier
	s_waitcnt lgkmcnt(0)
	v_mfma_f32_16x16x32_bf16 v[60:63], v[156:159], v[188:191], v[60:63]
	v_mfma_f32_16x16x32_bf16 v[56:59], v[164:167], v[188:191], v[56:59]
	v_mfma_f32_16x16x32_bf16 v[48:51], v[156:159], v[208:211], v[48:51]
	v_mfma_f32_16x16x32_bf16 v[40:43], v[164:167], v[208:211], v[40:43]
	v_mfma_f32_16x16x32_bf16 v[32:35], v[156:159], v[216:219], v[32:35]
	v_mfma_f32_16x16x32_bf16 v[24:27], v[164:167], v[216:219], v[24:27]
	v_mfma_f32_16x16x32_bf16 v[16:19], v[156:159], v[224:227], v[16:19]
	v_mfma_f32_16x16x32_bf16 v[8:11], v[164:167], v[224:227], v[8:11]
	v_mfma_f32_16x16x32_bf16 v[60:63], v[160:163], v[192:195], v[60:63]
	v_mfma_f32_16x16x32_bf16 v[56:59], v[168:171], v[192:195], v[56:59]
	v_mfma_f32_16x16x32_bf16 v[48:51], v[160:163], v[212:215], v[48:51]
	v_mfma_f32_16x16x32_bf16 v[40:43], v[168:171], v[212:215], v[40:43]
	v_mfma_f32_16x16x32_bf16 v[32:35], v[160:163], v[220:223], v[32:35]
	v_mfma_f32_16x16x32_bf16 v[24:27], v[168:171], v[220:223], v[24:27]
	v_mfma_f32_16x16x32_bf16 v[16:19], v[160:163], v[228:231], v[16:19]
	v_mfma_f32_16x16x32_bf16 v[8:11], v[168:171], v[228:231], v[8:11]
	v_mfma_f32_16x16x32_bf16 v[52:55], v[172:175], v[188:191], v[52:55]
	v_mfma_f32_16x16x32_bf16 v[44:47], v[180:183], v[188:191], v[44:47]
	v_mfma_f32_16x16x32_bf16 v[36:39], v[172:175], v[208:211], v[36:39]
	v_mfma_f32_16x16x32_bf16 v[28:31], v[180:183], v[208:211], v[28:31]
	v_mfma_f32_16x16x32_bf16 v[20:23], v[172:175], v[216:219], v[20:23]
	v_mfma_f32_16x16x32_bf16 v[12:15], v[180:183], v[216:219], v[12:15]
	v_mfma_f32_16x16x32_bf16 v[4:7], v[172:175], v[224:227], v[4:7]
	v_mfma_f32_16x16x32_bf16 v[0:3], v[180:183], v[224:227], v[0:3]
	v_mfma_f32_16x16x32_bf16 v[52:55], v[176:179], v[192:195], v[52:55]
	v_mfma_f32_16x16x32_bf16 v[44:47], v[184:187], v[192:195], v[44:47]
	v_mfma_f32_16x16x32_bf16 v[36:39], v[176:179], v[212:215], v[36:39]
	v_mfma_f32_16x16x32_bf16 v[28:31], v[184:187], v[212:215], v[28:31]
	v_mfma_f32_16x16x32_bf16 v[20:23], v[176:179], v[220:223], v[20:23]
	v_mfma_f32_16x16x32_bf16 v[12:15], v[184:187], v[220:223], v[12:15]
	v_mfma_f32_16x16x32_bf16 v[4:7], v[176:179], v[228:231], v[4:7]
	v_mfma_f32_16x16x32_bf16 v[0:3], v[184:187], v[228:231], v[0:3]
	s_barrier
	s_add_i32 s83, s83, 2
	s_add_u32 s64, s64, 0x100
	s_addc_u32 s65, s65, 0
	s_add_u32 s49, s49, 0x100
	s_addc_u32 s63, s63, 0
	s_cmp_gt_u32 s83, 13
	s_cbranch_scc0 .LBB0_300
	s_and_b64 vcc, exec, s[40:41]
	s_cbranch_vccz .LBB0_303
	s_barrier

; #define LAS __attribute__((address_space(3)))
; __device__ __forceinline__ void retention_unit(LAS unsigned char* lds, const Ptrs& P, int b, int h, int tid) {
;     ...
;     for (int i = tid; i < 128 * S72 * 2 / 16; i += NTHREADS) ((LAS v4u*)St)[i] = (v4u){0u, 0u, 0u, 0u};
;     f32x4 st[4];
; #pragma unroll
;     for (int i = 0; i < 4; ++i) st[i] = (f32x4){0.f, 0.f, 0.f, 0.f};
;     const int lrow = tid >> 3, lseg = tid & 7, vrow0 = tid >> 4, vseg = tid & 15;
;     const size_t tok0 = (size_t)b * SEQ;
;     const bf16* gq = P.Q + (tok0 + lrow) * 256 + h * 64 + lseg * 8; const bf16* gk = P.K + (tok0 + lrow) * 256 + h * 64 + lseg * 8;
;     const bf16* gv = P.V + (tok0 + vrow0) * 512 + h * 128 + vseg * 8;
;     const bf16* gsl = P.SG + (tok0 + fr) * 512 + h * 128 + 16 * w + 4 * fq;
;     bf16* gol = P.RS + (tok0 + fr) * 1024 + h * 128 + 16 * w + 4 * fq;
;     v4u rq = __builtin_nontemporal_load((const v4u*)gq), rk = __builtin_nontemporal_load((const v4u*)gk), rv0 = __builtin_nontemporal_load((const v4u*)gv), rv1 = __builtin_nontemporal_load((const v4u*)(gv + 32 * 512));
;     const float dkey = ex2((float)(63 - lrow) * lg), dch = ex2(64.f * lg);
;     const f32x4 gng4 = *(const f32x4*)(P.gng + h * 128 + 16 * w + 4 * fq);
;     const int it3 = w >> 1;
;     float dqv[4]; f32x4 decv[2];
; #pragma unroll
;     for (int it = 0; it < 4; ++it) dqv[it] = ex2((float)(16 * it + fr + 1) * lg);
; #pragma unroll
;     for (int j2 = 0; j2 < 2; ++j2)
; #pragma unroll
;         for (int r = 0; r < 4; ++r) decv[j2][r] = ex2(__builtin_fabsf((float)((16 * it3 + fr) - (16 * ((w & 1) * 2 + j2) + 4 * fq + r))) * lg);
;     f32x4 op[4]; v2u sgr[4];
; #pragma unroll
;     for (int it = 0; it < 4; ++it) { op[it] = (f32x4){0.f, 0.f, 0.f, 0.f}; sgr[it] = (v2u){0u, 0u}; }
;     for (int n = 0; n <= 32; ++n) {
;         LAS unsigned char* bufc = lds + (n & 1) * RSET;
;         LAS bf16* Qs = (LAS bf16*)(bufc + ROFF_Q); LAS bf16* Ks = (LAS bf16*)(bufc + ROFF_K); LAS bf16* K2s = (LAS bf16*)(bufc + ROFF_K2); LAS bf16* Vs = (LAS bf16*)(bufc + ROFF_V);
;         if (n < 32) {
;             *(LAS v4u*)(Qs + lrow * S72 + lseg * 8) = rq; *(LAS v4u*)(Ks + lrow * S72 + lseg * 8) = rk;
;             v4u k2;
; #pragma unroll
;             for (int t = 0; t < 4; ++t) k2[t] = pk2(bflo(rk[t]) * dkey, bfhi(rk[t]) * dkey);
;             *(LAS v4u*)(K2s + lrow * S72 + lseg * 8) = k2;
.LBB0_655:
	v_add_u32_e32 v1, 0x200, v1
	v_cmp_lt_u32_e32 vcc, s7, v1
	ds_write_b128 v0, v[180:183]
	s_or_b64 s[16:17], vcc, s[16:17]
	v_add_u32_e32 v0, 0x2000, v0
	s_andn2_b64 exec, exec, s[16:17]
	s_cbranch_execnz .LBB0_655
	s_or_b64 exec, exec, s[16:17]
	s_ashr_i32 s18, s86, 2
	s_ashr_i32 s19, s18, 31
	s_lshl_b64 s[16:17], s[18:19], 11
	v_mov_b32_e32 v1, s17
	v_or_b32_e32 v0, s16, v145
	v_lshlrev_b64 v[0:1], 9, v[0:1]
	v_lshl_add_u64 v[2:3], s[36:37], 0, v[0:1]
	s_lshl_b32 s4, s88, 7
	v_lshl_add_u64 v[0:1], s[48:49], 0, v[0:1]
	v_lshl_add_u64 v[2:3], v[2:3], 0, s[4:5]
	v_lshl_add_u64 v[0:1], v[0:1], 0, s[4:5]
	s_waitcnt vmcnt(2)
	v_lshl_add_u64 v[6:7], v[2:3], 0, v[72:73]
	v_lshl_add_u64 v[4:5], v[0:1], 0, v[72:73]
	v_mov_b32_e32 v1, s17
	v_or_b32_e32 v0, s16, v80
	global_load_dwordx4 v[8:11], v[6:7], off nt
	global_load_dwordx4 v[12:15], v[4:5], off nt
	v_lshlrev_b64 v[0:1], 10, v[0:1]
	s_lshl_b32 s90, s88, 8
	s_mov_b32 s91, s5
	v_lshl_add_u64 v[0:1], s[42:43], 0, v[0:1]
	v_lshl_add_u64 v[0:1], v[0:1], 0, s[90:91]
	v_lshl_add_u64 v[28:29], v[0:1], 0, v[84:85]
	v_add_co_u32_e32 v0, vcc, s21, v28
	s_and_b32 s93, s85, 3
	s_nop 0
	v_addc_co_u32_e32 v1, vcc, 0, v29, vcc
	global_load_dwordx4 v[16:19], v[28:29], off nt
	global_load_dwordx4 v[20:23], v[0:1], off nt
	s_lshr_b32 s87, s92, 6
	s_waitcnt lgkmcnt(0)
	v_mul_f32_e32 v0, s89, v147
	s_lshl_b32 s94, s88, 9
	s_lshl_b32 s91, s93, 7
	s_lshl_b32 s90, s93, 8
	s_lshl_b32 s88, s87, 4
	v_exp_f32_e32 v102, v0
	s_add_u32 s93, s50, s94
	s_addc_u32 s95, s51, 0
	s_and_b32 s94, s92, 0xffffffc0
	s_add_u32 s94, s93, s94
	s_addc_u32 s95, s95, 0
	global_load_dwordx4 v[0:3], v127, s[94:95]
	v_mov_b32_e32 v103, v102
	s_lshr_b32 s93, s92, 3
	s_lshr_b32 s92, s92, 5
	s_and_b32 s93, s93, 0x1ffffff0
	s_and_b32 s92, s92, 2
	s_waitcnt vmcnt(5)
	v_or_b32_e32 v24, s93, v144
	s_lshl_b32 s93, s92, 4
	v_or_b32_e32 v60, s93, v144
	v_mul_lo_u32 v62, v24, s20
	v_add_u32_e32 v176, v166, v62
	v_or_b32_e32 v25, s93, v146
	v_add_u32_e32 v26, v24, v152
	v_add_u32_e32 v27, v24, v153
	v_add_u32_e32 v30, v24, v154
	v_sub_u32_e32 v31, v24, v146
	v_sub_u32_e32 v24, v24, v25
	v_subrev_u32_e32 v25, s93, v26
	v_subrev_u32_e32 v32, s93, v27
	v_subrev_u32_e32 v33, s93, v30
	v_cvt_f32_i32_e32 v24, v24
	v_cvt_f32_i32_e32 v25, v25
	v_cvt_f32_i32_e32 v32, v32
	v_cvt_f32_i32_e32 v33, v33
	v_mul_f32_e64 v24, s89, |v24|
	v_mul_f32_e64 v25, s89, |v25|
	v_mul_f32_e64 v32, s89, |v32|
	v_mul_f32_e64 v33, s89, |v33|
	v_exp_f32_e32 v98, v24
	v_add_co_u32_e32 v24, vcc, s21, v6
	v_exp_f32_e32 v99, v25
	v_exp_f32_e32 v100, v32
	v_exp_f32_e32 v101, v33
	v_addc_co_u32_e32 v25, vcc, 0, v7, vcc
	s_xor_b32 s94, s93, -16
	v_add_u32_e32 v40, v156, v62
	s_lshl_b32 s93, s92, 5
	s_or_b32 s92, s92, 1
	v_add_u32_e32 v26, s94, v26
	v_add_u32_e32 v27, s94, v27
	v_add_u32_e32 v177, s93, v40
	v_lshl_or_b32 v61, s92, 4, v144
	v_cvt_f32_i32_e32 v26, v26
	v_cvt_f32_i32_e32 v27, v27
	v_add_co_u32_e32 v4, vcc, s21, v4
	s_waitcnt vmcnt(4)
	ds_write_b128 v164, v[8:11]
	s_waitcnt vmcnt(3)
	ds_write_b128 v164, v[12:15] offset:9216
	v_lshlrev_b32_e32 v8, 16, v12
	v_and_b32_e32 v9, 0xffff0000, v12
	v_lshlrev_b32_e32 v10, 16, v13
	v_and_b32_e32 v11, 0xffff0000, v13
	v_pk_mul_f32 v[8:9], v[102:103], v[8:9] op_sel_hi:[0,1]
	v_pk_mul_f32 v[10:11], v[102:103], v[10:11] op_sel_hi:[0,1]
	v_cvt_pk_bf16_f32 v8, v8, v9
	v_cvt_pk_bf16_f32 v9, v10, v11
	v_lshlrev_b32_e32 v10, 16, v14
	v_and_b32_e32 v11, 0xffff0000, v14
	v_lshlrev_b32_e32 v12, 16, v15
	v_and_b32_e32 v13, 0xffff0000, v15
	v_pk_mul_f32 v[10:11], v[102:103], v[10:11] op_sel_hi:[0,1]
	v_pk_mul_f32 v[12:13], v[102:103], v[12:13] op_sel_hi:[0,1]
	v_cvt_pk_bf16_f32 v10, v10, v11
	v_cvt_pk_bf16_f32 v11, v12, v13
	ds_write_b128 v164, v[8:11] offset:18432
	s_waitcnt vmcnt(2)
	ds_write_b128 v165, v[16:19] offset:27648
	s_waitcnt vmcnt(1)
	ds_write_b128 v165, v[20:23] offset:36864
	s_waitcnt lgkmcnt(0)
	s_barrier
	v_mad_u32_u24 v16, v60, s20, v166
	ds_read_b128 v[8:11], v16 offset:9216
	ds_read_b128 v[12:15], v176
	ds_read_b128 v[16:19], v16 offset:9280
	v_or_b32_e32 v20, s88, v144
	v_mul_lo_u32 v48, v20, s20
	ds_read_b128 v[20:23], v176 offset:64
	s_waitcnt lgkmcnt(2)
	v_mfma_f32_16x16x32_bf16 v[8:11], v[8:11], v[12:15], 0
	v_mul_f32_e64 v26, s89, |v26|
	v_mul_f32_e64 v27, s89, |v27|
	v_exp_f32_e32 v93, v26
	s_waitcnt lgkmcnt(0)
	v_mfma_f32_16x16x32_bf16 v[6:9], v[16:19], v[20:23], v[8:11]
	v_exp_f32_e32 v94, v27
	v_addc_co_u32_e32 v5, vcc, 0, v5, vcc
	s_nop 0
	v_mad_u32_u24 v10, v61, s20, v166
	v_add_u32_e32 v31, s94, v31
	s_nop 2
	v_pk_mul_f32 v[8:9], v[100:101], v[8:9]
	v_pk_mul_f32 v[6:7], v[98:99], v[6:7]
	v_add_u32_e32 v30, s94, v30
	v_cvt_pk_bf16_f32 v6, v6, v7
	v_cvt_pk_bf16_f32 v7, v8, v9
	ds_write_b64 v177, v[6:7]
	ds_read_b128 v[6:9], v10 offset:9216
	global_load_dwordx4 v[36:39], v[24:25], off nt
	s_nop 0
	global_load_dwordx4 v[24:27], v[4:5], off nt
	ds_read_b128 v[16:19], v10 offset:9280
	v_cvt_f32_i32_e32 v31, v31
	v_cvt_f32_i32_e32 v30, v30
	s_waitcnt lgkmcnt(1)
	v_mfma_f32_16x16x32_bf16 v[4:7], v[6:9], v[12:15], 0
	v_mul_f32_e64 v31, s89, |v31|
	v_mul_f32_e64 v30, s89, |v30|
	v_exp_f32_e32 v92, v31
	v_exp_f32_e32 v95, v30
	s_waitcnt lgkmcnt(0)
	v_mfma_f32_16x16x32_bf16 v[4:7], v[16:19], v[20:23], v[4:7]
	v_add_co_u32_e32 v10, vcc, s56, v28
	s_lshl_b32 s92, s92, 5
	s_nop 0
	v_addc_co_u32_e32 v11, vcc, 0, v29, vcc
	v_add_co_u32_e32 v8, vcc, s57, v28
	s_nop 2
	v_pk_mul_f32 v[6:7], v[94:95], v[6:7]
	v_pk_mul_f32 v[4:5], v[92:93], v[4:5]
	v_add_u32_e32 v142, s92, v40
	v_cvt_pk_bf16_f32 v4, v4, v5
	v_cvt_pk_bf16_f32 v5, v6, v7
	v_addc_co_u32_e32 v9, vcc, 0, v29, vcc
	global_load_dwordx4 v[28:31], v[10:11], off nt
	global_load_dwordx4 v[32:35], v[8:9], off nt
	ds_write_b64 v142, v[4:5]
	v_add_u32_e32 v137, v161, v48
	s_waitcnt lgkmcnt(0)
	s_barrier
; __device__ __forceinline__ void retention_unit(LAS unsigned char* lds, const Ptrs& P, int b, int h, int tid) {
;     ...
;         if (n < 32) {
; #pragma unroll
;             for (int j2 = 0; j2 < 2; ++j2) {
;                 const int jt = (w & 1) * 2 + j2; f32x4 a4 = (f32x4){0.f, 0.f, 0.f, 0.f};
; #pragma unroll
;                 for (int ks = 0; ks < 2; ++ks) {
;                     const bf16x8 qf = *(const LAS bf16x8*)(Qs + (16 * it3 + fr) * S72 + 32 * ks + 8 * fq), kf = *(const LAS bf16x8*)(Ks + (16 * jt + fr) * S72 + 32 * ks + 8 * fq);
;                     a4 = mfma16(kf, qf, a4); }
;                 a4 = a4 * decv[j2];
;                 v2u pw; pw.x = pk2(a4[0], a4[1]); pw.y = pk2(a4[2], a4[3]);
;                 *(LAS v2u*)(Ss + (16 * it3 + fr) * S72 + 16 * jt + 4 * fq) = pw;
;             }
;         }
;         LBAR();
;         if (n >= 1) {
; #pragma unroll
;             for (int it = 0; it < 4; ++it) { const int i = 16 * it + fr; const float mean = stat[i * 2], rstd = stat[i * 2 + 1]; const v2u sg = sgr[it];
;                 const f32x4 y = (op[it] - mean) * rstd * gng4 * (f32x4){bflo(sg.x), bfhi(sg.x), bflo(sg.y), bfhi(sg.y)};
;                 v2u pw; pw.x = pk2(y[0], y[1]); pw.y = pk2(y[2], y[3]);
;                 *(v2u*)(gol + ((size_t)(n - 1) * 64 + 16 * it) * 1024) = pw; }
;         }
;         if (n < 32) {
;             f32x4 o[4]; bf16x8 bst[2], bv[2];
; #pragma unroll
;             for (int ks = 0; ks < 2; ++ks) { bst[ks] = *(const LAS bf16x8*)(St + (16 * w + fr) * S72 + 32 * ks + 8 * fq); bv[ks] = tr_frag(bufc + ROFF_V, S144 * 2, w, ks, fq, fr); }
; #pragma unroll
;             for (int it = 0; it < 4; ++it) { o[it] = (f32x4){0.f, 0.f, 0.f, 0.f};
; #pragma unroll
;                 for (int ks = 0; ks < 2; ++ks) { const bf16x8 qf = *(const LAS bf16x8*)(Qs + (16 * it + fr) * S72 + 32 * ks + 8 * fq); o[it] = mfma16(bst[ks], qf, o[it]); }
;                 o[it] = o[it] * dqv[it];
; #pragma unroll
;                 for (int ks = 0; ks < 2; ++ks) { const bf16x8 sf = *(const LAS bf16x8*)(Ss + (16 * it + fr) * S72 + 32 * ks + 8 * fq); o[it] = mfma16(bv[ks], sf, o[it]); }
;             }
; #pragma unroll
;             for (int dt = 0; dt < 4; ++dt) { st[dt] = st[dt] * dch;
; #pragma unroll
;                 for (int ks = 0; ks < 2; ++ks) { const bf16x8 kf = tr_frag(bufc + ROFF_K2, S72 * 2, dt, ks, fq, fr); st[dt] = mfma16(kf, bv[ks], st[dt]); }
	ds_read_b128 v[4:7], v137
	ds_read_b128 v[8:11], v137 offset:64
	ds_read_b128 v[12:15], v128
	v_mul_f32_e32 v16, s89, v148
	v_exp_f32_e32 v90, v16
	ds_read_b128 v[16:19], v128 offset:64
	s_waitcnt lgkmcnt(1)
	v_mfma_f32_16x16x32_bf16 v[12:15], v[4:7], v[12:15], 0
	s_lshl_b32 s87, s87, 5
	v_add3_u32 v40, v167, s87, v168
	ds_read_b64_tr_b16 v[52:53], v40 offset:27648
	ds_read_b64_tr_b16 v[54:55], v40 offset:28800
	ds_read_b64_tr_b16 v[58:59], v40 offset:38016
	s_waitcnt lgkmcnt(3)
	v_mfma_f32_16x16x32_bf16 v[12:15], v[8:11], v[16:19], v[12:15]
	ds_read_b128 v[16:19], v129
	ds_read_b64_tr_b16 v[56:57], v40 offset:36864
	v_mov_b32_e32 v91, v90
	ds_read_b128 v[20:23], v129 offset:64
	v_add_u32_e32 v132, v157, v48
	s_nop 2
	v_pk_mul_f32 v[14:15], v[90:91], v[14:15] op_sel_hi:[0,1]
	v_pk_mul_f32 v[12:13], v[90:91], v[12:13] op_sel_hi:[0,1]
	v_mul_f32_e32 v75, s89, v151
	v_exp_f32_e32 v88, v75
	s_waitcnt lgkmcnt(2)
	v_mfma_f32_16x16x32_bf16 v[12:15], v[52:55], v[16:19], v[12:15]
	s_lshl_b64 s[92:93], s[18:19], 20
	v_add_u32_e32 v133, s87, v172
	v_mov_b32_e32 v89, v88
	s_waitcnt lgkmcnt(0)
	v_mfma_f32_16x16x32_bf16 v[40:43], v[56:59], v[20:23], v[12:15]
	s_nop 2
	ds_read_b128 v[12:15], v128 offset:2304
	ds_read_b128 v[16:19], v128 offset:2368
	v_mul_f32_e32 v20, s89, v149
	v_exp_f32_e32 v78, v20
	s_waitcnt lgkmcnt(1)
	v_mfma_f32_16x16x32_bf16 v[12:15], v[4:7], v[12:15], 0
	ds_read_b128 v[20:23], v129 offset:2368
	v_mov_b32_e32 v79, v78
	s_or_b32 s92, s92, s91
	s_waitcnt lgkmcnt(1)
	v_mfma_f32_16x16x32_bf16 v[12:15], v[8:11], v[16:19], v[12:15]
	ds_read_b128 v[16:19], v129 offset:2304
	v_add_u32_e32 v134, s87, v173
	v_add_u32_e32 v135, s87, v174
	v_mul_u32_u24_e32 v179, 0x90, v60
	v_mul_u32_u24_e32 v178, 0x90, v61
	s_nop 2
	v_pk_mul_f32 v[14:15], v[78:79], v[14:15] op_sel_hi:[0,1]
	v_pk_mul_f32 v[12:13], v[78:79], v[12:13] op_sel_hi:[0,1]
	v_mov_b32_e32 v108, v90
	v_mov_b32_e32 v109, v90
	s_waitcnt lgkmcnt(0)
	v_mfma_f32_16x16x32_bf16 v[12:15], v[52:55], v[16:19], v[12:15]
	ds_read_b128 v[16:19], v128 offset:4608
	v_mov_b32_e32 v96, v88
	v_mov_b32_e32 v97, v88
	v_mfma_f32_16x16x32_bf16 v[44:47], v[56:59], v[20:23], v[12:15]
	v_mul_f32_e32 v21, s89, v150
	v_mul_f32_e32 v20, s89, v126
	v_exp_f32_e32 v86, v21
	s_nop 0
	ds_read_b128 v[12:15], v128 offset:4672
	s_waitcnt lgkmcnt(1)
	v_mfma_f32_16x16x32_bf16 v[16:19], v[4:7], v[16:19], 0
	v_exp_f32_e32 v74, v20
	v_mov_b32_e32 v87, v86
	s_mov_b32 s89, 0
	s_waitcnt lgkmcnt(0)
	v_mfma_f32_16x16x32_bf16 v[12:15], v[8:11], v[12:15], v[16:19]
	v_mul_f32_e32 v110, 0, v74
	v_mov_b32_e32 v111, v110
	v_mov_b32_e32 v112, v110
	ds_read_b128 v[16:19], v129 offset:4608
	ds_read_b64_tr_b16 v[20:21], v130 offset:18432
	ds_read_b64_tr_b16 v[22:23], v130 offset:19008
	ds_read_b128 v[48:51], v129 offset:4672
	s_nop 0
	v_pk_mul_f32 v[14:15], v[86:87], v[14:15] op_sel_hi:[0,1]
	v_pk_mul_f32 v[12:13], v[86:87], v[12:13] op_sel_hi:[0,1]
	v_mov_b32_e32 v113, v110
	v_mov_b32_e32 v76, v74
	s_waitcnt lgkmcnt(3)
	v_mfma_f32_16x16x32_bf16 v[12:15], v[52:55], v[16:19], v[12:15]
	ds_read_b64_tr_b16 v[16:17], v130 offset:23040
	ds_read_b64_tr_b16 v[18:19], v130 offset:23616
	ds_read_b128 v[104:107], v128 offset:6912
	ds_read_b128 v[114:117], v128 offset:6976
	ds_read_b128 v[118:121], v129 offset:6912
	ds_read_b128 v[138:141], v129 offset:6976
	v_mov_b32_e32 v77, v74
	s_waitcnt lgkmcnt(7)
	v_mfma_f32_16x16x32_bf16 v[20:23], v[20:23], v[52:55], v[110:113]
	v_add_u32_e32 v136, s87, v175
	s_waitcnt lgkmcnt(4)
	v_mfma_f32_16x16x32_bf16 v[16:19], v[16:19], v[56:59], v[20:23]
	v_mfma_f32_16x16x32_bf16 v[48:51], v[56:59], v[48:51], v[12:15]
	s_waitcnt lgkmcnt(3)
; #define LAS __attribute__((address_space(3)))
; __device__ __forceinline__ unsigned pk2(float lo, float hi) { return pg8::cvt_pk_bf16(lo, hi); }
; __device__ __forceinline__ f32x4 mfma16(bf16x8 a, bf16x8 b, f32x4 c) { return __builtin_amdgcn_mfma_f32_16x16x32_bf16(a, b, c, 0, 0, 0); }
; __device__ __forceinline__ void retention_unit(LAS unsigned char* lds, const Ptrs& P, int b, int h, int tid) {
;     ...
;             for (int dt = 0; dt < 4; ++dt) { st[dt] = st[dt] * dch;
; #pragma unroll
;                 for (int ks = 0; ks < 2; ++ks) { const bf16x8 kf = tr_frag(bufc + ROFF_K2, S72 * 2, dt, ks, fq, fr); st[dt] = mfma16(kf, bv[ks], st[dt]); }
;                 v2u pw; pw.x = pk2(st[dt][0], st[dt][1]); pw.y = pk2(st[dt][2], st[dt][3]);
;                 *(LAS v2u*)(St + (16 * w + fr) * S72 + 16 * dt + 4 * fq) = pw; }
; #pragma unroll
;             for (int it = 0; it < 4; ++it) { const f32x4 v = o[it]; typedef float f32x2 __attribute__((ext_vector_type(2)));
;                 *(LAS f32x2*)(part + ((16 * it + fr) * 32 + w * 4 + fq) * 2) = (f32x2){(v[0] + v[1]) + (v[2] + v[3]), (v[0] * v[0] + v[1] * v[1]) + (v[2] * v[2] + v[3] * v[3])};
;                 op[it] = v; }
	v_mfma_f32_16x16x32_bf16 v[4:7], v[4:7], v[104:107], 0
	s_nop 4
	v_cvt_pk_bf16_f32 v20, v16, v17
	v_cvt_pk_bf16_f32 v21, v18, v19
	ds_write_b64 v132, v[20:21]
	ds_read_b64_tr_b16 v[20:21], v130 offset:18464
	ds_read_b64_tr_b16 v[22:23], v130 offset:19040
	ds_read_b64_tr_b16 v[12:13], v130 offset:23072
	ds_read_b64_tr_b16 v[14:15], v130 offset:23648
	s_waitcnt lgkmcnt(2)
	v_mfma_f32_16x16x32_bf16 v[20:23], v[20:23], v[52:55], v[110:113]
	s_waitcnt lgkmcnt(0)
	v_mfma_f32_16x16x32_bf16 v[12:15], v[12:15], v[56:59], v[20:23]
	v_mfma_f32_16x16x32_bf16 v[4:7], v[8:11], v[114:117], v[4:7]
	s_nop 6
	v_cvt_pk_bf16_f32 v20, v12, v13
	v_cvt_pk_bf16_f32 v21, v14, v15
	ds_write_b64 v132, v[20:21] offset:32
	ds_read_b64_tr_b16 v[20:21], v130 offset:18496
	ds_read_b64_tr_b16 v[22:23], v130 offset:19072
	ds_read_b64_tr_b16 v[104:105], v130 offset:23104
	ds_read_b64_tr_b16 v[106:107], v130 offset:23680
	s_waitcnt lgkmcnt(2)
	v_mfma_f32_16x16x32_bf16 v[8:11], v[20:23], v[52:55], v[110:113]
	v_mul_f32_e64 v6, v88, v6
	v_mul_f32_e64 v7, v88, v7
	v_pk_mul_f32 v[4:5], v[88:89], v[4:5] op_sel_hi:[0,1]
	s_waitcnt lgkmcnt(0)
	v_mfma_f32_16x16x32_bf16 v[8:11], v[104:107], v[56:59], v[8:11]
	v_mov_b32_e32 v106, v78
	v_mov_b32_e32 v107, v78
	v_mov_b32_e32 v104, v86
	v_mfma_f32_16x16x32_bf16 v[4:7], v[52:55], v[118:121], v[4:7]
	v_mov_b32_e32 v105, v86
	s_nop 2
	v_cvt_pk_bf16_f32 v20, v8, v9
	v_cvt_pk_bf16_f32 v21, v10, v11
	ds_write_b64 v132, v[20:21] offset:64
	ds_read_b64_tr_b16 v[114:115], v130 offset:18528
	ds_read_b64_tr_b16 v[116:117], v130 offset:19104
	ds_read_b64_tr_b16 v[118:119], v130 offset:23136
	ds_read_b64_tr_b16 v[120:121], v130 offset:23712
	v_mfma_f32_16x16x32_bf16 v[20:23], v[56:59], v[138:141], v[4:7]
	s_waitcnt lgkmcnt(2)
	v_mfma_f32_16x16x32_bf16 v[4:7], v[114:117], v[52:55], v[110:113]
	v_mul_f32_e32 v55, v41, v41
	v_mov_b32_e32 v54, v41
	s_waitcnt lgkmcnt(0)
	v_mfma_f32_16x16x32_bf16 v[4:7], v[118:121], v[56:59], v[4:7]
	v_mul_f32_e32 v57, v42, v42
	v_mul_f32_e32 v59, v43, v43
	v_mov_b32_e32 v56, v42
	v_mov_b32_e32 v58, v43
	v_lshl_add_u64 v[110:111], s[92:93], 0, v[64:65]
	s_nop 2
	v_cvt_pk_bf16_f32 v52, v4, v5
	v_cvt_pk_bf16_f32 v53, v6, v7
	ds_write_b64 v132, v[52:53] offset:96
	v_mul_f32_e32 v53, v40, v40
	v_mov_b32_e32 v52, v40
	v_pk_add_f32 v[52:53], v[52:53], v[54:55]
	v_pk_add_f32 v[54:55], v[56:57], v[58:59]
	v_mul_f32_e32 v57, v46, v46
	v_pk_add_f32 v[52:53], v[52:53], v[54:55]
	ds_write_b64 v133, v[52:53]
	v_mul_f32_e32 v53, v44, v44
	v_mul_f32_e32 v55, v45, v45
	v_mul_f32_e32 v59, v47, v47
	v_mov_b32_e32 v52, v44
	v_mov_b32_e32 v54, v45
	v_mov_b32_e32 v56, v46
	v_mov_b32_e32 v58, v47
	s_lshl_b64 s[92:93], s[18:19], 21
	v_pk_add_f32 v[52:53], v[52:53], v[54:55]
	v_pk_add_f32 v[54:55], v[56:57], v[58:59]
	s_or_b32 s94, s92, s90
	s_lshl_b64 s[18:19], s[18:19], 22
	v_pk_add_f32 v[52:53], v[52:53], v[54:55]
	s_add_u32 s90, s87, s90
	ds_write_b64 v134, v[52:53]
	v_mul_f32_e32 v53, v48, v48
	v_mul_f32_e32 v55, v49, v49
	v_mul_f32_e32 v57, v50, v50
	v_mul_f32_e32 v59, v51, v51
	v_mov_b32_e32 v52, v48
	v_mov_b32_e32 v54, v49
	v_mov_b32_e32 v56, v50
	v_mov_b32_e32 v58, v51
	s_addc_u32 s91, 0, 0
	v_pk_add_f32 v[52:53], v[52:53], v[54:55]
	v_pk_add_f32 v[54:55], v[56:57], v[58:59]
	s_add_u32 s18, s90, s18
	v_pk_add_f32 v[52:53], v[52:53], v[54:55]
	s_addc_u32 s19, s91, s19
	ds_write_b64 v135, v[52:53]
	v_mul_f32_e32 v53, v20, v20
	v_mul_f32_e32 v55, v21, v21
	v_mul_f32_e32 v57, v22, v22
	v_mul_f32_e32 v59, v23, v23
	v_mov_b32_e32 v52, v20
	v_mov_b32_e32 v54, v21
	v_mov_b32_e32 v56, v22
	v_mov_b32_e32 v58, v23
	v_lshl_add_u64 v[114:115], s[18:19], 0, v[68:69]
	s_add_u32 s18, s90, s92
	v_pk_add_f32 v[52:53], v[52:53], v[54:55]
	v_pk_add_f32 v[54:55], v[56:57], v[58:59]
	s_mov_b32 s95, s93
	s_addc_u32 s19, s91, s93
	v_pk_add_f32 v[52:53], v[52:53], v[54:55]
	v_lshl_add_u64 v[112:113], s[94:95], 0, v[66:67]
	v_lshl_add_u64 v[116:117], s[18:19], 0, v[70:71]
	ds_write_b64 v136, v[52:53]
	s_branch .LBB0_658

; #define LAS __attribute__((address_space(3)))
; #define LBAR() do { asm volatile("s_waitcnt lgkmcnt(0)" ::: "memory"); __builtin_amdgcn_s_barrier(); asm volatile("" ::: "memory"); } while (0)
; __device__ __forceinline__ unsigned pk2(float lo, float hi) { return pg8::cvt_pk_bf16(lo, hi); }
; __device__ __forceinline__ void retention_unit(LAS unsigned char* lds, const Ptrs& P, int b, int h, int tid) {
;     ...
;     for (int n = 0; n <= 32; ++n) {
;         LAS unsigned char* bufc = lds + (n & 1) * RSET;
;         LAS bf16* Qs = (LAS bf16*)(bufc + ROFF_Q); LAS bf16* Ks = (LAS bf16*)(bufc + ROFF_K); LAS bf16* K2s = (LAS bf16*)(bufc + ROFF_K2); LAS bf16* Vs = (LAS bf16*)(bufc + ROFF_V);
;         if (n < 32) {
;             *(LAS v4u*)(Qs + lrow * S72 + lseg * 8) = rq; *(LAS v4u*)(Ks + lrow * S72 + lseg * 8) = rk;
;             v4u k2;
; #pragma unroll
;             for (int t = 0; t < 4; ++t) k2[t] = pk2(bflo(rk[t]) * dkey, bfhi(rk[t]) * dkey);
;             *(LAS v4u*)(K2s + lrow * S72 + lseg * 8) = k2;
;             *(LAS v4u*)(Vs + vrow0 * S144 + vseg * 8) = rv0; *(LAS v4u*)(Vs + (vrow0 + 32) * S144 + vseg * 8) = rv1;
;         }
;         if (n >= 1) {
; #pragma unroll
;             for (int it = 0; it < 4; ++it) sgr[it] = __builtin_nontemporal_load((const v2u*)(gsl + ((size_t)(n - 1) * 64 + 16 * it) * 512));
;         }
;         LBAR();
;         if (n + 1 < 32) { const size_t o4 = (size_t)(n + 1) * 64;
;             rq = __builtin_nontemporal_load((const v4u*)(gq + o4 * 256)); rk = __builtin_nontemporal_load((const v4u*)(gk + o4 * 256)); rv0 = __builtin_nontemporal_load((const v4u*)(gv + o4 * 512)); rv1 = __builtin_nontemporal_load((const v4u*)(gv + (o4 + 32) * 512)); }
;         if (n >= 1) {
;             const int row = tid >> 3, sub = tid & 7;
;             const f32x4 pa = *(const LAS f32x4*)(part + (row * 32 + sub * 4) * 2), pb = *(const LAS f32x4*)(part + (row * 32 + sub * 4) * 2 + 4);
;             float s1 = (pa[0] + pa[2]) + (pb[0] + pb[2]), s2 = (pa[1] + pa[3]) + (pb[1] + pb[3]);
; #pragma unroll
;             for (int x = 1; x < 8; x <<= 1) { s1 += __shfl_xor(s1, x); s2 += __shfl_xor(s2, x); }
;             if (sub == 0) { const float mean = s1 * (1.f / 128.f); float var = s2 * (1.f / 128.f) - mean * mean; var = var < 0.f ? 0.f : var;
;                 stat[row * 2] = mean; stat[row * 2 + 1] = __builtin_amdgcn_rsqf(var + 1e-5f); }
;         }
.LBB0_658:
	s_add_i32 s89, s89, 1
	s_bitcmp1_b32 s89, 0
	s_cselect_b32 s18, 0xb400, 0
	s_add_i32 s90, s18, 0
	v_add3_u32 v52, s90, v163, v72
	s_waitcnt vmcnt(3)
	ds_write_b128 v52, v[36:39]
	s_waitcnt vmcnt(2)
	ds_write_b128 v52, v[24:27] offset:9216
	v_lshlrev_b32_e32 v36, 16, v24
	v_and_b32_e32 v37, 0xffff0000, v24
	v_pk_mul_f32 v[36:37], v[102:103], v[36:37]
	v_add_u32_e32 v56, 0, v159
	v_cvt_pk_bf16_f32 v24, v36, v37
	v_lshlrev_b32_e32 v36, 16, v25
	v_and_b32_e32 v37, 0xffff0000, v25
	v_pk_mul_f32 v[36:37], v[102:103], v[36:37]
	v_add_u32_e32 v139, 0x1d400, v56
	v_cvt_pk_bf16_f32 v25, v36, v37
	v_lshlrev_b32_e32 v36, 16, v26
	v_and_b32_e32 v37, 0xffff0000, v26
	v_pk_mul_f32 v[36:37], v[102:103], v[36:37]
	v_and_b32_e32 v60, 64, v131
	v_cvt_pk_bf16_f32 v26, v36, v37
	v_lshlrev_b32_e32 v36, 16, v27
	v_and_b32_e32 v37, 0xffff0000, v27
	v_pk_mul_f32 v[36:37], v[102:103], v[36:37]
	v_add_u32_e32 v60, 64, v60
	v_cvt_pk_bf16_f32 v27, v36, v37
	ds_write_b128 v52, v[24:27] offset:18432
	v_add3_u32 v24, s90, v158, v84
	s_waitcnt vmcnt(1)
	ds_write_b128 v24, v[28:31] offset:27648
	s_waitcnt vmcnt(0)
	ds_write_b128 v24, v[32:35] offset:36864
	v_lshl_add_u64 v[24:25], s[26:27], 0, v[116:117]
	v_add_co_u32_e32 v26, vcc, s58, v24
	v_xor_b32_e32 v61, 1, v131
	s_nop 0
	v_addc_co_u32_e32 v27, vcc, 0, v25, vcc
	v_add_co_u32_e32 v28, vcc, s59, v24
	s_nop 1
	v_addc_co_u32_e32 v29, vcc, 0, v25, vcc
	v_add_co_u32_e32 v30, vcc, s60, v24
	s_nop 1
	v_addc_co_u32_e32 v31, vcc, 0, v25, vcc
	v_add_co_u32_e32 v24, vcc, s61, v24
	s_nop 1
	v_addc_co_u32_e32 v25, vcc, 0, v25, vcc
	global_load_dwordx2 v[54:55], v[26:27], off nt
	global_load_dwordx2 v[52:53], v[28:29], off nt
	global_load_dwordx2 v[122:123], v[30:31], off nt
	global_load_dwordx2 v[118:119], v[24:25], off nt
	v_lshl_add_u64 v[24:25], s[26:27], 0, v[110:111]
	v_add_co_u32_e32 v26, vcc, s62, v24
	v_lshl_add_u64 v[28:29], s[26:27], 0, v[112:113]
	s_nop 0
	v_addc_co_u32_e32 v27, vcc, 0, v25, vcc
	v_add_co_u32_e32 v24, vcc, s63, v24
	s_waitcnt lgkmcnt(0)
	s_barrier
	s_nop 0
	v_addc_co_u32_e32 v25, vcc, 0, v25, vcc
	v_add_co_u32_e32 v30, vcc, s64, v28
	global_load_dwordx4 v[36:39], v[26:27], off nt
	s_nop 0
	global_load_dwordx4 v[24:27], v[24:25], off nt
	v_addc_co_u32_e32 v31, vcc, 0, v29, vcc
	v_add_co_u32_e32 v32, vcc, s65, v28
	s_nop 1
	v_addc_co_u32_e32 v33, vcc, 0, v29, vcc
	global_load_dwordx4 v[28:31], v[30:31], off nt
	s_nop 0
	global_load_dwordx4 v[32:35], v[32:33], off nt
	ds_read_b128 v[56:59], v139
	ds_read_b128 v[184:187], v139 offset:16
	v_cmp_lt_i32_e32 vcc, v61, v60
	s_waitcnt lgkmcnt(1)
	v_pk_add_f32 v[56:57], v[56:57], v[58:59]
	v_cndmask_b32_e32 v61, v131, v61, vcc
	s_waitcnt lgkmcnt(0)
	v_pk_add_f32 v[58:59], v[184:185], v[186:187]
	v_lshlrev_b32_e32 v138, 2, v61
	v_pk_add_f32 v[56:57], v[56:57], v[58:59]
	ds_bpermute_b32 v58, v138, v56
	ds_bpermute_b32 v59, v138, v57
	v_xor_b32_e32 v61, 2, v131
	v_cmp_lt_i32_e32 vcc, v61, v60
	s_waitcnt lgkmcnt(0)
	v_pk_add_f32 v[56:57], v[56:57], v[58:59]
	v_cndmask_b32_e32 v61, v131, v61, vcc
	v_lshlrev_b32_e32 v140, 2, v61
	ds_bpermute_b32 v58, v140, v56
	ds_bpermute_b32 v59, v140, v57
	s_waitcnt lgkmcnt(0)
	v_pk_add_f32 v[56:57], v[56:57], v[58:59]
	v_xor_b32_e32 v58, 4, v131
	v_cmp_lt_i32_e32 vcc, v58, v60
	s_nop 1
	v_cndmask_b32_e32 v58, v131, v58, vcc
	v_lshlrev_b32_e32 v141, 2, v58
	ds_bpermute_b32 v58, v141, v56
	ds_bpermute_b32 v59, v141, v57
	s_and_saveexec_b64 s[18:19], s[0:1]
	s_cbranch_execz .LBB0_657
	s_waitcnt lgkmcnt(0)
	v_pk_add_f32 v[56:57], v[56:57], v[58:59]
	v_add_u32_e32 v58, 0, v198
	v_pk_mul_f32 v[56:57], v[56:57], s[6:7] op_sel_hi:[1,0]
	v_add_u32_e32 v58, 0x21400, v58
	v_fma_f32 v57, -v56, v56, v57
	v_cmp_ngt_f32_e32 vcc, 0, v57
	s_nop 1
	v_cndmask_b32_e32 v57, 0, v57, vcc
	v_add_f32_e32 v57, 0x3727c5ac, v57
	v_rsq_f32_e32 v57, v57
	ds_write2_b32 v58, v56, v57 offset1:1
	s_branch .LBB0_657

; #define PG8_STAGE(bufoff, gbase, voff) do { _Pragma("unroll") for (int _i = 0; _i < 2; ++_i) \
;         __builtin_amdgcn_global_load_lds((const unsigned*)((const char*)(gbase) + (voff)[_i]), (PG8_LAS unsigned*)(lds + (bufoff) + ldsw + _i * 8192), 16, 0, 0); } while (0)
; #define PG8_LDA(dst, b, h) do { _Pragma("unroll") for (int m = 0; m < 4; ++m) _Pragma("unroll") for (int k = 0; k < 2; ++k) dst[m][k] = *(const PG8_LAS bf16x8*)(lds + PG8_SA(b, h) + aoff + m * 2048 + k * 1024); } while (0)
; #define PG8_LDB(dst, b, h) do { _Pragma("unroll") for (int n = 0; n < 2; ++n) _Pragma("unroll") for (int k = 0; k < 2; ++k) dst[n][k] = *(const PG8_LAS bf16x8*)(lds + PG8_SB(b, h) + boff + n * 2048 + k * 1024); } while (0)
; #define PG8_MMA(ai, bj, At, Bt) do { __builtin_amdgcn_s_setprio(1); _Pragma("unroll") for (int m = 0; m < 4; ++m) _Pragma("unroll") for (int n = 0; n < 2; ++n) _Pragma("unroll") for (int k = 0; k < 2; ++k) \
;         acc[ai][bj][m][n] = __builtin_amdgcn_mfma_f32_16x16x32_bf16(Bt[n][k], At[m][k], acc[ai][bj][m][n], 0, 0, 0); __builtin_amdgcn_s_setprio(0); } while (0)
; #define PG8_WAIT_V(n) asm volatile("s_waitcnt vmcnt(" #n ")" ::: "memory")
; #define PG8_WAIT_L(n) asm volatile("s_waitcnt lgkmcnt(" #n ")" ::: "memory")
; #define PG8_BAR __builtin_amdgcn_s_barrier()
; #define PG8_SCHED __builtin_amdgcn_sched_barrier(0)
; template <class Epi, class Sched, bool ALIGN_EPI = false, bool SP2 = false, bool ATILED = false>
; __device__ __forceinline__ void gemm_phase(PG8_LAS unsigned char* lds, const Gemm g, const Sched& S, const Epi& E) {
;     ...
;             PG8_LDB(B0, 0, 0); PG8_LDB(B1, 0, 1); PG8_SCHED; PG8_LDA(At, 0, 0); PG8_STAGE(PG8_SA(1, 1), a1 + hstepA, voffA);
;             PG8_WAIT_V(8); PG8_WAIT_L(0); PG8_BAR; PG8_MMA(0, 0, At, B0); PG8_MMA(0, 1, At, B1); PG8_BAR; PG8_SCHED;
;             PG8_LDA(At, 0, 1); PG8_STAGE(PG8_SB(0, 0), b2, voffB); PG8_STAGE(PG8_SB(0, 1), b2 + hstep, voffB); PG8_STAGE(PG8_SA(0, 0), a2, voffA);
.LBB0_735:
	ds_read_b128 v[128:131], v189
	ds_read_b128 v[132:135], v189 offset:1024
	ds_read_b128 v[136:139], v189 offset:2048
	ds_read_b128 v[140:143], v189 offset:3072
	ds_read_b128 v[144:147], v190
	ds_read_b128 v[148:151], v190 offset:1024
	ds_read_b128 v[168:171], v190 offset:2048
	ds_read_b128 v[172:175], v190 offset:3072
	s_add_u32 s54, s50, 0xfffc0080
	s_addc_u32 s55, s51, -1
	s_cmp_eq_u32 s73, 12
	s_cselect_b32 s57, s19, s55
	s_cselect_b32 s56, s49, s54
	s_cselect_b32 s55, s17, s72
	s_cselect_b32 s54, s70, s71
	v_lshl_add_u64 v[184:185], s[50:51], 0, v[160:161]
	s_add_i32 m0, s58, 0xc000
	ds_read_b128 v[176:179], v191
	ds_read_b128 v[180:183], v191 offset:1024
	ds_read_b128 v[194:197], v191 offset:2048
	ds_read_b128 v[200:203], v191 offset:3072
	ds_read_b128 v[204:207], v191 offset:4096
	ds_read_b128 v[208:211], v191 offset:5120
	ds_read_b128 v[212:215], v191 offset:6144
	ds_read_b128 v[216:219], v191 offset:7168
	global_load_lds_dwordx4 v[184:185], off
	v_lshl_add_u64 v[184:185], s[50:51], 0, v[162:163]
	s_add_i32 m0, s58, 0xe000
	s_nop 0
	global_load_lds_dwordx4 v[184:185], off
	s_waitcnt vmcnt(8)
	s_waitcnt lgkmcnt(0)
	s_barrier
	s_waitcnt lgkmcnt(0)
	v_mfma_f32_16x16x32_bf16 v[124:127], v[128:131], v[176:179], v[124:127]
	v_mfma_f32_16x16x32_bf16 v[120:123], v[136:139], v[176:179], v[120:123]
	v_mfma_f32_16x16x32_bf16 v[108:111], v[128:131], v[194:197], v[108:111]
	v_mfma_f32_16x16x32_bf16 v[104:107], v[136:139], v[194:197], v[104:107]
	v_mfma_f32_16x16x32_bf16 v[92:95], v[128:131], v[204:207], v[92:95]
	v_mfma_f32_16x16x32_bf16 v[88:91], v[136:139], v[204:207], v[88:91]
	v_mfma_f32_16x16x32_bf16 v[76:79], v[128:131], v[212:215], v[76:79]
	v_mfma_f32_16x16x32_bf16 v[72:75], v[136:139], v[212:215], v[72:75]
	v_mfma_f32_16x16x32_bf16 v[124:127], v[132:135], v[180:183], v[124:127]
	v_mfma_f32_16x16x32_bf16 v[120:123], v[140:143], v[180:183], v[120:123]
	v_mfma_f32_16x16x32_bf16 v[108:111], v[132:135], v[200:203], v[108:111]
	v_mfma_f32_16x16x32_bf16 v[104:107], v[140:143], v[200:203], v[104:107]
	v_mfma_f32_16x16x32_bf16 v[92:95], v[132:135], v[208:211], v[92:95]
	v_mfma_f32_16x16x32_bf16 v[88:91], v[140:143], v[208:211], v[88:91]
	v_mfma_f32_16x16x32_bf16 v[76:79], v[132:135], v[216:219], v[76:79]
	v_mfma_f32_16x16x32_bf16 v[72:75], v[140:143], v[216:219], v[72:75]
	v_mfma_f32_16x16x32_bf16 v[116:119], v[144:147], v[176:179], v[116:119]
	v_mfma_f32_16x16x32_bf16 v[112:115], v[168:171], v[176:179], v[112:115]
	v_mfma_f32_16x16x32_bf16 v[100:103], v[144:147], v[194:197], v[100:103]
	v_mfma_f32_16x16x32_bf16 v[96:99], v[168:171], v[194:197], v[96:99]
	v_mfma_f32_16x16x32_bf16 v[84:87], v[144:147], v[204:207], v[84:87]
	v_mfma_f32_16x16x32_bf16 v[80:83], v[168:171], v[204:207], v[80:83]
	v_mfma_f32_16x16x32_bf16 v[68:71], v[144:147], v[212:215], v[68:71]
	v_mfma_f32_16x16x32_bf16 v[64:67], v[168:171], v[212:215], v[64:67]
	v_mfma_f32_16x16x32_bf16 v[116:119], v[148:151], v[180:183], v[116:119]
	v_mfma_f32_16x16x32_bf16 v[112:115], v[172:175], v[180:183], v[112:115]
	v_mfma_f32_16x16x32_bf16 v[100:103], v[148:151], v[200:203], v[100:103]
	v_mfma_f32_16x16x32_bf16 v[96:99], v[172:175], v[200:203], v[96:99]
	v_mfma_f32_16x16x32_bf16 v[84:87], v[148:151], v[208:211], v[84:87]
	v_mfma_f32_16x16x32_bf16 v[80:83], v[172:175], v[208:211], v[80:83]
	v_mfma_f32_16x16x32_bf16 v[68:71], v[148:151], v[216:219], v[68:71]
	v_mfma_f32_16x16x32_bf16 v[64:67], v[172:175], v[216:219], v[64:67]
	s_barrier
	s_add_i32 s74, s67, s29
	v_lshl_add_u64 v[184:185], s[54:55], 0, v[154:155]
	s_mov_b32 m0, s74
	ds_read_b128 v[176:179], v191 offset:16384
	ds_read_b128 v[180:183], v191 offset:17408
	ds_read_b128 v[194:197], v191 offset:18432
	ds_read_b128 v[200:203], v191 offset:19456
	ds_read_b128 v[204:207], v191 offset:20480
	ds_read_b128 v[208:211], v191 offset:21504
	ds_read_b128 v[212:215], v191 offset:22528
	ds_read_b128 v[216:219], v191 offset:23552
	global_load_lds_dwordx4 v[184:185], off
	s_add_i32 m0, s74, 0x2000
	s_add_u32 s74, s54, 0x40000
	v_lshl_add_u64 v[220:221], s[54:55], 0, v[158:159]
	s_addc_u32 s75, s55, 0
	s_add_i32 s76, s68, s29
	global_load_lds_dwordx4 v[220:221], off
	v_lshl_add_u64 v[222:223], s[74:75], 0, v[154:155]
	s_mov_b32 m0, s76
	v_lshl_add_u64 v[224:225], s[56:57], 0, v[156:157]
	global_load_lds_dwordx4 v[222:223], off
	v_lshl_add_u64 v[222:223], s[74:75], 0, v[158:159]
	s_add_i32 m0, s76, 0x2000
	s_nop 0
	global_load_lds_dwordx4 v[222:223], off
	v_lshl_add_u64 v[222:223], s[56:57], 0, v[152:153]
	s_mov_b32 m0, s58
	s_nop 0
	global_load_lds_dwordx4 v[222:223], off
	s_mov_b32 m0, s59
	s_nop 0
	global_load_lds_dwordx4 v[224:225], off
	s_waitcnt vmcnt(8)
	s_waitcnt lgkmcnt(0)
	s_barrier
; #define PG8_STAGE(bufoff, gbase, voff) do { _Pragma("unroll") for (int _i = 0; _i < 2; ++_i) \
;         __builtin_amdgcn_global_load_lds((const unsigned*)((const char*)(gbase) + (voff)[_i]), (PG8_LAS unsigned*)(lds + (bufoff) + ldsw + _i * 8192), 16, 0, 0); } while (0)
; #define PG8_LDA(dst, b, h) do { _Pragma("unroll") for (int m = 0; m < 4; ++m) _Pragma("unroll") for (int k = 0; k < 2; ++k) dst[m][k] = *(const PG8_LAS bf16x8*)(lds + PG8_SA(b, h) + aoff + m * 2048 + k * 1024); } while (0)
; #define PG8_LDB(dst, b, h) do { _Pragma("unroll") for (int n = 0; n < 2; ++n) _Pragma("unroll") for (int k = 0; k < 2; ++k) dst[n][k] = *(const PG8_LAS bf16x8*)(lds + PG8_SB(b, h) + boff + n * 2048 + k * 1024); } while (0)
; #define PG8_MMA(ai, bj, At, Bt) do { __builtin_amdgcn_s_setprio(1); _Pragma("unroll") for (int m = 0; m < 4; ++m) _Pragma("unroll") for (int n = 0; n < 2; ++n) _Pragma("unroll") for (int k = 0; k < 2; ++k) \
;         acc[ai][bj][m][n] = __builtin_amdgcn_mfma_f32_16x16x32_bf16(Bt[n][k], At[m][k], acc[ai][bj][m][n], 0, 0, 0); __builtin_amdgcn_s_setprio(0); } while (0)
; #define PG8_WAIT_V(n) asm volatile("s_waitcnt vmcnt(" #n ")" ::: "memory")
; #define PG8_WAIT_L(n) asm volatile("s_waitcnt lgkmcnt(" #n ")" ::: "memory")
; #define PG8_BAR __builtin_amdgcn_s_barrier()
; #define PG8_SCHED __builtin_amdgcn_sched_barrier(0)
; template <class Epi, class Sched, bool ALIGN_EPI = false, bool SP2 = false, bool ATILED = false>
; __device__ __forceinline__ void gemm_phase(PG8_LAS unsigned char* lds, const Gemm g, const Sched& S, const Epi& E) {
;     ...
;             PG8_WAIT_V(8); PG8_WAIT_L(0); PG8_BAR; PG8_MMA(1, 0, At, B0); PG8_MMA(1, 1, At, B1); PG8_BAR; PG8_SCHED;
;             PG8_LDB(B0, 1, 0); PG8_LDB(B1, 1, 1); PG8_SCHED; PG8_LDA(At, 1, 0); PG8_STAGE(PG8_SA(0, 1), a2 + hstepA, voffA);
;             PG8_WAIT_V(8); PG8_WAIT_L(0); PG8_BAR; PG8_MMA(0, 0, At, B0); PG8_MMA(0, 1, At, B1); PG8_BAR; PG8_SCHED;
	s_waitcnt lgkmcnt(0)
	v_mfma_f32_16x16x32_bf16 v[60:63], v[128:131], v[176:179], v[60:63]
	v_mfma_f32_16x16x32_bf16 v[56:59], v[136:139], v[176:179], v[56:59]
	v_mfma_f32_16x16x32_bf16 v[44:47], v[128:131], v[194:197], v[44:47]
	v_mfma_f32_16x16x32_bf16 v[40:43], v[136:139], v[194:197], v[40:43]
	v_mfma_f32_16x16x32_bf16 v[28:31], v[128:131], v[204:207], v[28:31]
	v_mfma_f32_16x16x32_bf16 v[24:27], v[136:139], v[204:207], v[24:27]
	v_mfma_f32_16x16x32_bf16 v[12:15], v[128:131], v[212:215], v[12:15]
	v_mfma_f32_16x16x32_bf16 v[8:11], v[136:139], v[212:215], v[8:11]
	v_mfma_f32_16x16x32_bf16 v[60:63], v[132:135], v[180:183], v[60:63]
	v_mfma_f32_16x16x32_bf16 v[56:59], v[140:143], v[180:183], v[56:59]
	v_mfma_f32_16x16x32_bf16 v[44:47], v[132:135], v[200:203], v[44:47]
	v_mfma_f32_16x16x32_bf16 v[40:43], v[140:143], v[200:203], v[40:43]
	v_mfma_f32_16x16x32_bf16 v[28:31], v[132:135], v[208:211], v[28:31]
	v_mfma_f32_16x16x32_bf16 v[24:27], v[140:143], v[208:211], v[24:27]
	v_mfma_f32_16x16x32_bf16 v[12:15], v[132:135], v[216:219], v[12:15]
	v_mfma_f32_16x16x32_bf16 v[8:11], v[140:143], v[216:219], v[8:11]
	v_mfma_f32_16x16x32_bf16 v[52:55], v[144:147], v[176:179], v[52:55]
	v_mfma_f32_16x16x32_bf16 v[48:51], v[168:171], v[176:179], v[48:51]
	v_mfma_f32_16x16x32_bf16 v[36:39], v[144:147], v[194:197], v[36:39]
	v_mfma_f32_16x16x32_bf16 v[32:35], v[168:171], v[194:197], v[32:35]
	v_mfma_f32_16x16x32_bf16 v[20:23], v[144:147], v[204:207], v[20:23]
	v_mfma_f32_16x16x32_bf16 v[16:19], v[168:171], v[204:207], v[16:19]
	v_mfma_f32_16x16x32_bf16 v[4:7], v[144:147], v[212:215], v[4:7]
	v_mfma_f32_16x16x32_bf16 v[0:3], v[168:171], v[212:215], v[0:3]
	v_mfma_f32_16x16x32_bf16 v[52:55], v[148:151], v[180:183], v[52:55]
	v_mfma_f32_16x16x32_bf16 v[48:51], v[172:175], v[180:183], v[48:51]
	v_mfma_f32_16x16x32_bf16 v[36:39], v[148:151], v[200:203], v[36:39]
	v_mfma_f32_16x16x32_bf16 v[32:35], v[172:175], v[200:203], v[32:35]
	v_mfma_f32_16x16x32_bf16 v[20:23], v[148:151], v[208:211], v[20:23]
	v_mfma_f32_16x16x32_bf16 v[16:19], v[172:175], v[208:211], v[16:19]
	v_mfma_f32_16x16x32_bf16 v[4:7], v[148:151], v[216:219], v[4:7]
	v_mfma_f32_16x16x32_bf16 v[0:3], v[172:175], v[216:219], v[0:3]
	s_barrier
	s_add_i32 s74, 0, 0x18000
	s_add_i32 s75, 0, 0x1c000
	v_add_u32_e32 v140, s74, v187
	v_add_u32_e32 v172, s75, v187
	ds_read_b128 v[128:131], v140
	ds_read_b128 v[132:135], v140 offset:1024
	ds_read_b128 v[136:139], v140 offset:2048
	ds_read_b128 v[140:143], v140 offset:3072
	ds_read_b128 v[144:147], v172
	ds_read_b128 v[148:151], v172 offset:1024
	ds_read_b128 v[168:171], v172 offset:2048
	ds_read_b128 v[172:175], v172 offset:3072
	s_add_u32 s56, s56, 0x40000
	s_addc_u32 s57, s57, 0
	s_mov_b32 m0, s60
	v_lshl_add_u64 v[226:227], s[56:57], 0, v[152:153]
	ds_read_b128 v[176:179], v191 offset:32768
	ds_read_b128 v[180:183], v191 offset:33792
	ds_read_b128 v[194:197], v191 offset:34816
	ds_read_b128 v[200:203], v191 offset:35840
	ds_read_b128 v[204:207], v191 offset:36864
	ds_read_b128 v[208:211], v191 offset:37888
	ds_read_b128 v[212:215], v191 offset:38912
	ds_read_b128 v[216:219], v191 offset:39936
	global_load_lds_dwordx4 v[226:227], off
	v_lshl_add_u64 v[226:227], s[56:57], 0, v[156:157]
	s_mov_b32 m0, s61
	s_nop 0
	global_load_lds_dwordx4 v[226:227], off
	s_waitcnt vmcnt(8)
	s_waitcnt lgkmcnt(0)
	s_barrier
	s_waitcnt lgkmcnt(0)
	v_mfma_f32_16x16x32_bf16 v[124:127], v[128:131], v[176:179], v[124:127]
	v_mfma_f32_16x16x32_bf16 v[120:123], v[136:139], v[176:179], v[120:123]
	v_mfma_f32_16x16x32_bf16 v[108:111], v[128:131], v[194:197], v[108:111]
	v_mfma_f32_16x16x32_bf16 v[104:107], v[136:139], v[194:197], v[104:107]
	v_mfma_f32_16x16x32_bf16 v[92:95], v[128:131], v[204:207], v[92:95]
	v_mfma_f32_16x16x32_bf16 v[88:91], v[136:139], v[204:207], v[88:91]
	v_mfma_f32_16x16x32_bf16 v[76:79], v[128:131], v[212:215], v[76:79]
	v_mfma_f32_16x16x32_bf16 v[72:75], v[136:139], v[212:215], v[72:75]
	v_mfma_f32_16x16x32_bf16 v[124:127], v[132:135], v[180:183], v[124:127]
	v_mfma_f32_16x16x32_bf16 v[120:123], v[140:143], v[180:183], v[120:123]
	v_mfma_f32_16x16x32_bf16 v[108:111], v[132:135], v[200:203], v[108:111]
	v_mfma_f32_16x16x32_bf16 v[104:107], v[140:143], v[200:203], v[104:107]
	v_mfma_f32_16x16x32_bf16 v[92:95], v[132:135], v[208:211], v[92:95]
	v_mfma_f32_16x16x32_bf16 v[88:91], v[140:143], v[208:211], v[88:91]
	v_mfma_f32_16x16x32_bf16 v[76:79], v[132:135], v[216:219], v[76:79]
	v_mfma_f32_16x16x32_bf16 v[72:75], v[140:143], v[216:219], v[72:75]
	v_mfma_f32_16x16x32_bf16 v[116:119], v[144:147], v[176:179], v[116:119]
	v_mfma_f32_16x16x32_bf16 v[112:115], v[168:171], v[176:179], v[112:115]
	v_mfma_f32_16x16x32_bf16 v[100:103], v[144:147], v[194:197], v[100:103]
	v_mfma_f32_16x16x32_bf16 v[96:99], v[168:171], v[194:197], v[96:99]
	v_mfma_f32_16x16x32_bf16 v[84:87], v[144:147], v[204:207], v[84:87]
	v_mfma_f32_16x16x32_bf16 v[80:83], v[168:171], v[204:207], v[80:83]
	v_mfma_f32_16x16x32_bf16 v[68:71], v[144:147], v[212:215], v[68:71]
	v_mfma_f32_16x16x32_bf16 v[64:67], v[168:171], v[212:215], v[64:67]
	v_mfma_f32_16x16x32_bf16 v[116:119], v[148:151], v[180:183], v[116:119]
	v_mfma_f32_16x16x32_bf16 v[112:115], v[172:175], v[180:183], v[112:115]
	v_mfma_f32_16x16x32_bf16 v[100:103], v[148:151], v[200:203], v[100:103]
	v_mfma_f32_16x16x32_bf16 v[96:99], v[172:175], v[200:203], v[96:99]
	v_mfma_f32_16x16x32_bf16 v[84:87], v[148:151], v[208:211], v[84:87]
	v_mfma_f32_16x16x32_bf16 v[80:83], v[172:175], v[208:211], v[80:83]
	v_mfma_f32_16x16x32_bf16 v[68:71], v[148:151], v[216:219], v[68:71]
	v_mfma_f32_16x16x32_bf16 v[64:67], v[172:175], v[216:219], v[64:67]
	s_barrier
; #define PG8_STAGE(bufoff, gbase, voff) do { _Pragma("unroll") for (int _i = 0; _i < 2; ++_i) \
;         __builtin_amdgcn_global_load_lds((const unsigned*)((const char*)(gbase) + (voff)[_i]), (PG8_LAS unsigned*)(lds + (bufoff) + ldsw + _i * 8192), 16, 0, 0); } while (0)
; #define PG8_LDA(dst, b, h) do { _Pragma("unroll") for (int m = 0; m < 4; ++m) _Pragma("unroll") for (int k = 0; k < 2; ++k) dst[m][k] = *(const PG8_LAS bf16x8*)(lds + PG8_SA(b, h) + aoff + m * 2048 + k * 1024); } while (0)
; #define PG8_MMA(ai, bj, At, Bt) do { __builtin_amdgcn_s_setprio(1); _Pragma("unroll") for (int m = 0; m < 4; ++m) _Pragma("unroll") for (int n = 0; n < 2; ++n) _Pragma("unroll") for (int k = 0; k < 2; ++k) \
;         acc[ai][bj][m][n] = __builtin_amdgcn_mfma_f32_16x16x32_bf16(Bt[n][k], At[m][k], acc[ai][bj][m][n], 0, 0, 0); __builtin_amdgcn_s_setprio(0); } while (0)
; #define PG8_WAIT_V(n) asm volatile("s_waitcnt vmcnt(" #n ")" ::: "memory")
; #define PG8_WAIT_L(n) asm volatile("s_waitcnt lgkmcnt(" #n ")" ::: "memory")
; #define PG8_BAR __builtin_amdgcn_s_barrier()
; #define PG8_SCHED __builtin_amdgcn_sched_barrier(0)
; template <class Epi, class Sched, bool ALIGN_EPI = false, bool SP2 = false, bool ATILED = false>
; __device__ __forceinline__ void gemm_phase(PG8_LAS unsigned char* lds, const Gemm g, const Sched& S, const Epi& E) {
;     ...
;         for (int t = 0; t < nt; t += 2) {
;             const bool last = (t == nt - 2);
;             const char* a1 = cA + (size_t)(t + 1) * kstepA;
;             const char* a2 = last ? nA : cA + (size_t)(t + 2) * kstepA; const char* b2 = last ? nB : cB + (size_t)(t + 2) * kstep;
;             const char* a3 = a2 + kstepA; const char* b3 = b2 + kstep;
;             if (last && has_next) S.a_ready(nxt);
;     ...
;             PG8_LDA(At, 1, 1); PG8_STAGE(PG8_SB(1, 0), b3, voffB); PG8_STAGE(PG8_SB(1, 1), b3 + hstep, voffB); PG8_STAGE(PG8_SA(1, 0), a3, voffA);
;             PG8_WAIT_V(8); PG8_WAIT_L(0); PG8_BAR; PG8_MMA(1, 0, At, B0); PG8_MMA(1, 1, At, B1); PG8_BAR; PG8_SCHED;
	s_add_i32 s56, s74, s29
	v_lshl_add_u64 v[184:185], v[184:185], 0, s[12:13]
	s_mov_b32 m0, s56
	ds_read_b128 v[176:179], v191 offset:49152
	ds_read_b128 v[180:183], v191 offset:50176
	ds_read_b128 v[194:197], v191 offset:51200
	ds_read_b128 v[200:203], v191 offset:52224
	ds_read_b128 v[204:207], v191 offset:53248
	ds_read_b128 v[208:211], v191 offset:54272
	ds_read_b128 v[212:215], v191 offset:55296
	ds_read_b128 v[216:219], v191 offset:56320
	global_load_lds_dwordx4 v[184:185], off
	s_add_i32 m0, s56, 0x2000
	s_add_u32 s54, s54, 0x40080
	v_lshl_add_u64 v[184:185], v[220:221], 0, s[12:13]
	s_addc_u32 s55, s55, 0
	s_add_i32 s56, s75, s29
	global_load_lds_dwordx4 v[184:185], off
	v_lshl_add_u64 v[184:185], s[54:55], 0, v[154:155]
	s_mov_b32 m0, s56
	s_nop 0
	global_load_lds_dwordx4 v[184:185], off
	v_lshl_add_u64 v[184:185], s[54:55], 0, v[158:159]
	s_add_i32 m0, s56, 0x2000
	s_nop 0
	global_load_lds_dwordx4 v[184:185], off
	v_lshl_add_u64 v[184:185], v[222:223], 0, s[12:13]
	s_mov_b32 m0, s63
	s_nop 0
	global_load_lds_dwordx4 v[184:185], off
	v_lshl_add_u64 v[184:185], v[224:225], 0, s[12:13]
	s_mov_b32 m0, s64
	s_nop 0
	global_load_lds_dwordx4 v[184:185], off
	s_waitcnt vmcnt(8)
	s_waitcnt lgkmcnt(0)
	s_barrier
	s_waitcnt lgkmcnt(0)
	v_mfma_f32_16x16x32_bf16 v[60:63], v[128:131], v[176:179], v[60:63]
	v_mfma_f32_16x16x32_bf16 v[56:59], v[136:139], v[176:179], v[56:59]
	v_mfma_f32_16x16x32_bf16 v[44:47], v[128:131], v[194:197], v[44:47]
	v_mfma_f32_16x16x32_bf16 v[40:43], v[136:139], v[194:197], v[40:43]
	v_mfma_f32_16x16x32_bf16 v[28:31], v[128:131], v[204:207], v[28:31]
	v_mfma_f32_16x16x32_bf16 v[24:27], v[136:139], v[204:207], v[24:27]
	v_mfma_f32_16x16x32_bf16 v[12:15], v[128:131], v[212:215], v[12:15]
	v_mfma_f32_16x16x32_bf16 v[8:11], v[136:139], v[212:215], v[8:11]
	v_mfma_f32_16x16x32_bf16 v[60:63], v[132:135], v[180:183], v[60:63]
	v_mfma_f32_16x16x32_bf16 v[56:59], v[140:143], v[180:183], v[56:59]
	v_mfma_f32_16x16x32_bf16 v[44:47], v[132:135], v[200:203], v[44:47]
	v_mfma_f32_16x16x32_bf16 v[40:43], v[140:143], v[200:203], v[40:43]
	v_mfma_f32_16x16x32_bf16 v[28:31], v[132:135], v[208:211], v[28:31]
	v_mfma_f32_16x16x32_bf16 v[24:27], v[140:143], v[208:211], v[24:27]
	v_mfma_f32_16x16x32_bf16 v[12:15], v[132:135], v[216:219], v[12:15]
	v_mfma_f32_16x16x32_bf16 v[8:11], v[140:143], v[216:219], v[8:11]
	v_mfma_f32_16x16x32_bf16 v[52:55], v[144:147], v[176:179], v[52:55]
	v_mfma_f32_16x16x32_bf16 v[48:51], v[168:171], v[176:179], v[48:51]
	v_mfma_f32_16x16x32_bf16 v[36:39], v[144:147], v[194:197], v[36:39]
	v_mfma_f32_16x16x32_bf16 v[32:35], v[168:171], v[194:197], v[32:35]
	v_mfma_f32_16x16x32_bf16 v[20:23], v[144:147], v[204:207], v[20:23]
	v_mfma_f32_16x16x32_bf16 v[16:19], v[168:171], v[204:207], v[16:19]
	v_mfma_f32_16x16x32_bf16 v[4:7], v[144:147], v[212:215], v[4:7]
	v_mfma_f32_16x16x32_bf16 v[0:3], v[168:171], v[212:215], v[0:3]
	v_mfma_f32_16x16x32_bf16 v[52:55], v[148:151], v[180:183], v[52:55]
	v_mfma_f32_16x16x32_bf16 v[48:51], v[172:175], v[180:183], v[48:51]
	v_mfma_f32_16x16x32_bf16 v[36:39], v[148:151], v[200:203], v[36:39]
	v_mfma_f32_16x16x32_bf16 v[32:35], v[172:175], v[200:203], v[32:35]
	v_mfma_f32_16x16x32_bf16 v[20:23], v[148:151], v[208:211], v[20:23]
	v_mfma_f32_16x16x32_bf16 v[16:19], v[172:175], v[208:211], v[16:19]
	v_mfma_f32_16x16x32_bf16 v[4:7], v[148:151], v[216:219], v[4:7]
	v_mfma_f32_16x16x32_bf16 v[0:3], v[172:175], v[216:219], v[0:3]
	s_barrier
	s_add_i32 s73, s73, 2
	s_add_u32 s50, s50, 0x100
	s_addc_u32 s51, s51, 0
	s_add_u32 s71, s71, 0x100
	s_addc_u32 s72, s72, 0
	s_cmp_gt_u32 s73, 13
	s_cbranch_scc0 .LBB0_735
	s_and_b64 vcc, exec, s[14:15]
	s_cbranch_vccz .LBB0_738
	s_barrier

; #define PG8_STAGE(bufoff, gbase, voff) do { _Pragma("unroll") for (int _i = 0; _i < 2; ++_i) \
;         __builtin_amdgcn_global_load_lds((const unsigned*)((const char*)(gbase) + (voff)[_i]), (PG8_LAS unsigned*)(lds + (bufoff) + ldsw + _i * 8192), 16, 0, 0); } while (0)
; #define PG8_LDA(dst, b, h) do { _Pragma("unroll") for (int m = 0; m < 4; ++m) _Pragma("unroll") for (int k = 0; k < 2; ++k) dst[m][k] = *(const PG8_LAS bf16x8*)(lds + PG8_SA(b, h) + aoff + m * 2048 + k * 1024); } while (0)
; #define PG8_LDB(dst, b, h) do { _Pragma("unroll") for (int n = 0; n < 2; ++n) _Pragma("unroll") for (int k = 0; k < 2; ++k) dst[n][k] = *(const PG8_LAS bf16x8*)(lds + PG8_SB(b, h) + boff + n * 2048 + k * 1024); } while (0)
; #define PG8_MMA(ai, bj, At, Bt) do { __builtin_amdgcn_s_setprio(1); _Pragma("unroll") for (int m = 0; m < 4; ++m) _Pragma("unroll") for (int n = 0; n < 2; ++n) _Pragma("unroll") for (int k = 0; k < 2; ++k) \
;         acc[ai][bj][m][n] = __builtin_amdgcn_mfma_f32_16x16x32_bf16(Bt[n][k], At[m][k], acc[ai][bj][m][n], 0, 0, 0); __builtin_amdgcn_s_setprio(0); } while (0)
; #define PG8_WAIT_V(n) asm volatile("s_waitcnt vmcnt(" #n ")" ::: "memory")
; #define PG8_WAIT_L(n) asm volatile("s_waitcnt lgkmcnt(" #n ")" ::: "memory")
; #define PG8_BAR __builtin_amdgcn_s_barrier()
; #define PG8_SCHED __builtin_amdgcn_sched_barrier(0)
; template <class Epi, class Sched, bool ALIGN_EPI = false, bool SP2 = false, bool ATILED = false>
; __device__ __forceinline__ void gemm_phase(PG8_LAS unsigned char* lds, const Gemm g, const Sched& S, const Epi& E) {
;     ...
;             PG8_LDB(B0, 0, 0); PG8_LDB(B1, 0, 1); PG8_SCHED; PG8_LDA(At, 0, 0); PG8_STAGE(PG8_SA(1, 1), a1 + hstepA, voffA);
;             PG8_WAIT_V(8); PG8_WAIT_L(0); PG8_BAR; PG8_MMA(0, 0, At, B0); PG8_MMA(0, 1, At, B1); PG8_BAR; PG8_SCHED;
;             PG8_LDA(At, 0, 1); PG8_STAGE(PG8_SB(0, 0), b2, voffB); PG8_STAGE(PG8_SB(0, 1), b2 + hstep, voffB); PG8_STAGE(PG8_SA(0, 0), a2, voffA);
.LBB0_817:
	ds_read_b128 v[150:153], v156
	ds_read_b128 v[162:165], v156 offset:1024
	ds_read_b128 v[166:169], v156 offset:2048
	ds_read_b128 v[170:173], v156 offset:3072
	ds_read_b128 v[174:177], v157
	ds_read_b128 v[178:181], v157 offset:1024
	ds_read_b128 v[182:185], v157 offset:2048
	ds_read_b128 v[186:189], v157 offset:3072
	s_add_u32 s42, s20, 0xfffc0080
	s_addc_u32 s43, s21, -1
	s_cmp_eq_u32 s68, 12
	s_cselect_b32 s45, s13, s43
	s_cselect_b32 s44, s64, s42
	s_cselect_b32 s43, s11, s67
	s_cselect_b32 s42, s65, s66
	v_lshl_add_u64 v[224:225], s[20:21], 0, v[140:141]
	s_add_i32 m0, s19, 0xc000
	ds_read_b128 v[190:193], v158
	ds_read_b128 v[194:197], v158 offset:1024
	ds_read_b128 v[200:203], v158 offset:2048
	ds_read_b128 v[204:207], v158 offset:3072
	ds_read_b128 v[208:211], v158 offset:4096
	ds_read_b128 v[212:215], v158 offset:5120
	ds_read_b128 v[216:219], v158 offset:6144
	ds_read_b128 v[220:223], v158 offset:7168
	global_load_lds_dwordx4 v[224:225], off
	v_lshl_add_u64 v[224:225], s[20:21], 0, v[142:143]
	s_add_i32 m0, s19, 0xe000
	s_nop 0
	global_load_lds_dwordx4 v[224:225], off
	s_waitcnt vmcnt(8)
	s_waitcnt lgkmcnt(0)
	s_barrier
	s_waitcnt lgkmcnt(0)
	v_mfma_f32_16x16x32_bf16 v[124:127], v[150:153], v[190:193], v[124:127]
	v_mfma_f32_16x16x32_bf16 v[120:123], v[166:169], v[190:193], v[120:123]
	v_mfma_f32_16x16x32_bf16 v[108:111], v[150:153], v[200:203], v[108:111]
	v_mfma_f32_16x16x32_bf16 v[104:107], v[166:169], v[200:203], v[104:107]
	v_mfma_f32_16x16x32_bf16 v[92:95], v[150:153], v[208:211], v[92:95]
	v_mfma_f32_16x16x32_bf16 v[88:91], v[166:169], v[208:211], v[88:91]
	v_mfma_f32_16x16x32_bf16 v[76:79], v[150:153], v[216:219], v[76:79]
	v_mfma_f32_16x16x32_bf16 v[72:75], v[166:169], v[216:219], v[72:75]
	v_mfma_f32_16x16x32_bf16 v[124:127], v[162:165], v[194:197], v[124:127]
	v_mfma_f32_16x16x32_bf16 v[120:123], v[170:173], v[194:197], v[120:123]
	v_mfma_f32_16x16x32_bf16 v[108:111], v[162:165], v[204:207], v[108:111]
	v_mfma_f32_16x16x32_bf16 v[104:107], v[170:173], v[204:207], v[104:107]
	v_mfma_f32_16x16x32_bf16 v[92:95], v[162:165], v[212:215], v[92:95]
	v_mfma_f32_16x16x32_bf16 v[88:91], v[170:173], v[212:215], v[88:91]
	v_mfma_f32_16x16x32_bf16 v[76:79], v[162:165], v[220:223], v[76:79]
	v_mfma_f32_16x16x32_bf16 v[72:75], v[170:173], v[220:223], v[72:75]
	v_mfma_f32_16x16x32_bf16 v[116:119], v[174:177], v[190:193], v[116:119]
	v_mfma_f32_16x16x32_bf16 v[112:115], v[182:185], v[190:193], v[112:115]
	v_mfma_f32_16x16x32_bf16 v[100:103], v[174:177], v[200:203], v[100:103]
	v_mfma_f32_16x16x32_bf16 v[96:99], v[182:185], v[200:203], v[96:99]
	v_mfma_f32_16x16x32_bf16 v[84:87], v[174:177], v[208:211], v[84:87]
	v_mfma_f32_16x16x32_bf16 v[80:83], v[182:185], v[208:211], v[80:83]
	v_mfma_f32_16x16x32_bf16 v[68:71], v[174:177], v[216:219], v[68:71]
	v_mfma_f32_16x16x32_bf16 v[64:67], v[182:185], v[216:219], v[64:67]
	v_mfma_f32_16x16x32_bf16 v[116:119], v[178:181], v[194:197], v[116:119]
	v_mfma_f32_16x16x32_bf16 v[112:115], v[186:189], v[194:197], v[112:115]
	v_mfma_f32_16x16x32_bf16 v[100:103], v[178:181], v[204:207], v[100:103]
	v_mfma_f32_16x16x32_bf16 v[96:99], v[186:189], v[204:207], v[96:99]
	v_mfma_f32_16x16x32_bf16 v[84:87], v[178:181], v[212:215], v[84:87]
	v_mfma_f32_16x16x32_bf16 v[80:83], v[186:189], v[212:215], v[80:83]
	v_mfma_f32_16x16x32_bf16 v[68:71], v[178:181], v[220:223], v[68:71]
	v_mfma_f32_16x16x32_bf16 v[64:67], v[186:189], v[220:223], v[64:67]
	s_barrier
	s_add_i32 s69, s60, s46
	v_lshl_add_u64 v[224:225], s[42:43], 0, v[130:131]
	s_mov_b32 m0, s69
	ds_read_b128 v[190:193], v158 offset:16384
	ds_read_b128 v[194:197], v158 offset:17408
	ds_read_b128 v[200:203], v158 offset:18432
	ds_read_b128 v[204:207], v158 offset:19456
	ds_read_b128 v[208:211], v158 offset:20480
	ds_read_b128 v[212:215], v158 offset:21504
	ds_read_b128 v[216:219], v158 offset:22528
	ds_read_b128 v[220:223], v158 offset:23552
	global_load_lds_dwordx4 v[224:225], off
	s_add_i32 m0, s69, 0x2000
	s_add_u32 s70, s42, 0x40000
	v_lshl_add_u64 v[226:227], s[42:43], 0, v[134:135]
	s_addc_u32 s71, s43, 0
	s_add_i32 s69, s61, s46
	global_load_lds_dwordx4 v[226:227], off
	v_lshl_add_u64 v[228:229], s[70:71], 0, v[130:131]
	s_mov_b32 m0, s69
	v_lshl_add_u64 v[230:231], s[44:45], 0, v[132:133]
	global_load_lds_dwordx4 v[228:229], off
	v_lshl_add_u64 v[228:229], s[70:71], 0, v[134:135]
	s_add_i32 m0, s69, 0x2000
	s_nop 0
	global_load_lds_dwordx4 v[228:229], off
	v_lshl_add_u64 v[228:229], s[44:45], 0, v[128:129]
	s_mov_b32 m0, s19
	s_nop 0
	global_load_lds_dwordx4 v[228:229], off
	s_mov_b32 m0, s48
	s_nop 0
	global_load_lds_dwordx4 v[230:231], off
	s_waitcnt vmcnt(8)
	s_waitcnt lgkmcnt(0)
	s_barrier
; #define PG8_STAGE(bufoff, gbase, voff) do { _Pragma("unroll") for (int _i = 0; _i < 2; ++_i) \
;         __builtin_amdgcn_global_load_lds((const unsigned*)((const char*)(gbase) + (voff)[_i]), (PG8_LAS unsigned*)(lds + (bufoff) + ldsw + _i * 8192), 16, 0, 0); } while (0)
; #define PG8_LDA(dst, b, h) do { _Pragma("unroll") for (int m = 0; m < 4; ++m) _Pragma("unroll") for (int k = 0; k < 2; ++k) dst[m][k] = *(const PG8_LAS bf16x8*)(lds + PG8_SA(b, h) + aoff + m * 2048 + k * 1024); } while (0)
; #define PG8_LDB(dst, b, h) do { _Pragma("unroll") for (int n = 0; n < 2; ++n) _Pragma("unroll") for (int k = 0; k < 2; ++k) dst[n][k] = *(const PG8_LAS bf16x8*)(lds + PG8_SB(b, h) + boff + n * 2048 + k * 1024); } while (0)
; #define PG8_MMA(ai, bj, At, Bt) do { __builtin_amdgcn_s_setprio(1); _Pragma("unroll") for (int m = 0; m < 4; ++m) _Pragma("unroll") for (int n = 0; n < 2; ++n) _Pragma("unroll") for (int k = 0; k < 2; ++k) \
;         acc[ai][bj][m][n] = __builtin_amdgcn_mfma_f32_16x16x32_bf16(Bt[n][k], At[m][k], acc[ai][bj][m][n], 0, 0, 0); __builtin_amdgcn_s_setprio(0); } while (0)
; #define PG8_WAIT_V(n) asm volatile("s_waitcnt vmcnt(" #n ")" ::: "memory")
; #define PG8_WAIT_L(n) asm volatile("s_waitcnt lgkmcnt(" #n ")" ::: "memory")
; #define PG8_BAR __builtin_amdgcn_s_barrier()
; #define PG8_SCHED __builtin_amdgcn_sched_barrier(0)
; template <class Epi, class Sched, bool ALIGN_EPI = false, bool SP2 = false, bool ATILED = false>
; __device__ __forceinline__ void gemm_phase(PG8_LAS unsigned char* lds, const Gemm g, const Sched& S, const Epi& E) {
;     ...
;             PG8_WAIT_V(8); PG8_WAIT_L(0); PG8_BAR; PG8_MMA(1, 0, At, B0); PG8_MMA(1, 1, At, B1); PG8_BAR; PG8_SCHED;
;             PG8_LDB(B0, 1, 0); PG8_LDB(B1, 1, 1); PG8_SCHED; PG8_LDA(At, 1, 0); PG8_STAGE(PG8_SA(0, 1), a2 + hstepA, voffA);
;             PG8_WAIT_V(8); PG8_WAIT_L(0); PG8_BAR; PG8_MMA(0, 0, At, B0); PG8_MMA(0, 1, At, B1); PG8_BAR; PG8_SCHED;
	s_waitcnt lgkmcnt(0)
	v_mfma_f32_16x16x32_bf16 v[60:63], v[150:153], v[190:193], v[60:63]
	v_mfma_f32_16x16x32_bf16 v[56:59], v[166:169], v[190:193], v[56:59]
	v_mfma_f32_16x16x32_bf16 v[44:47], v[150:153], v[200:203], v[44:47]
	v_mfma_f32_16x16x32_bf16 v[40:43], v[166:169], v[200:203], v[40:43]
	v_mfma_f32_16x16x32_bf16 v[28:31], v[150:153], v[208:211], v[28:31]
	v_mfma_f32_16x16x32_bf16 v[24:27], v[166:169], v[208:211], v[24:27]
	v_mfma_f32_16x16x32_bf16 v[12:15], v[150:153], v[216:219], v[12:15]
	v_mfma_f32_16x16x32_bf16 v[8:11], v[166:169], v[216:219], v[8:11]
	v_mfma_f32_16x16x32_bf16 v[60:63], v[162:165], v[194:197], v[60:63]
	v_mfma_f32_16x16x32_bf16 v[56:59], v[170:173], v[194:197], v[56:59]
	v_mfma_f32_16x16x32_bf16 v[44:47], v[162:165], v[204:207], v[44:47]
	v_mfma_f32_16x16x32_bf16 v[40:43], v[170:173], v[204:207], v[40:43]
	v_mfma_f32_16x16x32_bf16 v[28:31], v[162:165], v[212:215], v[28:31]
	v_mfma_f32_16x16x32_bf16 v[24:27], v[170:173], v[212:215], v[24:27]
	v_mfma_f32_16x16x32_bf16 v[12:15], v[162:165], v[220:223], v[12:15]
	v_mfma_f32_16x16x32_bf16 v[8:11], v[170:173], v[220:223], v[8:11]
	v_mfma_f32_16x16x32_bf16 v[52:55], v[174:177], v[190:193], v[52:55]
	v_mfma_f32_16x16x32_bf16 v[48:51], v[182:185], v[190:193], v[48:51]
	v_mfma_f32_16x16x32_bf16 v[36:39], v[174:177], v[200:203], v[36:39]
	v_mfma_f32_16x16x32_bf16 v[32:35], v[182:185], v[200:203], v[32:35]
	v_mfma_f32_16x16x32_bf16 v[20:23], v[174:177], v[208:211], v[20:23]
	v_mfma_f32_16x16x32_bf16 v[16:19], v[182:185], v[208:211], v[16:19]
	v_mfma_f32_16x16x32_bf16 v[4:7], v[174:177], v[216:219], v[4:7]
	v_mfma_f32_16x16x32_bf16 v[0:3], v[182:185], v[216:219], v[0:3]
	v_mfma_f32_16x16x32_bf16 v[52:55], v[178:181], v[194:197], v[52:55]
	v_mfma_f32_16x16x32_bf16 v[48:51], v[186:189], v[194:197], v[48:51]
	v_mfma_f32_16x16x32_bf16 v[36:39], v[178:181], v[204:207], v[36:39]
	v_mfma_f32_16x16x32_bf16 v[32:35], v[186:189], v[204:207], v[32:35]
	v_mfma_f32_16x16x32_bf16 v[20:23], v[178:181], v[212:215], v[20:23]
	v_mfma_f32_16x16x32_bf16 v[16:19], v[186:189], v[212:215], v[16:19]
	v_mfma_f32_16x16x32_bf16 v[4:7], v[178:181], v[220:223], v[4:7]
	v_mfma_f32_16x16x32_bf16 v[0:3], v[186:189], v[220:223], v[0:3]
	s_barrier
	s_add_i32 s69, 0, 0x18000
	v_add_u32_e32 v136, s69, v155
	s_add_i32 s70, 0, 0x1c000
	ds_read_b128 v[150:153], v136
	ds_read_b128 v[162:165], v136 offset:1024
	ds_read_b128 v[166:169], v136 offset:2048
	ds_read_b128 v[170:173], v136 offset:3072
	v_add_u32_e32 v136, s70, v155
	ds_read_b128 v[174:177], v136
	ds_read_b128 v[178:181], v136 offset:1024
	ds_read_b128 v[182:185], v136 offset:2048
	ds_read_b128 v[186:189], v136 offset:3072
	s_add_u32 s44, s44, 0x40000
	s_addc_u32 s45, s45, 0
	s_mov_b32 m0, s49
	v_lshl_add_u64 v[232:233], s[44:45], 0, v[128:129]
	ds_read_b128 v[190:193], v158 offset:32768
	ds_read_b128 v[194:197], v158 offset:33792
	ds_read_b128 v[200:203], v158 offset:34816
	ds_read_b128 v[204:207], v158 offset:35840
	ds_read_b128 v[208:211], v158 offset:36864
	ds_read_b128 v[212:215], v158 offset:37888
	ds_read_b128 v[216:219], v158 offset:38912
	ds_read_b128 v[220:223], v158 offset:39936
	global_load_lds_dwordx4 v[232:233], off
	v_lshl_add_u64 v[232:233], s[44:45], 0, v[132:133]
	s_mov_b32 m0, s50
	s_nop 0
	global_load_lds_dwordx4 v[232:233], off
	s_waitcnt vmcnt(8)
	s_waitcnt lgkmcnt(0)
	s_barrier
	s_waitcnt lgkmcnt(0)
	v_mfma_f32_16x16x32_bf16 v[124:127], v[150:153], v[190:193], v[124:127]
	v_mfma_f32_16x16x32_bf16 v[120:123], v[166:169], v[190:193], v[120:123]
	v_mfma_f32_16x16x32_bf16 v[108:111], v[150:153], v[200:203], v[108:111]
	v_mfma_f32_16x16x32_bf16 v[104:107], v[166:169], v[200:203], v[104:107]
	v_mfma_f32_16x16x32_bf16 v[92:95], v[150:153], v[208:211], v[92:95]
	v_mfma_f32_16x16x32_bf16 v[88:91], v[166:169], v[208:211], v[88:91]
	v_mfma_f32_16x16x32_bf16 v[76:79], v[150:153], v[216:219], v[76:79]
	v_mfma_f32_16x16x32_bf16 v[72:75], v[166:169], v[216:219], v[72:75]
	v_mfma_f32_16x16x32_bf16 v[124:127], v[162:165], v[194:197], v[124:127]
	v_mfma_f32_16x16x32_bf16 v[120:123], v[170:173], v[194:197], v[120:123]
	v_mfma_f32_16x16x32_bf16 v[108:111], v[162:165], v[204:207], v[108:111]
	v_mfma_f32_16x16x32_bf16 v[104:107], v[170:173], v[204:207], v[104:107]
	v_mfma_f32_16x16x32_bf16 v[92:95], v[162:165], v[212:215], v[92:95]
	v_mfma_f32_16x16x32_bf16 v[88:91], v[170:173], v[212:215], v[88:91]
	v_mfma_f32_16x16x32_bf16 v[76:79], v[162:165], v[220:223], v[76:79]
	v_mfma_f32_16x16x32_bf16 v[72:75], v[170:173], v[220:223], v[72:75]
	v_mfma_f32_16x16x32_bf16 v[116:119], v[174:177], v[190:193], v[116:119]
	v_mfma_f32_16x16x32_bf16 v[112:115], v[182:185], v[190:193], v[112:115]
	v_mfma_f32_16x16x32_bf16 v[100:103], v[174:177], v[200:203], v[100:103]
	v_mfma_f32_16x16x32_bf16 v[96:99], v[182:185], v[200:203], v[96:99]
	v_mfma_f32_16x16x32_bf16 v[84:87], v[174:177], v[208:211], v[84:87]
	v_mfma_f32_16x16x32_bf16 v[80:83], v[182:185], v[208:211], v[80:83]
	v_mfma_f32_16x16x32_bf16 v[68:71], v[174:177], v[216:219], v[68:71]
	v_mfma_f32_16x16x32_bf16 v[64:67], v[182:185], v[216:219], v[64:67]
	v_mfma_f32_16x16x32_bf16 v[116:119], v[178:181], v[194:197], v[116:119]
	v_mfma_f32_16x16x32_bf16 v[112:115], v[186:189], v[194:197], v[112:115]
	v_mfma_f32_16x16x32_bf16 v[100:103], v[178:181], v[204:207], v[100:103]
	v_mfma_f32_16x16x32_bf16 v[96:99], v[186:189], v[204:207], v[96:99]
	v_mfma_f32_16x16x32_bf16 v[84:87], v[178:181], v[212:215], v[84:87]
	v_mfma_f32_16x16x32_bf16 v[80:83], v[186:189], v[212:215], v[80:83]
	v_mfma_f32_16x16x32_bf16 v[68:71], v[178:181], v[220:223], v[68:71]
	v_mfma_f32_16x16x32_bf16 v[64:67], v[186:189], v[220:223], v[64:67]
	s_barrier
; #define PG8_STAGE(bufoff, gbase, voff) do { _Pragma("unroll") for (int _i = 0; _i < 2; ++_i) \
;         __builtin_amdgcn_global_load_lds((const unsigned*)((const char*)(gbase) + (voff)[_i]), (PG8_LAS unsigned*)(lds + (bufoff) + ldsw + _i * 8192), 16, 0, 0); } while (0)
; #define PG8_LDA(dst, b, h) do { _Pragma("unroll") for (int m = 0; m < 4; ++m) _Pragma("unroll") for (int k = 0; k < 2; ++k) dst[m][k] = *(const PG8_LAS bf16x8*)(lds + PG8_SA(b, h) + aoff + m * 2048 + k * 1024); } while (0)
; #define PG8_MMA(ai, bj, At, Bt) do { __builtin_amdgcn_s_setprio(1); _Pragma("unroll") for (int m = 0; m < 4; ++m) _Pragma("unroll") for (int n = 0; n < 2; ++n) _Pragma("unroll") for (int k = 0; k < 2; ++k) \
;         acc[ai][bj][m][n] = __builtin_amdgcn_mfma_f32_16x16x32_bf16(Bt[n][k], At[m][k], acc[ai][bj][m][n], 0, 0, 0); __builtin_amdgcn_s_setprio(0); } while (0)
; #define PG8_WAIT_V(n) asm volatile("s_waitcnt vmcnt(" #n ")" ::: "memory")
; #define PG8_WAIT_L(n) asm volatile("s_waitcnt lgkmcnt(" #n ")" ::: "memory")
; #define PG8_BAR __builtin_amdgcn_s_barrier()
; #define PG8_SCHED __builtin_amdgcn_sched_barrier(0)
; template <class Epi, class Sched, bool ALIGN_EPI = false, bool SP2 = false, bool ATILED = false>
; __device__ __forceinline__ void gemm_phase(PG8_LAS unsigned char* lds, const Gemm g, const Sched& S, const Epi& E) {
;     ...
;         for (int t = 0; t < nt; t += 2) {
;             const bool last = (t == nt - 2);
;             const char* a1 = cA + (size_t)(t + 1) * kstepA;
;             const char* a2 = last ? nA : cA + (size_t)(t + 2) * kstepA; const char* b2 = last ? nB : cB + (size_t)(t + 2) * kstep;
;             const char* a3 = a2 + kstepA; const char* b3 = b2 + kstep;
;             if (last && has_next) S.a_ready(nxt);
;     ...
;             PG8_LDA(At, 1, 1); PG8_STAGE(PG8_SB(1, 0), b3, voffB); PG8_STAGE(PG8_SB(1, 1), b3 + hstep, voffB); PG8_STAGE(PG8_SA(1, 0), a3, voffA);
;             PG8_WAIT_V(8); PG8_WAIT_L(0); PG8_BAR; PG8_MMA(1, 0, At, B0); PG8_MMA(1, 1, At, B1); PG8_BAR; PG8_SCHED;
	s_add_i32 s44, s69, s46
	v_lshl_add_u64 v[224:225], v[224:225], 0, s[6:7]
	s_mov_b32 m0, s44
	ds_read_b128 v[190:193], v158 offset:49152
	ds_read_b128 v[194:197], v158 offset:50176
	ds_read_b128 v[200:203], v158 offset:51200
	ds_read_b128 v[204:207], v158 offset:52224
	ds_read_b128 v[208:211], v158 offset:53248
	ds_read_b128 v[212:215], v158 offset:54272
	ds_read_b128 v[216:219], v158 offset:55296
	ds_read_b128 v[220:223], v158 offset:56320
	global_load_lds_dwordx4 v[224:225], off
	s_add_i32 m0, s44, 0x2000
	s_add_u32 s42, s42, 0x40080
	v_lshl_add_u64 v[224:225], v[226:227], 0, s[6:7]
	s_addc_u32 s43, s43, 0
	s_add_i32 s44, s70, s46
	global_load_lds_dwordx4 v[224:225], off
	v_lshl_add_u64 v[224:225], s[42:43], 0, v[130:131]
	s_mov_b32 m0, s44
	s_nop 0
	global_load_lds_dwordx4 v[224:225], off
	v_lshl_add_u64 v[224:225], s[42:43], 0, v[134:135]
	s_add_i32 m0, s44, 0x2000
	s_nop 0
	global_load_lds_dwordx4 v[224:225], off
	v_lshl_add_u64 v[224:225], v[228:229], 0, s[6:7]
	s_mov_b32 m0, s58
	s_nop 0
	global_load_lds_dwordx4 v[224:225], off
	v_lshl_add_u64 v[224:225], v[230:231], 0, s[6:7]
	s_mov_b32 m0, s59
	s_nop 0
	global_load_lds_dwordx4 v[224:225], off
	s_waitcnt vmcnt(8)
	s_waitcnt lgkmcnt(0)
	s_barrier
	s_waitcnt lgkmcnt(0)
	v_mfma_f32_16x16x32_bf16 v[60:63], v[150:153], v[190:193], v[60:63]
	v_mfma_f32_16x16x32_bf16 v[56:59], v[166:169], v[190:193], v[56:59]
	v_mfma_f32_16x16x32_bf16 v[44:47], v[150:153], v[200:203], v[44:47]
	v_mfma_f32_16x16x32_bf16 v[40:43], v[166:169], v[200:203], v[40:43]
	v_mfma_f32_16x16x32_bf16 v[28:31], v[150:153], v[208:211], v[28:31]
	v_mfma_f32_16x16x32_bf16 v[24:27], v[166:169], v[208:211], v[24:27]
	v_mfma_f32_16x16x32_bf16 v[12:15], v[150:153], v[216:219], v[12:15]
	v_mfma_f32_16x16x32_bf16 v[8:11], v[166:169], v[216:219], v[8:11]
	v_mfma_f32_16x16x32_bf16 v[60:63], v[162:165], v[194:197], v[60:63]
	v_mfma_f32_16x16x32_bf16 v[56:59], v[170:173], v[194:197], v[56:59]
	v_mfma_f32_16x16x32_bf16 v[44:47], v[162:165], v[204:207], v[44:47]
	v_mfma_f32_16x16x32_bf16 v[40:43], v[170:173], v[204:207], v[40:43]
	v_mfma_f32_16x16x32_bf16 v[28:31], v[162:165], v[212:215], v[28:31]
	v_mfma_f32_16x16x32_bf16 v[24:27], v[170:173], v[212:215], v[24:27]
	v_mfma_f32_16x16x32_bf16 v[12:15], v[162:165], v[220:223], v[12:15]
	v_mfma_f32_16x16x32_bf16 v[8:11], v[170:173], v[220:223], v[8:11]
	v_mfma_f32_16x16x32_bf16 v[52:55], v[174:177], v[190:193], v[52:55]
	v_mfma_f32_16x16x32_bf16 v[48:51], v[182:185], v[190:193], v[48:51]
	v_mfma_f32_16x16x32_bf16 v[36:39], v[174:177], v[200:203], v[36:39]
	v_mfma_f32_16x16x32_bf16 v[32:35], v[182:185], v[200:203], v[32:35]
	v_mfma_f32_16x16x32_bf16 v[20:23], v[174:177], v[208:211], v[20:23]
	v_mfma_f32_16x16x32_bf16 v[16:19], v[182:185], v[208:211], v[16:19]
	v_mfma_f32_16x16x32_bf16 v[4:7], v[174:177], v[216:219], v[4:7]
	v_mfma_f32_16x16x32_bf16 v[0:3], v[182:185], v[216:219], v[0:3]
	v_mfma_f32_16x16x32_bf16 v[52:55], v[178:181], v[194:197], v[52:55]
	v_mfma_f32_16x16x32_bf16 v[48:51], v[186:189], v[194:197], v[48:51]
	v_mfma_f32_16x16x32_bf16 v[36:39], v[178:181], v[204:207], v[36:39]
	v_mfma_f32_16x16x32_bf16 v[32:35], v[186:189], v[204:207], v[32:35]
	v_mfma_f32_16x16x32_bf16 v[20:23], v[178:181], v[212:215], v[20:23]
	v_mfma_f32_16x16x32_bf16 v[16:19], v[186:189], v[212:215], v[16:19]
	v_mfma_f32_16x16x32_bf16 v[4:7], v[178:181], v[220:223], v[4:7]
	v_mfma_f32_16x16x32_bf16 v[0:3], v[186:189], v[220:223], v[0:3]
	s_barrier
	s_add_i32 s68, s68, 2
	s_add_u32 s20, s20, 0x100
	s_addc_u32 s21, s21, 0
	s_add_u32 s66, s66, 0x100
	s_addc_u32 s67, s67, 0
	s_cmp_gt_u32 s68, 13
	s_cbranch_scc0 .LBB0_817
	s_and_b64 vcc, exec, s[8:9]
	s_cbranch_vccz .LBB0_820
	s_barrier

; #define PG8_STAGE(bufoff, gbase, voff) do { _Pragma("unroll") for (int _i = 0; _i < 2; ++_i) \
;         __builtin_amdgcn_global_load_lds((const unsigned*)((const char*)(gbase) + (voff)[_i]), (PG8_LAS unsigned*)(lds + (bufoff) + ldsw + _i * 8192), 16, 0, 0); } while (0)
; #define PG8_LDA(dst, b, h) do { _Pragma("unroll") for (int m = 0; m < 4; ++m) _Pragma("unroll") for (int k = 0; k < 2; ++k) dst[m][k] = *(const PG8_LAS bf16x8*)(lds + PG8_SA(b, h) + aoff + m * 2048 + k * 1024); } while (0)
; #define PG8_LDB(dst, b, h) do { _Pragma("unroll") for (int n = 0; n < 2; ++n) _Pragma("unroll") for (int k = 0; k < 2; ++k) dst[n][k] = *(const PG8_LAS bf16x8*)(lds + PG8_SB(b, h) + boff + n * 2048 + k * 1024); } while (0)
; #define PG8_MMA(ai, bj, At, Bt) do { __builtin_amdgcn_s_setprio(1); _Pragma("unroll") for (int m = 0; m < 4; ++m) _Pragma("unroll") for (int n = 0; n < 2; ++n) _Pragma("unroll") for (int k = 0; k < 2; ++k) \
;         acc[ai][bj][m][n] = __builtin_amdgcn_mfma_f32_16x16x32_bf16(Bt[n][k], At[m][k], acc[ai][bj][m][n], 0, 0, 0); __builtin_amdgcn_s_setprio(0); } while (0)
; #define PG8_WAIT_V(n) asm volatile("s_waitcnt vmcnt(" #n ")" ::: "memory")
; #define PG8_WAIT_L(n) asm volatile("s_waitcnt lgkmcnt(" #n ")" ::: "memory")
; #define PG8_BAR __builtin_amdgcn_s_barrier()
; #define PG8_SCHED __builtin_amdgcn_sched_barrier(0)
; template <class Epi, class Sched, bool ALIGN_EPI = false, bool SP2 = false, bool ATILED = false>
; __device__ __forceinline__ void gemm_phase(PG8_LAS unsigned char* lds, const Gemm g, const Sched& S, const Epi& E) {
;     ...
;             const bool last = (t == nt - 2);
;             const char* a1 = cA + (size_t)(t + 1) * kstepA;
;             const char* a2 = last ? nA : cA + (size_t)(t + 2) * kstepA; const char* b2 = last ? nB : cB + (size_t)(t + 2) * kstep;
;             const char* a3 = a2 + kstepA; const char* b3 = b2 + kstep;
;             if (last && has_next) S.a_ready(nxt);
;             if constexpr (SP2) {
;             PG8_LDB(B0, 0, 0); PG8_LDB(B1, 0, 1); PG8_SCHED; PG8_LDA(At, 0, 0); PG8_STAGE(PG8_SA(1, 1), a1 + hstepA, voffA);
;             PG8_WAIT_V(8); PG8_WAIT_L(0); PG8_BAR; PG8_MMA(0, 0, At, B0); PG8_MMA(0, 1, At, B1); PG8_BAR; PG8_SCHED;
;             PG8_LDA(At, 0, 1); PG8_STAGE(PG8_SB(0, 0), b2, voffB); PG8_STAGE(PG8_SB(0, 1), b2 + hstep, voffB); PG8_STAGE(PG8_SA(0, 0), a2, voffA);
.LBB0_898:
	ds_read_b128 v[24:27], v210
	ds_read_b128 v[28:31], v210 offset:1024
	ds_read_b128 v[36:39], v210 offset:2048
	ds_read_b128 v[44:47], v210 offset:3072
	ds_read_b128 v[144:147], v211
	ds_read_b128 v[148:151], v211 offset:1024
	ds_read_b128 v[152:155], v211 offset:2048
	ds_read_b128 v[156:159], v211 offset:3072
	s_add_u32 s42, s40, 0x4000
	s_addc_u32 s43, s41, 0
	s_cmp_eq_u32 s63, 40
	s_cselect_b32 s46, s8, s42
	s_cselect_b32 s47, s9, s43
	s_cselect_b32 s44, s30, s35
	s_cselect_b32 s45, s31, s62
	s_add_u32 s42, s46, 0x8000
	s_addc_u32 s43, s47, 0
	v_lshl_add_u64 v[222:223], s[40:41], 0, v[176:177]
	s_add_i32 m0, s29, 0xc000
	ds_read_b128 v[160:163], v212
	ds_read_b128 v[164:167], v212 offset:1024
	ds_read_b128 v[184:187], v212 offset:2048
	ds_read_b128 v[188:191], v212 offset:3072
	ds_read_b128 v[192:195], v212 offset:4096
	ds_read_b128 v[196:199], v212 offset:5120
	ds_read_b128 v[200:203], v212 offset:6144
	ds_read_b128 v[218:221], v212 offset:7168
	global_load_lds_dwordx4 v[222:223], off
	v_lshl_add_u64 v[222:223], s[40:41], 0, v[178:179]
	s_add_i32 m0, s29, 0xe000
	s_nop 0
	global_load_lds_dwordx4 v[222:223], off
	s_waitcnt vmcnt(8)
	s_waitcnt lgkmcnt(0)
	s_barrier
	s_waitcnt lgkmcnt(0)
	v_mfma_f32_16x16x32_bf16 v[140:143], v[24:27], v[160:163], v[140:143]
	v_mfma_f32_16x16x32_bf16 v[136:139], v[36:39], v[160:163], v[136:139]
	v_mfma_f32_16x16x32_bf16 v[124:127], v[24:27], v[184:187], v[124:127]
	v_mfma_f32_16x16x32_bf16 v[120:123], v[36:39], v[184:187], v[120:123]
	v_mfma_f32_16x16x32_bf16 v[108:111], v[24:27], v[192:195], v[108:111]
	v_mfma_f32_16x16x32_bf16 v[104:107], v[36:39], v[192:195], v[104:107]
	v_mfma_f32_16x16x32_bf16 v[92:95], v[24:27], v[200:203], v[92:95]
	v_mfma_f32_16x16x32_bf16 v[88:91], v[36:39], v[200:203], v[88:91]
	v_mfma_f32_16x16x32_bf16 v[140:143], v[28:31], v[164:167], v[140:143]
	v_mfma_f32_16x16x32_bf16 v[136:139], v[44:47], v[164:167], v[136:139]
	v_mfma_f32_16x16x32_bf16 v[124:127], v[28:31], v[188:191], v[124:127]
	v_mfma_f32_16x16x32_bf16 v[120:123], v[44:47], v[188:191], v[120:123]
	v_mfma_f32_16x16x32_bf16 v[108:111], v[28:31], v[196:199], v[108:111]
	v_mfma_f32_16x16x32_bf16 v[104:107], v[44:47], v[196:199], v[104:107]
	v_mfma_f32_16x16x32_bf16 v[92:95], v[28:31], v[218:221], v[92:95]
	v_mfma_f32_16x16x32_bf16 v[88:91], v[44:47], v[218:221], v[88:91]
	v_mfma_f32_16x16x32_bf16 v[132:135], v[144:147], v[160:163], v[132:135]
	v_mfma_f32_16x16x32_bf16 v[128:131], v[152:155], v[160:163], v[128:131]
	v_mfma_f32_16x16x32_bf16 v[116:119], v[144:147], v[184:187], v[116:119]
	v_mfma_f32_16x16x32_bf16 v[112:115], v[152:155], v[184:187], v[112:115]
	v_mfma_f32_16x16x32_bf16 v[100:103], v[144:147], v[192:195], v[100:103]
	v_mfma_f32_16x16x32_bf16 v[96:99], v[152:155], v[192:195], v[96:99]
	v_mfma_f32_16x16x32_bf16 v[84:87], v[144:147], v[200:203], v[84:87]
	v_mfma_f32_16x16x32_bf16 v[80:83], v[152:155], v[200:203], v[80:83]
	v_mfma_f32_16x16x32_bf16 v[132:135], v[148:151], v[164:167], v[132:135]
	v_mfma_f32_16x16x32_bf16 v[128:131], v[156:159], v[164:167], v[128:131]
	v_mfma_f32_16x16x32_bf16 v[116:119], v[148:151], v[188:191], v[116:119]
	v_mfma_f32_16x16x32_bf16 v[112:115], v[156:159], v[188:191], v[112:115]
	v_mfma_f32_16x16x32_bf16 v[100:103], v[148:151], v[196:199], v[100:103]
	v_mfma_f32_16x16x32_bf16 v[96:99], v[156:159], v[196:199], v[96:99]
	v_mfma_f32_16x16x32_bf16 v[84:87], v[148:151], v[218:221], v[84:87]
	v_mfma_f32_16x16x32_bf16 v[80:83], v[156:159], v[218:221], v[80:83]
	s_barrier
	s_add_i32 s64, s57, s3
	v_lshl_add_u64 v[222:223], s[44:45], 0, v[170:171]
	s_mov_b32 m0, s64
	ds_read_b128 v[160:163], v212 offset:16384
	ds_read_b128 v[164:167], v212 offset:17408
	ds_read_b128 v[184:187], v212 offset:18432
	ds_read_b128 v[188:191], v212 offset:19456
	ds_read_b128 v[192:195], v212 offset:20480
	ds_read_b128 v[196:199], v212 offset:21504
	ds_read_b128 v[200:203], v212 offset:22528
	ds_read_b128 v[218:221], v212 offset:23552
	global_load_lds_dwordx4 v[222:223], off
	s_add_i32 m0, s64, 0x2000
	s_add_u32 s64, s44, 0xb0000
	v_lshl_add_u64 v[224:225], s[44:45], 0, v[174:175]
	s_addc_u32 s65, s45, 0
	s_add_i32 s66, s58, s3
	global_load_lds_dwordx4 v[224:225], off
	v_lshl_add_u64 v[226:227], s[64:65], 0, v[170:171]
	s_mov_b32 m0, s66
	s_nop 0
	global_load_lds_dwordx4 v[226:227], off
	v_lshl_add_u64 v[226:227], s[64:65], 0, v[174:175]
	s_add_i32 m0, s66, 0x2000
	s_nop 0
	global_load_lds_dwordx4 v[226:227], off
	v_lshl_add_u64 v[226:227], s[46:47], 0, v[168:169]
	s_mov_b32 m0, s29
	s_nop 0
	global_load_lds_dwordx4 v[226:227], off
	v_lshl_add_u64 v[226:227], s[46:47], 0, v[172:173]
	s_mov_b32 m0, s33
	s_nop 0
	global_load_lds_dwordx4 v[226:227], off
	s_waitcnt vmcnt(8)
	s_waitcnt lgkmcnt(0)
	s_barrier
; #define PG8_STAGE(bufoff, gbase, voff) do { _Pragma("unroll") for (int _i = 0; _i < 2; ++_i) \
;         __builtin_amdgcn_global_load_lds((const unsigned*)((const char*)(gbase) + (voff)[_i]), (PG8_LAS unsigned*)(lds + (bufoff) + ldsw + _i * 8192), 16, 0, 0); } while (0)
; #define PG8_LDA(dst, b, h) do { _Pragma("unroll") for (int m = 0; m < 4; ++m) _Pragma("unroll") for (int k = 0; k < 2; ++k) dst[m][k] = *(const PG8_LAS bf16x8*)(lds + PG8_SA(b, h) + aoff + m * 2048 + k * 1024); } while (0)
; #define PG8_LDB(dst, b, h) do { _Pragma("unroll") for (int n = 0; n < 2; ++n) _Pragma("unroll") for (int k = 0; k < 2; ++k) dst[n][k] = *(const PG8_LAS bf16x8*)(lds + PG8_SB(b, h) + boff + n * 2048 + k * 1024); } while (0)
; #define PG8_MMA(ai, bj, At, Bt) do { __builtin_amdgcn_s_setprio(1); _Pragma("unroll") for (int m = 0; m < 4; ++m) _Pragma("unroll") for (int n = 0; n < 2; ++n) _Pragma("unroll") for (int k = 0; k < 2; ++k) \
;         acc[ai][bj][m][n] = __builtin_amdgcn_mfma_f32_16x16x32_bf16(Bt[n][k], At[m][k], acc[ai][bj][m][n], 0, 0, 0); __builtin_amdgcn_s_setprio(0); } while (0)
; #define PG8_WAIT_V(n) asm volatile("s_waitcnt vmcnt(" #n ")" ::: "memory")
; #define PG8_WAIT_L(n) asm volatile("s_waitcnt lgkmcnt(" #n ")" ::: "memory")
; #define PG8_BAR __builtin_amdgcn_s_barrier()
; #define PG8_SCHED __builtin_amdgcn_sched_barrier(0)
; template <class Epi, class Sched, bool ALIGN_EPI = false, bool SP2 = false, bool ATILED = false>
; __device__ __forceinline__ void gemm_phase(PG8_LAS unsigned char* lds, const Gemm g, const Sched& S, const Epi& E) {
;     ...
;             PG8_WAIT_V(8); PG8_WAIT_L(0); PG8_BAR; PG8_MMA(1, 0, At, B0); PG8_MMA(1, 1, At, B1); PG8_BAR; PG8_SCHED;
;             PG8_LDB(B0, 1, 0); PG8_LDB(B1, 1, 1); PG8_SCHED; PG8_LDA(At, 1, 0); PG8_STAGE(PG8_SA(0, 1), a2 + hstepA, voffA);
;             PG8_WAIT_V(8); PG8_WAIT_L(0); PG8_BAR; PG8_MMA(0, 0, At, B0); PG8_MMA(0, 1, At, B1); PG8_BAR; PG8_SCHED;
	s_waitcnt lgkmcnt(0)
	v_mfma_f32_16x16x32_bf16 v[76:79], v[24:27], v[160:163], v[76:79]
	v_mfma_f32_16x16x32_bf16 v[72:75], v[36:39], v[160:163], v[72:75]
	v_mfma_f32_16x16x32_bf16 v[60:63], v[24:27], v[184:187], v[60:63]
	v_mfma_f32_16x16x32_bf16 v[56:59], v[36:39], v[184:187], v[56:59]
	v_mfma_f32_16x16x32_bf16 v[40:43], v[24:27], v[192:195], v[40:43]
	v_mfma_f32_16x16x32_bf16 v[32:35], v[36:39], v[192:195], v[32:35]
	v_mfma_f32_16x16x32_bf16 v[12:15], v[24:27], v[200:203], v[12:15]
	v_mfma_f32_16x16x32_bf16 v[8:11], v[36:39], v[200:203], v[8:11]
	v_mfma_f32_16x16x32_bf16 v[76:79], v[28:31], v[164:167], v[76:79]
	v_mfma_f32_16x16x32_bf16 v[72:75], v[44:47], v[164:167], v[72:75]
	v_mfma_f32_16x16x32_bf16 v[60:63], v[28:31], v[188:191], v[60:63]
	v_mfma_f32_16x16x32_bf16 v[56:59], v[44:47], v[188:191], v[56:59]
	v_mfma_f32_16x16x32_bf16 v[40:43], v[28:31], v[196:199], v[40:43]
	v_mfma_f32_16x16x32_bf16 v[32:35], v[44:47], v[196:199], v[32:35]
	v_mfma_f32_16x16x32_bf16 v[12:15], v[28:31], v[218:221], v[12:15]
	v_mfma_f32_16x16x32_bf16 v[8:11], v[44:47], v[218:221], v[8:11]
	v_mfma_f32_16x16x32_bf16 v[20:23], v[144:147], v[192:195], v[20:23]
	v_mfma_f32_16x16x32_bf16 v[16:19], v[152:155], v[192:195], v[16:19]
	v_mfma_f32_16x16x32_bf16 v[4:7], v[144:147], v[200:203], v[4:7]
	v_mfma_f32_16x16x32_bf16 v[0:3], v[152:155], v[200:203], v[0:3]
	v_mfma_f32_16x16x32_bf16 v[24:27], v[144:147], v[160:163], v[68:71]
	v_mfma_f32_16x16x32_bf16 v[28:31], v[152:155], v[160:163], v[64:67]
	v_mfma_f32_16x16x32_bf16 v[36:39], v[144:147], v[184:187], v[52:55]
	v_mfma_f32_16x16x32_bf16 v[44:47], v[152:155], v[184:187], v[48:51]
	v_mfma_f32_16x16x32_bf16 v[20:23], v[148:151], v[196:199], v[20:23]
	v_mfma_f32_16x16x32_bf16 v[16:19], v[156:159], v[196:199], v[16:19]
	v_mfma_f32_16x16x32_bf16 v[4:7], v[148:151], v[218:221], v[4:7]
	v_mfma_f32_16x16x32_bf16 v[0:3], v[156:159], v[218:221], v[0:3]
	v_mfma_f32_16x16x32_bf16 v[24:27], v[148:151], v[164:167], v[24:27]
	v_mfma_f32_16x16x32_bf16 v[28:31], v[156:159], v[164:167], v[28:31]
	v_mfma_f32_16x16x32_bf16 v[36:39], v[148:151], v[188:191], v[36:39]
	v_mfma_f32_16x16x32_bf16 v[44:47], v[156:159], v[188:191], v[44:47]
	s_barrier
	s_add_i32 s64, 0, 0x18000
	s_add_i32 s65, 0, 0x1c000
	v_add_u32_e32 v68, s64, v205
	v_add_u32_e32 v156, s65, v205
	ds_read_b128 v[48:51], v68
	ds_read_b128 v[52:55], v68 offset:1024
	ds_read_b128 v[64:67], v68 offset:2048
	ds_read_b128 v[68:71], v68 offset:3072
	ds_read_b128 v[144:147], v156
	ds_read_b128 v[148:151], v156 offset:1024
	ds_read_b128 v[152:155], v156 offset:2048
	ds_read_b128 v[156:159], v156 offset:3072
	s_add_u32 s46, s46, 0x4000
	s_addc_u32 s47, s47, 0
	s_mov_b32 m0, s48
	v_lshl_add_u64 v[226:227], s[46:47], 0, v[168:169]
	ds_read_b128 v[160:163], v212 offset:32768
	ds_read_b128 v[164:167], v212 offset:33792
	ds_read_b128 v[184:187], v212 offset:34816
	ds_read_b128 v[188:191], v212 offset:35840
	ds_read_b128 v[192:195], v212 offset:36864
	ds_read_b128 v[196:199], v212 offset:37888
	ds_read_b128 v[200:203], v212 offset:38912
	ds_read_b128 v[218:221], v212 offset:39936
	global_load_lds_dwordx4 v[226:227], off
	v_lshl_add_u64 v[226:227], s[46:47], 0, v[172:173]
	s_mov_b32 m0, s49
	s_nop 0
	global_load_lds_dwordx4 v[226:227], off
	s_waitcnt vmcnt(8)
	s_waitcnt lgkmcnt(0)
	s_barrier
	s_waitcnt lgkmcnt(0)
	v_mfma_f32_16x16x32_bf16 v[140:143], v[48:51], v[160:163], v[140:143]
	v_mfma_f32_16x16x32_bf16 v[136:139], v[64:67], v[160:163], v[136:139]
	v_mfma_f32_16x16x32_bf16 v[124:127], v[48:51], v[184:187], v[124:127]
	v_mfma_f32_16x16x32_bf16 v[120:123], v[64:67], v[184:187], v[120:123]
	v_mfma_f32_16x16x32_bf16 v[108:111], v[48:51], v[192:195], v[108:111]
	v_mfma_f32_16x16x32_bf16 v[104:107], v[64:67], v[192:195], v[104:107]
	v_mfma_f32_16x16x32_bf16 v[92:95], v[48:51], v[200:203], v[92:95]
	v_mfma_f32_16x16x32_bf16 v[88:91], v[64:67], v[200:203], v[88:91]
	v_mfma_f32_16x16x32_bf16 v[140:143], v[52:55], v[164:167], v[140:143]
	v_mfma_f32_16x16x32_bf16 v[136:139], v[68:71], v[164:167], v[136:139]
	v_mfma_f32_16x16x32_bf16 v[124:127], v[52:55], v[188:191], v[124:127]
	v_mfma_f32_16x16x32_bf16 v[120:123], v[68:71], v[188:191], v[120:123]
	v_mfma_f32_16x16x32_bf16 v[108:111], v[52:55], v[196:199], v[108:111]
	v_mfma_f32_16x16x32_bf16 v[104:107], v[68:71], v[196:199], v[104:107]
	v_mfma_f32_16x16x32_bf16 v[92:95], v[52:55], v[218:221], v[92:95]
	v_mfma_f32_16x16x32_bf16 v[88:91], v[68:71], v[218:221], v[88:91]
	v_mfma_f32_16x16x32_bf16 v[132:135], v[144:147], v[160:163], v[132:135]
	v_mfma_f32_16x16x32_bf16 v[128:131], v[152:155], v[160:163], v[128:131]
	v_mfma_f32_16x16x32_bf16 v[116:119], v[144:147], v[184:187], v[116:119]
	v_mfma_f32_16x16x32_bf16 v[112:115], v[152:155], v[184:187], v[112:115]
	v_mfma_f32_16x16x32_bf16 v[100:103], v[144:147], v[192:195], v[100:103]
	v_mfma_f32_16x16x32_bf16 v[96:99], v[152:155], v[192:195], v[96:99]
	v_mfma_f32_16x16x32_bf16 v[84:87], v[144:147], v[200:203], v[84:87]
	v_mfma_f32_16x16x32_bf16 v[80:83], v[152:155], v[200:203], v[80:83]
	v_mfma_f32_16x16x32_bf16 v[132:135], v[148:151], v[164:167], v[132:135]
	v_mfma_f32_16x16x32_bf16 v[128:131], v[156:159], v[164:167], v[128:131]
	v_mfma_f32_16x16x32_bf16 v[116:119], v[148:151], v[188:191], v[116:119]
	v_mfma_f32_16x16x32_bf16 v[112:115], v[156:159], v[188:191], v[112:115]
	v_mfma_f32_16x16x32_bf16 v[100:103], v[148:151], v[196:199], v[100:103]
	v_mfma_f32_16x16x32_bf16 v[96:99], v[156:159], v[196:199], v[96:99]
	v_mfma_f32_16x16x32_bf16 v[84:87], v[148:151], v[218:221], v[84:87]
	v_mfma_f32_16x16x32_bf16 v[80:83], v[156:159], v[218:221], v[80:83]
	s_barrier
; #define PG8_STAGE(bufoff, gbase, voff) do { _Pragma("unroll") for (int _i = 0; _i < 2; ++_i) \
;         __builtin_amdgcn_global_load_lds((const unsigned*)((const char*)(gbase) + (voff)[_i]), (PG8_LAS unsigned*)(lds + (bufoff) + ldsw + _i * 8192), 16, 0, 0); } while (0)
; #define PG8_LDA(dst, b, h) do { _Pragma("unroll") for (int m = 0; m < 4; ++m) _Pragma("unroll") for (int k = 0; k < 2; ++k) dst[m][k] = *(const PG8_LAS bf16x8*)(lds + PG8_SA(b, h) + aoff + m * 2048 + k * 1024); } while (0)
; #define PG8_MMA(ai, bj, At, Bt) do { __builtin_amdgcn_s_setprio(1); _Pragma("unroll") for (int m = 0; m < 4; ++m) _Pragma("unroll") for (int n = 0; n < 2; ++n) _Pragma("unroll") for (int k = 0; k < 2; ++k) \
;         acc[ai][bj][m][n] = __builtin_amdgcn_mfma_f32_16x16x32_bf16(Bt[n][k], At[m][k], acc[ai][bj][m][n], 0, 0, 0); __builtin_amdgcn_s_setprio(0); } while (0)
; #define PG8_WAIT_V(n) asm volatile("s_waitcnt vmcnt(" #n ")" ::: "memory")
; #define PG8_WAIT_L(n) asm volatile("s_waitcnt lgkmcnt(" #n ")" ::: "memory")
; #define PG8_BAR __builtin_amdgcn_s_barrier()
; #define PG8_SCHED __builtin_amdgcn_sched_barrier(0)
; template <class Epi, class Sched, bool ALIGN_EPI = false, bool SP2 = false, bool ATILED = false>
; __device__ __forceinline__ void gemm_phase(PG8_LAS unsigned char* lds, const Gemm g, const Sched& S, const Epi& E) {
;     ...
;         for (int t = 0; t < nt; t += 2) {
;     ...
;             PG8_LDA(At, 1, 1); PG8_STAGE(PG8_SB(1, 0), b3, voffB); PG8_STAGE(PG8_SB(1, 1), b3 + hstep, voffB); PG8_STAGE(PG8_SA(1, 0), a3, voffA);
;             PG8_WAIT_V(8); PG8_WAIT_L(0); PG8_BAR; PG8_MMA(1, 0, At, B0); PG8_MMA(1, 1, At, B1); PG8_BAR; PG8_SCHED;
	s_add_i32 s46, s64, s3
	v_lshl_add_u64 v[222:223], v[222:223], 0, s[16:17]
	s_mov_b32 m0, s46
	ds_read_b128 v[160:163], v212 offset:49152
	ds_read_b128 v[164:167], v212 offset:50176
	ds_read_b128 v[184:187], v212 offset:51200
	ds_read_b128 v[188:191], v212 offset:52224
	ds_read_b128 v[192:195], v212 offset:53248
	ds_read_b128 v[196:199], v212 offset:54272
	ds_read_b128 v[200:203], v212 offset:55296
	ds_read_b128 v[218:221], v212 offset:56320
	global_load_lds_dwordx4 v[222:223], off
	s_add_i32 m0, s46, 0x2000
	s_add_u32 s44, s44, 0xb0080
	v_lshl_add_u64 v[222:223], v[224:225], 0, s[16:17]
	s_addc_u32 s45, s45, 0
	s_add_i32 s46, s65, s3
	global_load_lds_dwordx4 v[222:223], off
	v_lshl_add_u64 v[222:223], s[44:45], 0, v[170:171]
	s_mov_b32 m0, s46
	s_nop 0
	global_load_lds_dwordx4 v[222:223], off
	v_lshl_add_u64 v[222:223], s[44:45], 0, v[174:175]
	s_add_i32 m0, s46, 0x2000
	s_nop 0
	global_load_lds_dwordx4 v[222:223], off
	v_lshl_add_u64 v[222:223], s[42:43], 0, v[168:169]
	s_mov_b32 m0, s53
	s_nop 0
	global_load_lds_dwordx4 v[222:223], off
	v_lshl_add_u64 v[222:223], s[42:43], 0, v[172:173]
	s_mov_b32 m0, s54
	s_nop 0
	global_load_lds_dwordx4 v[222:223], off
	s_waitcnt vmcnt(8)
	s_waitcnt lgkmcnt(0)
	s_barrier
	s_waitcnt lgkmcnt(0)
	v_mfma_f32_16x16x32_bf16 v[76:79], v[48:51], v[160:163], v[76:79]
	v_mfma_f32_16x16x32_bf16 v[72:75], v[64:67], v[160:163], v[72:75]
	v_mfma_f32_16x16x32_bf16 v[60:63], v[48:51], v[184:187], v[60:63]
	v_mfma_f32_16x16x32_bf16 v[56:59], v[64:67], v[184:187], v[56:59]
	v_mfma_f32_16x16x32_bf16 v[40:43], v[48:51], v[192:195], v[40:43]
	v_mfma_f32_16x16x32_bf16 v[32:35], v[64:67], v[192:195], v[32:35]
	v_mfma_f32_16x16x32_bf16 v[12:15], v[48:51], v[200:203], v[12:15]
	v_mfma_f32_16x16x32_bf16 v[8:11], v[64:67], v[200:203], v[8:11]
	v_mfma_f32_16x16x32_bf16 v[76:79], v[52:55], v[164:167], v[76:79]
	v_mfma_f32_16x16x32_bf16 v[72:75], v[68:71], v[164:167], v[72:75]
	v_mfma_f32_16x16x32_bf16 v[60:63], v[52:55], v[188:191], v[60:63]
	v_mfma_f32_16x16x32_bf16 v[56:59], v[68:71], v[188:191], v[56:59]
	v_mfma_f32_16x16x32_bf16 v[40:43], v[52:55], v[196:199], v[40:43]
	v_mfma_f32_16x16x32_bf16 v[32:35], v[68:71], v[196:199], v[32:35]
	v_mfma_f32_16x16x32_bf16 v[12:15], v[52:55], v[218:221], v[12:15]
	v_mfma_f32_16x16x32_bf16 v[8:11], v[68:71], v[218:221], v[8:11]
	v_mfma_f32_16x16x32_bf16 v[24:27], v[144:147], v[160:163], v[24:27]
	v_mfma_f32_16x16x32_bf16 v[68:71], v[148:151], v[164:167], v[24:27]
	v_mfma_f32_16x16x32_bf16 v[24:27], v[152:155], v[160:163], v[28:31]
	v_mfma_f32_16x16x32_bf16 v[64:67], v[156:159], v[164:167], v[24:27]
	v_mfma_f32_16x16x32_bf16 v[24:27], v[144:147], v[184:187], v[36:39]
	v_mfma_f32_16x16x32_bf16 v[52:55], v[148:151], v[188:191], v[24:27]
	v_mfma_f32_16x16x32_bf16 v[24:27], v[152:155], v[184:187], v[44:47]
	v_mfma_f32_16x16x32_bf16 v[20:23], v[144:147], v[192:195], v[20:23]
	v_mfma_f32_16x16x32_bf16 v[16:19], v[152:155], v[192:195], v[16:19]
	v_mfma_f32_16x16x32_bf16 v[4:7], v[144:147], v[200:203], v[4:7]
	v_mfma_f32_16x16x32_bf16 v[0:3], v[152:155], v[200:203], v[0:3]
	v_mfma_f32_16x16x32_bf16 v[48:51], v[156:159], v[188:191], v[24:27]
	v_mfma_f32_16x16x32_bf16 v[20:23], v[148:151], v[196:199], v[20:23]
	v_mfma_f32_16x16x32_bf16 v[16:19], v[156:159], v[196:199], v[16:19]
	v_mfma_f32_16x16x32_bf16 v[4:7], v[148:151], v[218:221], v[4:7]
	v_mfma_f32_16x16x32_bf16 v[0:3], v[156:159], v[218:221], v[0:3]
	s_barrier
	s_add_i32 s63, s63, 2
	s_add_u32 s35, s35, 0x100
	s_addc_u32 s62, s62, 0
	s_add_u32 s40, s40, 0x10000
	s_addc_u32 s41, s41, 0
	s_cmp_gt_u32 s63, 41
	s_cbranch_scc0 .LBB0_898
	s_and_b64 vcc, exec, s[18:19]
	s_cbranch_vccz .LBB0_901
	s_barrier
